# v64 + residual-stream y stores (M2/E4/O5 epilogues) with the nt cache hint
# speedup vs baseline: 1.0142x; 1.0142x over previous
.LBB0_681:
	s_add_i32 s9, s7, 1
	s_bitcmp1_b32 s9, 0
	s_cselect_b32 s10, 0xe000, 0
	v_add_u32_e32 v246, s10, v109
	s_bitcmp1_b32 s7, 0
	s_cselect_b32 s10, 0xe000, 0
	v_add_u32_e32 v153, s10, v114
	v_add_u32_e32 v154, s10, v113
	s_waitcnt vmcnt(0) lgkmcnt(0)
	s_barrier
	v_add_u32_e32 v181, v153, v111
	ds_read_b128 v[116:119], v181 offset:0x0
	ds_read_b128 v[120:123], v181 offset:0x1000
	v_add_u32_e32 v181, v154, v111
	ds_read_b128 v[124:127], v181 offset:0x0
	ds_read_b128 v[130:133], v181 offset:0x1000
	ds_read_b128 v[134:137], v181 offset:0x2000
	v_mfma_f32_32x32x16_bf16 v[64:79], v[144:147], v[182:185], v[64:79]
	v_mfma_f32_32x32x16_bf16 v[32:47], v[144:147], v[186:189], v[32:47]
	v_lshl_add_u64 v[244:245], v[98:99], 0, s[2:3]
	v_lshl_add_u64 v[244:245], v[244:245], 0, s[12:13]
	v_readfirstlane_b32 s10, v246
	s_mov_b32 m0, s10
	s_nop 0
	global_load_lds_dwordx4 v[244:245], off
	v_mfma_f32_32x32x16_bf16 v[0:15], v[144:147], v[190:193], v[0:15]
	v_mfma_f32_32x32x16_bf16 v[80:95], v[148:151], v[182:185], v[80:95]
	v_add_u32_e32 v243, 0x2000, v246
	v_lshl_add_u64 v[244:245], v[98:99], 0, s[2:3]
	v_lshl_add_u64 v[244:245], v[244:245], 0, s[16:17]
	v_readfirstlane_b32 s10, v243
	s_mov_b32 m0, s10
	s_nop 0
	global_load_lds_dwordx4 v[244:245], off
	v_mfma_f32_32x32x16_bf16 v[48:63], v[148:151], v[186:189], v[48:63]
	v_mfma_f32_32x32x16_bf16 v[16:31], v[148:151], v[190:193], v[16:31]
	v_add_u32_e32 v243, 0x4000, v246
	v_lshl_add_u64 v[244:245], v[98:99], 0, s[2:3]
	v_lshl_add_u64 v[244:245], v[244:245], 0, s[18:19]
	v_readfirstlane_b32 s10, v243
	s_mov_b32 m0, s10
	s_nop 0
	global_load_lds_dwordx4 v[244:245], off
	v_add_u32_e32 v181, v153, v110
	ds_read_b128 v[144:147], v181 offset:0x0
	ds_read_b128 v[148:151], v181 offset:0x1000
	v_add_u32_e32 v181, v154, v110
	ds_read_b128 v[182:185], v181 offset:0x0
	ds_read_b128 v[186:189], v181 offset:0x1000
	ds_read_b128 v[190:193], v181 offset:0x2000
	s_waitcnt lgkmcnt(5)
	v_mfma_f32_32x32x16_bf16 v[64:79], v[116:119], v[124:127], v[64:79]
	v_mfma_f32_32x32x16_bf16 v[32:47], v[116:119], v[130:133], v[32:47]
	v_add_u32_e32 v243, 0x6000, v246
	s_mov_b64 s[10:11], 0x6a94080
	v_lshl_add_u64 v[244:245], v[96:97], 0, s[2:3]
	v_lshl_add_u64 v[244:245], v[244:245], 0, s[10:11]
	v_readfirstlane_b32 s10, v243
	s_mov_b32 m0, s10
	s_nop 0
	global_load_lds_dwordx4 v[244:245], off
	v_mfma_f32_32x32x16_bf16 v[0:15], v[116:119], v[134:137], v[0:15]
	v_mfma_f32_32x32x16_bf16 v[80:95], v[120:123], v[124:127], v[80:95]
	v_add_u32_e32 v243, 0x8000, v246
	s_mov_b64 s[10:11], 0x6ab4080
	v_lshl_add_u64 v[244:245], v[96:97], 0, s[2:3]
	v_lshl_add_u64 v[244:245], v[244:245], 0, s[10:11]
	v_readfirstlane_b32 s10, v243
	s_mov_b32 m0, s10
	s_nop 0
	global_load_lds_dwordx4 v[244:245], off
	v_mfma_f32_32x32x16_bf16 v[48:63], v[120:123], v[130:133], v[48:63]
	v_mfma_f32_32x32x16_bf16 v[16:31], v[120:123], v[134:137], v[16:31]
	v_add_u32_e32 v243, 0xa000, v246
	s_mov_b64 s[10:11], 0x6ad4080
	v_lshl_add_u64 v[244:245], v[96:97], 0, s[2:3]
	v_lshl_add_u64 v[244:245], v[244:245], 0, s[10:11]
	v_readfirstlane_b32 s10, v243
	s_mov_b32 m0, s10
	s_nop 0
	global_load_lds_dwordx4 v[244:245], off
	v_add_u32_e32 v181, v153, v108
	ds_read_b128 v[116:119], v181 offset:0x0
	ds_read_b128 v[120:123], v181 offset:0x1000
	v_add_u32_e32 v181, v154, v108
	ds_read_b128 v[124:127], v181 offset:0x0
	ds_read_b128 v[130:133], v181 offset:0x1000
	ds_read_b128 v[134:137], v181 offset:0x2000
	s_waitcnt lgkmcnt(5)
	v_mfma_f32_32x32x16_bf16 v[64:79], v[144:147], v[182:185], v[64:79]
	v_mfma_f32_32x32x16_bf16 v[32:47], v[144:147], v[186:189], v[32:47]
	v_add_u32_e32 v243, 0xc000, v246
	s_mov_b64 s[10:11], 0x6af4080
	v_lshl_add_u64 v[244:245], v[96:97], 0, s[2:3]
	v_lshl_add_u64 v[244:245], v[244:245], 0, s[10:11]
	v_readfirstlane_b32 s10, v243
	s_mov_b32 m0, s10
	s_nop 0
	global_load_lds_dwordx4 v[244:245], off
	v_mfma_f32_32x32x16_bf16 v[0:15], v[144:147], v[190:193], v[0:15]
	v_mfma_f32_32x32x16_bf16 v[80:95], v[148:151], v[182:185], v[80:95]
	v_mfma_f32_32x32x16_bf16 v[48:63], v[148:151], v[186:189], v[48:63]
	v_mfma_f32_32x32x16_bf16 v[16:31], v[148:151], v[190:193], v[16:31]
	v_add_u32_e32 v181, v153, v107
	ds_read_b128 v[144:147], v181 offset:0x0
	ds_read_b128 v[148:151], v181 offset:0x1000
	v_add_u32_e32 v181, v154, v107
	ds_read_b128 v[182:185], v181 offset:0x0
	ds_read_b128 v[186:189], v181 offset:0x1000
	ds_read_b128 v[190:193], v181 offset:0x2000
	s_waitcnt lgkmcnt(5)
	v_mfma_f32_32x32x16_bf16 v[64:79], v[116:119], v[124:127], v[64:79]
	v_mfma_f32_32x32x16_bf16 v[32:47], v[116:119], v[130:133], v[32:47]
	v_mfma_f32_32x32x16_bf16 v[0:15], v[116:119], v[134:137], v[0:15]
	v_mfma_f32_32x32x16_bf16 v[80:95], v[120:123], v[124:127], v[80:95]
	v_mfma_f32_32x32x16_bf16 v[48:63], v[120:123], v[130:133], v[48:63]
	v_mfma_f32_32x32x16_bf16 v[16:31], v[120:123], v[134:137], v[16:31]
	s_waitcnt lgkmcnt(0)
	s_add_u32 s2, s2, 0x80
	s_addc_u32 s3, s3, 0
	s_mov_b32 s7, s9
	s_cmpk_lg_i32 s2, 0x780
	s_cbranch_scc1 .LBB0_681
	s_bitcmp1_b32 s7, 0
	s_cselect_b32 s10, 0xe000, 0
	v_add_u32_e32 v153, s10, v114
	v_add_u32_e32 v154, s10, v113
	s_waitcnt vmcnt(0) lgkmcnt(0)
	s_barrier
	v_add_u32_e32 v181, v153, v111
	ds_read_b128 v[116:119], v181 offset:0x0
	ds_read_b128 v[120:123], v181 offset:0x1000
	v_add_u32_e32 v181, v154, v111
	ds_read_b128 v[124:127], v181 offset:0x0
	ds_read_b128 v[130:133], v181 offset:0x1000
	ds_read_b128 v[134:137], v181 offset:0x2000
	v_mfma_f32_32x32x16_bf16 v[64:79], v[144:147], v[182:185], v[64:79]
	v_mfma_f32_32x32x16_bf16 v[32:47], v[144:147], v[186:189], v[32:47]
	v_mfma_f32_32x32x16_bf16 v[0:15], v[144:147], v[190:193], v[0:15]
	v_mfma_f32_32x32x16_bf16 v[80:95], v[148:151], v[182:185], v[80:95]
	v_mfma_f32_32x32x16_bf16 v[48:63], v[148:151], v[186:189], v[48:63]
	v_mfma_f32_32x32x16_bf16 v[16:31], v[148:151], v[190:193], v[16:31]
	v_add_u32_e32 v181, v153, v110
	ds_read_b128 v[144:147], v181 offset:0x0
	ds_read_b128 v[148:151], v181 offset:0x1000
	v_add_u32_e32 v181, v154, v110
	ds_read_b128 v[182:185], v181 offset:0x0
	ds_read_b128 v[186:189], v181 offset:0x1000
	ds_read_b128 v[190:193], v181 offset:0x2000
	s_waitcnt lgkmcnt(5)
	v_mfma_f32_32x32x16_bf16 v[64:79], v[116:119], v[124:127], v[64:79]
	v_mfma_f32_32x32x16_bf16 v[32:47], v[116:119], v[130:133], v[32:47]
	v_mfma_f32_32x32x16_bf16 v[0:15], v[116:119], v[134:137], v[0:15]
	v_mfma_f32_32x32x16_bf16 v[80:95], v[120:123], v[124:127], v[80:95]
	v_mfma_f32_32x32x16_bf16 v[48:63], v[120:123], v[130:133], v[48:63]
	v_mfma_f32_32x32x16_bf16 v[16:31], v[120:123], v[134:137], v[16:31]
	v_add_u32_e32 v181, v153, v108
	ds_read_b128 v[116:119], v181 offset:0x0
	ds_read_b128 v[120:123], v181 offset:0x1000
	v_add_u32_e32 v181, v154, v108
	ds_read_b128 v[124:127], v181 offset:0x0
	ds_read_b128 v[130:133], v181 offset:0x1000
	ds_read_b128 v[134:137], v181 offset:0x2000
	s_waitcnt lgkmcnt(5)
	v_mfma_f32_32x32x16_bf16 v[64:79], v[144:147], v[182:185], v[64:79]
	v_mfma_f32_32x32x16_bf16 v[32:47], v[144:147], v[186:189], v[32:47]
	v_mfma_f32_32x32x16_bf16 v[0:15], v[144:147], v[190:193], v[0:15]
	v_mfma_f32_32x32x16_bf16 v[80:95], v[148:151], v[182:185], v[80:95]
	v_mfma_f32_32x32x16_bf16 v[48:63], v[148:151], v[186:189], v[48:63]
	v_mfma_f32_32x32x16_bf16 v[16:31], v[148:151], v[190:193], v[16:31]
	v_add_u32_e32 v181, v153, v107
	ds_read_b128 v[144:147], v181 offset:0x0
	ds_read_b128 v[148:151], v181 offset:0x1000
	v_add_u32_e32 v181, v154, v107
	ds_read_b128 v[182:185], v181 offset:0x0
	ds_read_b128 v[186:189], v181 offset:0x1000
	ds_read_b128 v[190:193], v181 offset:0x2000
	s_waitcnt lgkmcnt(5)
	v_mfma_f32_32x32x16_bf16 v[64:79], v[116:119], v[124:127], v[64:79]
	v_mfma_f32_32x32x16_bf16 v[32:47], v[116:119], v[130:133], v[32:47]
	v_mfma_f32_32x32x16_bf16 v[0:15], v[116:119], v[134:137], v[0:15]
	v_mfma_f32_32x32x16_bf16 v[80:95], v[120:123], v[124:127], v[80:95]
	v_mfma_f32_32x32x16_bf16 v[48:63], v[120:123], v[130:133], v[48:63]
	v_mfma_f32_32x32x16_bf16 v[16:31], v[120:123], v[134:137], v[16:31]
	s_waitcnt lgkmcnt(0)
	v_mfma_f32_32x32x16_bf16 v[64:79], v[144:147], v[182:185], v[64:79]
	v_mfma_f32_32x32x16_bf16 v[32:47], v[144:147], v[186:189], v[32:47]
	v_mfma_f32_32x32x16_bf16 v[0:15], v[144:147], v[190:193], v[0:15]
	v_mfma_f32_32x32x16_bf16 v[80:95], v[148:151], v[182:185], v[80:95]
	v_mfma_f32_32x32x16_bf16 v[48:63], v[148:151], v[186:189], v[48:63]
	v_mfma_f32_32x32x16_bf16 v[16:31], v[148:151], v[190:193], v[16:31]
	v_add_u32_e32 v96, s4, v106
	v_lshrrev_b32_e32 v128, 4, v101
	v_and_b32_e32 v112, 15, v100
	v_or_b32_e32 v100, v96, v128
	v_add_u32_e32 v105, s8, v105
	v_ashrrev_i32_e32 v101, 31, v100
	v_lshl_or_b32 v98, v112, 2, v105
	v_lshlrev_b64 v[106:107], 12, v[100:101]
	v_ashrrev_i32_e32 v99, 31, v98
	v_lshl_add_u64 v[106:107], s[40:41], 0, v[106:107]
	v_lshl_add_u64 v[110:111], v[98:99], 2, v[106:107]
	s_barrier
	v_add_co_u32_e32 v182, vcc, 0x20000, v110
	s_nop 1
	v_addc_co_u32_e32 v183, vcc, 0, v111, vcc
	global_load_dwordx4 v[184:187], v[182:183], off
	v_add_co_u32_e32 v182, vcc, 0x4000, v182
	s_nop 1
	v_addc_co_u32_e32 v183, vcc, 0, v183, vcc
	global_load_dwordx4 v[188:191], v[182:183], off
	v_add_co_u32_e32 v182, vcc, 0x4000, v182
	s_nop 1
	v_addc_co_u32_e32 v183, vcc, 0, v183, vcc
	global_load_dwordx4 v[192:195], v[182:183], off
	v_add_co_u32_e32 v182, vcc, 0x4000, v182
	s_nop 1
	v_addc_co_u32_e32 v183, vcc, 0, v183, vcc
	global_load_dwordx4 v[116:119], v[182:183], off
	v_add_co_u32_e32 v182, vcc, 0x4000, v182
	s_nop 1
	v_addc_co_u32_e32 v183, vcc, 0, v183, vcc
	global_load_dwordx4 v[120:123], v[182:183], off
	v_add_co_u32_e32 v182, vcc, 0x4000, v182
	s_nop 1
	v_addc_co_u32_e32 v183, vcc, 0, v183, vcc
	global_load_dwordx4 v[124:127], v[182:183], off
	v_add_co_u32_e32 v182, vcc, 0x4000, v182
	s_nop 1
	v_addc_co_u32_e32 v183, vcc, 0, v183, vcc
	global_load_dwordx4 v[130:133], v[182:183], off
	v_add_co_u32_e32 v182, vcc, 0x4000, v182
	s_nop 1
	v_addc_co_u32_e32 v183, vcc, 0, v183, vcc
	global_load_dwordx4 v[134:137], v[182:183], off
	s_movk_i32 s2, 0x2400
	s_cmp_lt_i32 s5, 22
	v_mul_lo_u32 v97, v103, s2
	s_cselect_b64 s[2:3], -1, 0
	s_cmp_gt_i32 s5, 21
	s_movk_i32 s5, 0x110
	v_and_b32_e32 v103, 16, v104
	v_mad_u32_u24 v104, v102, s5, v97
	v_add_u32_e32 v113, 0xfffff000, v96
	v_cndmask_b32_e64 v102, 0, 1, s[2:3]
	s_cselect_b64 s[2:3], -1, 0
	s_add_i32 s7, s4, 0xfffff000
	v_add_u32_e32 v104, v104, v103
	ds_write_b128 v104, v[64:67]
	ds_write_b128 v104, v[68:71] offset:32
	ds_write_b128 v104, v[72:75] offset:64
	ds_write_b128 v104, v[76:79] offset:96
	ds_write_b128 v104, v[80:83] offset:128
	ds_write_b128 v104, v[84:87] offset:160
	ds_write_b128 v104, v[88:91] offset:192
	ds_write_b128 v104, v[92:95] offset:224
	v_xor_b32_e32 v64, s7, v113
	s_movk_i32 s4, 0x400
	v_lshl_or_b32 v97, v112, 4, v97
	v_cmp_gt_u32_e32 vcc, s4, v64
	v_mad_u32_u24 v115, v128, s5, v97
	s_and_b64 s[4:5], s[2:3], vcc
	v_cndmask_b32_e64 v71, 0, 1, s[4:5]
	s_movk_i32 s4, 0x1000
	v_cmp_gt_i32_e32 vcc, s4, v100
	v_subrev_u32_e32 v114, s8, v98
	v_lshl_add_u32 v103, v114, 2, v167
	v_cndmask_b32_e32 v64, v71, v102, vcc
	v_and_b32_e32 v64, 1, v64
	v_cmp_eq_u32_e32 vcc, 1, v64
	v_ashrrev_i32_e32 v68, 6, v105
	s_mov_b32 s4, 0xc000
	v_cndmask_b32_e64 v64, v171, 0, vcc
	v_add_u32_e32 v70, v103, v64
	ds_read_b128 v[64:67], v115
	ds_read_b128 v[72:75], v70
	v_cmp_eq_u32_e64 s[36:37], 0, v112
	v_mad_i64_i32 v[68:69], s[4:5], v68, s4, 0
	s_and_b64 vcc, exec, s[0:1]
	s_waitcnt lgkmcnt(0)
	v_pk_fma_f32 v[66:67], v[66:67], v[74:75], v[200:201]
	v_pk_fma_f32 v[64:65], v[64:65], v[72:73], v[198:199]
	global_store_dwordx4 v[110:111], v[64:67], off nt
	s_cbranch_vccnz .LBB0_686
	ds_read_b128 v[72:75], v70 offset:2048
	v_lshlrev_b64 v[76:77], 10, v[100:101]
	v_lshl_add_u64 v[76:77], v[76:77], 1, s[42:43]
	v_lshl_add_u64 v[76:77], v[98:99], 1, v[76:77]
	s_waitcnt lgkmcnt(0)
	v_pk_mul_f32 v[72:73], v[64:65], v[72:73]
	v_pk_mul_f32 v[64:65], v[64:65], v[64:65]
	v_pk_mul_f32 v[74:75], v[66:67], v[74:75]
	v_pk_mul_f32 v[66:67], v[66:67], v[66:67]
	v_add_f32_e32 v64, v64, v65
	v_add_f32_e32 v64, v66, v64
	v_add_f32_e32 v64, v67, v64
	v_cvt_pk_bf16_f32 v72, v72, v73
	v_cvt_pk_bf16_f32 v73, v74, v75
	v_add_f32_dpp v64, v64, v64 quad_perm:[1,0,3,2] row_mask:0xf bank_mask:0xf bound_ctrl:1
	global_store_dwordx2 v[76:77], v[72:73], off
	s_nop 0
	v_add_f32_dpp v64, v64, v64 quad_perm:[2,3,0,1] row_mask:0xf bank_mask:0xf bound_ctrl:1
	s_nop 1
	v_add_f32_dpp v64, v64, v64 row_half_mirror row_mask:0xf bank_mask:0xf bound_ctrl:1
	s_nop 1
	v_mov_b32_dpp v65, v64 row_mirror row_mask:0xf bank_mask:0xf bound_ctrl:1
	s_and_saveexec_b64 s[4:5], s[36:37]
	s_cbranch_execz .LBB0_685
	v_lshl_add_u64 v[66:67], s[52:53], 0, v[68:69]
	v_lshl_add_u64 v[66:67], v[100:101], 2, v[66:67]
	v_add_f32_e32 v64, v64, v65
	global_store_dword v[66:67], v64, off

.LBB0_686:
	v_or_b32_e32 v70, 4, v128
	v_or_b32_e32 v72, v96, v70
	v_ashrrev_i32_e32 v73, 31, v72
	v_lshlrev_b64 v[64:65], 12, v[72:73]
	v_lshl_add_u64 v[64:65], s[40:41], 0, v[64:65]
	v_lshl_add_u64 v[84:85], v[98:99], 2, v[64:65]
	s_movk_i32 s4, 0x1000
	v_mul_u32_u24_e32 v74, 0x110, v128
	v_cmp_gt_i32_e32 vcc, s4, v72
	v_add_u32_e32 v86, v74, v97
	s_nop 0
	v_cndmask_b32_e32 v74, v71, v102, vcc
	v_and_b32_e32 v74, 1, v74
	v_cmp_eq_u32_e32 vcc, 1, v74
	s_nop 1
	v_cndmask_b32_e64 v74, v171, 0, vcc
	v_add_u32_e32 v74, v103, v74
	ds_read_b128 v[76:79], v86 offset:1088
	ds_read_b128 v[80:83], v74
	s_and_b64 vcc, exec, s[0:1]
	s_waitcnt lgkmcnt(0)
	v_pk_fma_f32 v[66:67], v[78:79], v[82:83], v[204:205]
	v_pk_fma_f32 v[64:65], v[76:77], v[80:81], v[202:203]
	global_store_dwordx4 v[84:85], v[64:67], off nt
	s_cbranch_vccnz .LBB0_690
	ds_read_b128 v[74:77], v74 offset:2048
	v_lshlrev_b64 v[72:73], 10, v[72:73]
	v_lshl_add_u64 v[72:73], v[72:73], 1, s[42:43]
	v_lshl_add_u64 v[72:73], v[98:99], 1, v[72:73]
	s_waitcnt lgkmcnt(0)
	v_pk_mul_f32 v[74:75], v[64:65], v[74:75]
	v_pk_mul_f32 v[64:65], v[64:65], v[64:65]
	v_pk_mul_f32 v[76:77], v[66:67], v[76:77]
	v_pk_mul_f32 v[66:67], v[66:67], v[66:67]
	v_add_f32_e32 v64, v64, v65
	v_add_f32_e32 v64, v66, v64
	v_add_f32_e32 v64, v67, v64
	v_cvt_pk_bf16_f32 v74, v74, v75
	v_cvt_pk_bf16_f32 v75, v76, v77
	v_add_f32_dpp v64, v64, v64 quad_perm:[1,0,3,2] row_mask:0xf bank_mask:0xf bound_ctrl:1
	global_store_dwordx2 v[72:73], v[74:75], off
	s_nop 0
	v_add_f32_dpp v64, v64, v64 quad_perm:[2,3,0,1] row_mask:0xf bank_mask:0xf bound_ctrl:1
	s_nop 1
	v_add_f32_dpp v64, v64, v64 row_half_mirror row_mask:0xf bank_mask:0xf bound_ctrl:1
	s_nop 1
	v_mov_b32_dpp v65, v64 row_mirror row_mask:0xf bank_mask:0xf bound_ctrl:1
	s_and_saveexec_b64 s[4:5], s[36:37]
	s_cbranch_execz .LBB0_689
	v_ashrrev_i32_e32 v97, 31, v96
	v_lshl_add_u64 v[66:67], s[52:53], 0, v[68:69]
	v_lshl_add_u64 v[72:73], v[96:97], 0, v[128:129]
	v_lshl_add_u64 v[66:67], v[72:73], 2, v[66:67]
	v_add_f32_e32 v64, v64, v65
	global_store_dword v[66:67], v64, off offset:16

.LBB0_690:
	v_or_b32_e32 v72, 8, v128
	v_or_b32_e32 v74, v96, v72
	v_ashrrev_i32_e32 v75, 31, v74
	v_lshlrev_b64 v[64:65], 12, v[74:75]
	v_lshl_add_u64 v[64:65], s[40:41], 0, v[64:65]
	v_lshl_add_u64 v[84:85], v[98:99], 2, v[64:65]
	s_movk_i32 s4, 0x1000
	v_cmp_gt_i32_e32 vcc, s4, v74
	s_nop 1
	v_cndmask_b32_e32 v73, v71, v102, vcc
	v_and_b32_e32 v73, 1, v73
	v_cmp_eq_u32_e32 vcc, 1, v73
	s_nop 1
	v_cndmask_b32_e64 v73, v171, 0, vcc
	v_add_u32_e32 v73, v103, v73
	ds_read_b128 v[76:79], v86 offset:2176
	ds_read_b128 v[80:83], v73
	s_and_b64 vcc, exec, s[0:1]
	s_waitcnt lgkmcnt(0)
	v_pk_fma_f32 v[66:67], v[78:79], v[82:83], v[208:209]
	v_pk_fma_f32 v[64:65], v[76:77], v[80:81], v[206:207]
	global_store_dwordx4 v[84:85], v[64:67], off nt
	s_cbranch_vccnz .LBB0_694
	ds_read_b128 v[76:79], v73 offset:2048
	v_lshlrev_b64 v[74:75], 10, v[74:75]
	v_lshl_add_u64 v[74:75], v[74:75], 1, s[42:43]
	v_lshl_add_u64 v[74:75], v[98:99], 1, v[74:75]
	s_waitcnt lgkmcnt(0)
	v_pk_mul_f32 v[76:77], v[64:65], v[76:77]
	v_pk_mul_f32 v[64:65], v[64:65], v[64:65]
	v_pk_mul_f32 v[78:79], v[66:67], v[78:79]
	v_pk_mul_f32 v[66:67], v[66:67], v[66:67]
	v_add_f32_e32 v64, v64, v65
	v_add_f32_e32 v64, v66, v64
	v_add_f32_e32 v64, v67, v64
	v_cvt_pk_bf16_f32 v76, v76, v77
	v_cvt_pk_bf16_f32 v77, v78, v79
	v_add_f32_dpp v64, v64, v64 quad_perm:[1,0,3,2] row_mask:0xf bank_mask:0xf bound_ctrl:1
	global_store_dwordx2 v[74:75], v[76:77], off
	s_nop 0
	v_add_f32_dpp v64, v64, v64 quad_perm:[2,3,0,1] row_mask:0xf bank_mask:0xf bound_ctrl:1
	s_nop 1
	v_add_f32_dpp v64, v64, v64 row_half_mirror row_mask:0xf bank_mask:0xf bound_ctrl:1
	s_nop 1
	v_mov_b32_dpp v65, v64 row_mirror row_mask:0xf bank_mask:0xf bound_ctrl:1
	s_and_saveexec_b64 s[4:5], s[36:37]
	s_cbranch_execz .LBB0_693
	v_ashrrev_i32_e32 v97, 31, v96
	v_lshl_add_u64 v[66:67], s[52:53], 0, v[68:69]
	v_lshl_add_u64 v[74:75], v[96:97], 0, v[128:129]
	v_lshl_add_u64 v[66:67], v[74:75], 2, v[66:67]
	v_add_f32_e32 v64, v64, v65
	global_store_dword v[66:67], v64, off offset:32

.LBB0_694:
	v_or_b32_e32 v74, 12, v128
	v_or_b32_e32 v76, v96, v74
	v_ashrrev_i32_e32 v77, 31, v76
	v_lshlrev_b64 v[64:65], 12, v[76:77]
	v_lshl_add_u64 v[64:65], s[40:41], 0, v[64:65]
	v_lshl_add_u64 v[88:89], v[98:99], 2, v[64:65]
	s_movk_i32 s4, 0x1000
	v_cmp_gt_i32_e32 vcc, s4, v76
	s_nop 1
	v_cndmask_b32_e32 v73, v71, v102, vcc
	v_and_b32_e32 v73, 1, v73
	v_cmp_eq_u32_e32 vcc, 1, v73
	s_nop 1
	v_cndmask_b32_e64 v73, v171, 0, vcc
	v_add_u32_e32 v73, v103, v73
	ds_read_b128 v[78:81], v86 offset:3264
	ds_read_b128 v[82:85], v73
	s_and_b64 vcc, exec, s[0:1]
	s_waitcnt lgkmcnt(0)
	v_pk_fma_f32 v[66:67], v[80:81], v[84:85], v[212:213]
	v_pk_fma_f32 v[64:65], v[78:79], v[82:83], v[210:211]
	global_store_dwordx4 v[88:89], v[64:67], off nt
	s_cbranch_vccnz .LBB0_698
	ds_read_b128 v[78:81], v73 offset:2048
	v_lshlrev_b64 v[76:77], 10, v[76:77]
	v_lshl_add_u64 v[76:77], v[76:77], 1, s[42:43]
	v_lshl_add_u64 v[76:77], v[98:99], 1, v[76:77]
	s_waitcnt lgkmcnt(0)
	v_pk_mul_f32 v[78:79], v[64:65], v[78:79]
	v_pk_mul_f32 v[64:65], v[64:65], v[64:65]
	v_pk_mul_f32 v[80:81], v[66:67], v[80:81]
	v_pk_mul_f32 v[66:67], v[66:67], v[66:67]
	v_add_f32_e32 v64, v64, v65
	v_add_f32_e32 v64, v66, v64
	v_add_f32_e32 v64, v67, v64
	v_cvt_pk_bf16_f32 v78, v78, v79
	v_cvt_pk_bf16_f32 v79, v80, v81
	v_add_f32_dpp v64, v64, v64 quad_perm:[1,0,3,2] row_mask:0xf bank_mask:0xf bound_ctrl:1
	global_store_dwordx2 v[76:77], v[78:79], off
	s_nop 0
	v_add_f32_dpp v64, v64, v64 quad_perm:[2,3,0,1] row_mask:0xf bank_mask:0xf bound_ctrl:1
	s_nop 1
	v_add_f32_dpp v64, v64, v64 row_half_mirror row_mask:0xf bank_mask:0xf bound_ctrl:1
	s_nop 1
	v_mov_b32_dpp v65, v64 row_mirror row_mask:0xf bank_mask:0xf bound_ctrl:1
	s_and_saveexec_b64 s[4:5], s[36:37]
	s_cbranch_execz .LBB0_697
	v_ashrrev_i32_e32 v97, 31, v96
	v_lshl_add_u64 v[66:67], s[52:53], 0, v[68:69]
	v_lshl_add_u64 v[76:77], v[96:97], 0, v[128:129]
	v_lshl_add_u64 v[66:67], v[76:77], 2, v[66:67]
	v_add_f32_e32 v64, v64, v65
	global_store_dword v[66:67], v64, off offset:48

.LBB0_698:
	v_or_b32_e32 v76, 16, v128
	v_or_b32_e32 v78, v96, v76
	v_ashrrev_i32_e32 v79, 31, v78
	v_lshlrev_b64 v[64:65], 12, v[78:79]
	v_lshl_add_u64 v[64:65], s[40:41], 0, v[64:65]
	v_lshl_add_u64 v[84:85], v[98:99], 2, v[64:65]
	s_movk_i32 s4, 0x1000
	v_cmp_gt_i32_e32 vcc, s4, v78
	s_nop 1
	v_cndmask_b32_e32 v73, v71, v102, vcc
	v_and_b32_e32 v73, 1, v73
	v_cmp_eq_u32_e32 vcc, 1, v73
	s_nop 1
	v_cndmask_b32_e64 v73, v171, 0, vcc
	v_add_u32_e32 v73, v103, v73
	ds_read_b128 v[80:83], v86 offset:4352
	ds_read_b128 v[88:91], v73
	s_and_b64 vcc, exec, s[0:1]
	s_waitcnt lgkmcnt(0)
	v_pk_fma_f32 v[66:67], v[82:83], v[90:91], v[216:217]
	v_pk_fma_f32 v[64:65], v[80:81], v[88:89], v[214:215]
	global_store_dwordx4 v[84:85], v[64:67], off nt
	s_cbranch_vccnz .LBB0_702
	ds_read_b128 v[80:83], v73 offset:2048
	v_lshlrev_b64 v[78:79], 10, v[78:79]
	v_lshl_add_u64 v[78:79], v[78:79], 1, s[42:43]
	v_lshl_add_u64 v[78:79], v[98:99], 1, v[78:79]
	s_waitcnt lgkmcnt(0)
	v_pk_mul_f32 v[80:81], v[64:65], v[80:81]
	v_pk_mul_f32 v[64:65], v[64:65], v[64:65]
	v_pk_mul_f32 v[82:83], v[66:67], v[82:83]
	v_pk_mul_f32 v[66:67], v[66:67], v[66:67]
	v_add_f32_e32 v64, v64, v65
	v_add_f32_e32 v64, v66, v64
	v_add_f32_e32 v64, v67, v64
	v_cvt_pk_bf16_f32 v80, v80, v81
	v_cvt_pk_bf16_f32 v81, v82, v83
	v_add_f32_dpp v64, v64, v64 quad_perm:[1,0,3,2] row_mask:0xf bank_mask:0xf bound_ctrl:1
	global_store_dwordx2 v[78:79], v[80:81], off
	s_nop 0
	v_add_f32_dpp v64, v64, v64 quad_perm:[2,3,0,1] row_mask:0xf bank_mask:0xf bound_ctrl:1
	s_nop 1
	v_add_f32_dpp v64, v64, v64 row_half_mirror row_mask:0xf bank_mask:0xf bound_ctrl:1
	s_nop 1
	v_mov_b32_dpp v65, v64 row_mirror row_mask:0xf bank_mask:0xf bound_ctrl:1
	s_and_saveexec_b64 s[4:5], s[36:37]
	s_cbranch_execz .LBB0_701
	v_ashrrev_i32_e32 v97, 31, v96
	v_lshl_add_u64 v[66:67], s[52:53], 0, v[68:69]
	v_lshl_add_u64 v[78:79], v[96:97], 0, v[128:129]
	v_lshl_add_u64 v[66:67], v[78:79], 2, v[66:67]
	v_add_f32_e32 v64, v64, v65
	global_store_dword v[66:67], v64, off offset:64

.LBB0_702:
	v_or_b32_e32 v78, 20, v128
	v_or_b32_e32 v80, v96, v78
	v_ashrrev_i32_e32 v81, 31, v80
	v_lshlrev_b64 v[64:65], 12, v[80:81]
	v_lshl_add_u64 v[64:65], s[40:41], 0, v[64:65]
	v_lshl_add_u64 v[92:93], v[98:99], 2, v[64:65]
	s_movk_i32 s4, 0x1000
	v_cmp_gt_i32_e32 vcc, s4, v80
	s_nop 1
	v_cndmask_b32_e32 v73, v71, v102, vcc
	v_and_b32_e32 v73, 1, v73
	v_cmp_eq_u32_e32 vcc, 1, v73
	s_nop 1
	v_cndmask_b32_e64 v73, v171, 0, vcc
	v_add_u32_e32 v73, v103, v73
	ds_read_b128 v[82:85], v86 offset:5440
	ds_read_b128 v[88:91], v73
	s_and_b64 vcc, exec, s[0:1]
	s_waitcnt lgkmcnt(0)
	v_pk_fma_f32 v[66:67], v[84:85], v[90:91], v[220:221]
	v_pk_fma_f32 v[64:65], v[82:83], v[88:89], v[218:219]
	global_store_dwordx4 v[92:93], v[64:67], off nt
	s_cbranch_vccnz .LBB0_706
	ds_read_b128 v[82:85], v73 offset:2048
	v_lshlrev_b64 v[80:81], 10, v[80:81]
	v_lshl_add_u64 v[80:81], v[80:81], 1, s[42:43]
	v_lshl_add_u64 v[80:81], v[98:99], 1, v[80:81]
	s_waitcnt lgkmcnt(0)
	v_pk_mul_f32 v[82:83], v[64:65], v[82:83]
	v_pk_mul_f32 v[64:65], v[64:65], v[64:65]
	v_pk_mul_f32 v[84:85], v[66:67], v[84:85]
	v_pk_mul_f32 v[66:67], v[66:67], v[66:67]
	v_add_f32_e32 v64, v64, v65
	v_add_f32_e32 v64, v66, v64
	v_add_f32_e32 v64, v67, v64
	v_cvt_pk_bf16_f32 v82, v82, v83
	v_cvt_pk_bf16_f32 v83, v84, v85
	v_add_f32_dpp v64, v64, v64 quad_perm:[1,0,3,2] row_mask:0xf bank_mask:0xf bound_ctrl:1
	global_store_dwordx2 v[80:81], v[82:83], off
	s_nop 0
	v_add_f32_dpp v64, v64, v64 quad_perm:[2,3,0,1] row_mask:0xf bank_mask:0xf bound_ctrl:1
	s_nop 1
	v_add_f32_dpp v64, v64, v64 row_half_mirror row_mask:0xf bank_mask:0xf bound_ctrl:1
	s_nop 1
	v_mov_b32_dpp v65, v64 row_mirror row_mask:0xf bank_mask:0xf bound_ctrl:1
	s_and_saveexec_b64 s[4:5], s[36:37]
	s_cbranch_execz .LBB0_705
	v_ashrrev_i32_e32 v97, 31, v96
	v_lshl_add_u64 v[66:67], s[52:53], 0, v[68:69]
	v_lshl_add_u64 v[80:81], v[96:97], 0, v[128:129]
	v_lshl_add_u64 v[66:67], v[80:81], 2, v[66:67]
	v_add_f32_e32 v64, v64, v65
	global_store_dword v[66:67], v64, off offset:80

.LBB0_706:
	v_or_b32_e32 v80, 24, v128
	v_or_b32_e32 v82, v96, v80
	v_ashrrev_i32_e32 v83, 31, v82
	v_lshlrev_b64 v[64:65], 12, v[82:83]
	v_lshl_add_u64 v[64:65], s[40:41], 0, v[64:65]
	v_lshl_add_u64 v[84:85], v[98:99], 2, v[64:65]
	s_movk_i32 s4, 0x1000
	v_cmp_gt_i32_e32 vcc, s4, v82
	s_nop 1
	v_cndmask_b32_e32 v73, v71, v102, vcc
	v_and_b32_e32 v73, 1, v73
	v_cmp_eq_u32_e32 vcc, 1, v73
	s_nop 1
	v_cndmask_b32_e64 v73, v171, 0, vcc
	v_add_u32_e32 v73, v103, v73
	ds_read_b128 v[88:91], v86 offset:6528
	ds_read_b128 v[92:95], v73
	s_and_b64 vcc, exec, s[0:1]
	s_waitcnt lgkmcnt(0)
	v_pk_fma_f32 v[66:67], v[90:91], v[94:95], v[224:225]
	v_pk_fma_f32 v[64:65], v[88:89], v[92:93], v[222:223]
	global_store_dwordx4 v[84:85], v[64:67], off nt
	s_cbranch_vccnz .LBB0_710
	ds_read_b128 v[88:91], v73 offset:2048
	v_lshlrev_b64 v[82:83], 10, v[82:83]
	v_lshl_add_u64 v[82:83], v[82:83], 1, s[42:43]
	v_lshl_add_u64 v[82:83], v[98:99], 1, v[82:83]
	s_waitcnt lgkmcnt(0)
	v_pk_mul_f32 v[88:89], v[64:65], v[88:89]
	v_pk_mul_f32 v[64:65], v[64:65], v[64:65]
	v_pk_mul_f32 v[84:85], v[66:67], v[90:91]
	v_pk_mul_f32 v[66:67], v[66:67], v[66:67]
	v_add_f32_e32 v64, v64, v65
	v_add_f32_e32 v64, v66, v64
	v_add_f32_e32 v64, v67, v64
	v_cvt_pk_bf16_f32 v88, v88, v89
	v_cvt_pk_bf16_f32 v89, v84, v85
	v_add_f32_dpp v64, v64, v64 quad_perm:[1,0,3,2] row_mask:0xf bank_mask:0xf bound_ctrl:1
	global_store_dwordx2 v[82:83], v[88:89], off
	s_nop 0
	v_add_f32_dpp v64, v64, v64 quad_perm:[2,3,0,1] row_mask:0xf bank_mask:0xf bound_ctrl:1
	s_nop 1
	v_add_f32_dpp v64, v64, v64 row_half_mirror row_mask:0xf bank_mask:0xf bound_ctrl:1
	s_nop 1
	v_mov_b32_dpp v65, v64 row_mirror row_mask:0xf bank_mask:0xf bound_ctrl:1
	s_and_saveexec_b64 s[4:5], s[36:37]
	s_cbranch_execz .LBB0_709
	v_ashrrev_i32_e32 v97, 31, v96
	v_lshl_add_u64 v[66:67], s[52:53], 0, v[68:69]
	v_lshl_add_u64 v[82:83], v[96:97], 0, v[128:129]
	v_lshl_add_u64 v[66:67], v[82:83], 2, v[66:67]
	v_add_f32_e32 v64, v64, v65
	global_store_dword v[66:67], v64, off offset:96

.LBB0_710:
	v_or_b32_e32 v82, 28, v128
	v_or_b32_e32 v84, v96, v82
	v_ashrrev_i32_e32 v85, 31, v84
	v_lshlrev_b64 v[64:65], 12, v[84:85]
	v_lshl_add_u64 v[64:65], s[40:41], 0, v[64:65]
	v_lshl_add_u64 v[100:101], v[98:99], 2, v[64:65]
	s_movk_i32 s4, 0x1000
	v_cmp_gt_i32_e32 vcc, s4, v84
	s_nop 1
	v_cndmask_b32_e32 v71, v71, v102, vcc
	v_and_b32_e32 v71, 1, v71
	v_cmp_eq_u32_e32 vcc, 1, v71
	s_nop 1
	v_cndmask_b32_e64 v71, v171, 0, vcc
	v_add_u32_e32 v71, v103, v71
	ds_read_b128 v[88:91], v86 offset:7616
	ds_read_b128 v[92:95], v71
	s_and_b64 vcc, exec, s[0:1]
	s_waitcnt lgkmcnt(0)
	v_pk_fma_f32 v[66:67], v[90:91], v[94:95], v[228:229]
	v_pk_fma_f32 v[64:65], v[88:89], v[92:93], v[226:227]
	global_store_dwordx4 v[100:101], v[64:67], off nt
	s_cbranch_vccnz .LBB0_714
	ds_read_b128 v[88:91], v71 offset:2048
	v_lshlrev_b64 v[84:85], 10, v[84:85]
	v_lshl_add_u64 v[84:85], v[84:85], 1, s[42:43]
	v_lshl_add_u64 v[84:85], v[98:99], 1, v[84:85]
	s_waitcnt lgkmcnt(0)
	v_pk_mul_f32 v[88:89], v[64:65], v[88:89]
	v_pk_mul_f32 v[64:65], v[64:65], v[64:65]
	v_pk_mul_f32 v[90:91], v[66:67], v[90:91]
	v_pk_mul_f32 v[66:67], v[66:67], v[66:67]
	v_add_f32_e32 v64, v64, v65
	v_add_f32_e32 v64, v66, v64
	v_add_f32_e32 v64, v67, v64
	v_cvt_pk_bf16_f32 v88, v88, v89
	v_cvt_pk_bf16_f32 v89, v90, v91
	v_add_f32_dpp v64, v64, v64 quad_perm:[1,0,3,2] row_mask:0xf bank_mask:0xf bound_ctrl:1
	global_store_dwordx2 v[84:85], v[88:89], off
	s_nop 0
	v_add_f32_dpp v64, v64, v64 quad_perm:[2,3,0,1] row_mask:0xf bank_mask:0xf bound_ctrl:1
	s_nop 1
	v_add_f32_dpp v64, v64, v64 row_half_mirror row_mask:0xf bank_mask:0xf bound_ctrl:1
	s_nop 1
	v_mov_b32_dpp v65, v64 row_mirror row_mask:0xf bank_mask:0xf bound_ctrl:1
	s_and_saveexec_b64 s[4:5], s[36:37]
	s_cbranch_execz .LBB0_713
	v_ashrrev_i32_e32 v97, 31, v96
	v_lshl_add_u64 v[66:67], s[52:53], 0, v[68:69]
	v_lshl_add_u64 v[84:85], v[96:97], 0, v[128:129]
	v_lshl_add_u64 v[66:67], v[84:85], 2, v[66:67]
	v_add_f32_e32 v64, v64, v65
	global_store_dword v[66:67], v64, off offset:112

.LBB0_714:
	s_nop 0
	v_add_u32_e32 v66, 32, v96
	v_or_b32_e32 v64, v66, v128
	v_ashrrev_i32_e32 v65, 31, v64
	v_lshlrev_b64 v[84:85], 12, v[64:65]
	v_lshl_add_u64 v[84:85], s[40:41], 0, v[84:85]
	v_lshl_add_u64 v[84:85], v[98:99], 2, v[84:85]
	v_add_co_u32_e32 v182, vcc, 0x20000, v84
	s_nop 1
	v_addc_co_u32_e32 v183, vcc, 0, v85, vcc
	global_load_dwordx4 v[198:201], v[182:183], off
	v_add_co_u32_e32 v182, vcc, 0x4000, v182
	s_nop 1
	v_addc_co_u32_e32 v183, vcc, 0, v183, vcc
	global_load_dwordx4 v[202:205], v[182:183], off
	v_add_co_u32_e32 v182, vcc, 0x4000, v182
	s_nop 1
	v_addc_co_u32_e32 v183, vcc, 0, v183, vcc
	global_load_dwordx4 v[206:209], v[182:183], off
	v_add_co_u32_e32 v182, vcc, 0x4000, v182
	s_nop 1
	v_addc_co_u32_e32 v183, vcc, 0, v183, vcc
	global_load_dwordx4 v[210:213], v[182:183], off
	v_add_co_u32_e32 v182, vcc, 0x4000, v182
	s_nop 1
	v_addc_co_u32_e32 v183, vcc, 0, v183, vcc
	global_load_dwordx4 v[214:217], v[182:183], off
	v_add_co_u32_e32 v182, vcc, 0x4000, v182
	s_nop 1
	v_addc_co_u32_e32 v183, vcc, 0, v183, vcc
	global_load_dwordx4 v[218:221], v[182:183], off
	v_add_co_u32_e32 v182, vcc, 0x4000, v182
	s_nop 1
	v_addc_co_u32_e32 v183, vcc, 0, v183, vcc
	global_load_dwordx4 v[222:225], v[182:183], off
	v_add_co_u32_e32 v182, vcc, 0x4000, v182
	s_nop 1
	v_addc_co_u32_e32 v183, vcc, 0, v183, vcc
	global_load_dwordx4 v[226:229], v[182:183], off
	ds_write_b128 v104, v[32:35]
	ds_write_b128 v104, v[36:39] offset:32
	ds_write_b128 v104, v[40:43] offset:64
	ds_write_b128 v104, v[44:47] offset:96
	ds_write_b128 v104, v[48:51] offset:128
	ds_write_b128 v104, v[52:55] offset:160
	ds_write_b128 v104, v[56:59] offset:192
	ds_write_b128 v104, v[60:63] offset:224
	v_add_u32_e32 v32, 0xfffff020, v96
	v_xor_b32_e32 v32, s7, v32
	s_movk_i32 s4, 0x400
	v_cmp_gt_u32_e32 vcc, s4, v32
	s_and_b64 s[4:5], s[2:3], vcc
	v_cndmask_b32_e64 v38, 0, 1, s[4:5]
	s_movk_i32 s4, 0x1000
	v_cmp_gt_i32_e32 vcc, s4, v64
	s_nop 1
	v_cndmask_b32_e32 v32, v38, v102, vcc
	v_and_b32_e32 v32, 1, v32
	v_cmp_eq_u32_e32 vcc, 1, v32
	s_nop 1
	v_cndmask_b32_e64 v32, v171, 0, vcc
	v_add_u32_e32 v36, v103, v32
	ds_read_b128 v[32:35], v86
	ds_read_b128 v[40:43], v36
	s_and_b64 vcc, exec, s[0:1]
	s_waitcnt vmcnt(23) lgkmcnt(0)
	v_pk_fma_f32 v[34:35], v[34:35], v[42:43], v[186:187]
	v_pk_fma_f32 v[32:33], v[32:33], v[40:41], v[184:185]
	global_store_dwordx4 v[84:85], v[32:35], off nt
	s_cbranch_vccnz .LBB0_718
	ds_read_b128 v[40:43], v36 offset:2048
	v_lshlrev_b64 v[36:37], 10, v[64:65]
	v_lshl_add_u64 v[36:37], v[36:37], 1, s[42:43]
	v_lshl_add_u64 v[36:37], v[98:99], 1, v[36:37]
	s_waitcnt lgkmcnt(0)
	v_pk_mul_f32 v[40:41], v[32:33], v[40:41]
	v_pk_mul_f32 v[32:33], v[32:33], v[32:33]
	v_pk_mul_f32 v[42:43], v[34:35], v[42:43]
	v_pk_mul_f32 v[34:35], v[34:35], v[34:35]
	v_add_f32_e32 v32, v32, v33
	v_add_f32_e32 v32, v34, v32
	v_add_f32_e32 v32, v35, v32
	v_cvt_pk_bf16_f32 v40, v40, v41
	v_cvt_pk_bf16_f32 v41, v42, v43
	v_add_f32_dpp v32, v32, v32 quad_perm:[1,0,3,2] row_mask:0xf bank_mask:0xf bound_ctrl:1
	global_store_dwordx2 v[36:37], v[40:41], off
	s_nop 0
	v_add_f32_dpp v32, v32, v32 quad_perm:[2,3,0,1] row_mask:0xf bank_mask:0xf bound_ctrl:1
	s_nop 1
	v_add_f32_dpp v32, v32, v32 row_half_mirror row_mask:0xf bank_mask:0xf bound_ctrl:1
	s_nop 1
	v_mov_b32_dpp v33, v32 row_mirror row_mask:0xf bank_mask:0xf bound_ctrl:1
	s_and_saveexec_b64 s[4:5], s[36:37]
	s_cbranch_execz .LBB0_717
	v_ashrrev_i32_e32 v97, 31, v96
	v_lshl_add_u64 v[34:35], s[52:53], 0, v[68:69]
	v_lshl_add_u64 v[36:37], v[96:97], 0, v[128:129]
	v_lshl_add_u64 v[34:35], v[36:37], 2, v[34:35]
	v_add_f32_e32 v32, v32, v33
	global_store_dword v[34:35], v32, off offset:128

.LBB0_718:
	v_or_b32_e32 v36, v66, v70
	v_ashrrev_i32_e32 v37, 31, v36
	v_lshlrev_b64 v[32:33], 12, v[36:37]
	v_lshl_add_u64 v[32:33], s[40:41], 0, v[32:33]
	v_lshl_add_u64 v[48:49], v[98:99], 2, v[32:33]
	s_movk_i32 s4, 0x1000
	v_cmp_gt_i32_e32 vcc, s4, v36
	s_nop 1
	v_cndmask_b32_e32 v39, v38, v102, vcc
	v_and_b32_e32 v39, 1, v39
	v_cmp_eq_u32_e32 vcc, 1, v39
	s_nop 1
	v_cndmask_b32_e64 v39, v171, 0, vcc
	v_add_u32_e32 v39, v103, v39
	ds_read_b128 v[40:43], v86 offset:1088
	ds_read_b128 v[44:47], v39
	s_and_b64 vcc, exec, s[0:1]
	s_waitcnt vmcnt(23) lgkmcnt(0)
	v_pk_fma_f32 v[34:35], v[42:43], v[46:47], v[190:191]
	v_pk_fma_f32 v[32:33], v[40:41], v[44:45], v[188:189]
	global_store_dwordx4 v[48:49], v[32:35], off nt
	s_cbranch_vccnz .LBB0_722
	ds_read_b128 v[40:43], v39 offset:2048
	v_lshlrev_b64 v[36:37], 10, v[36:37]
	v_lshl_add_u64 v[36:37], v[36:37], 1, s[42:43]
	v_lshl_add_u64 v[36:37], v[98:99], 1, v[36:37]
	s_waitcnt lgkmcnt(0)
	v_pk_mul_f32 v[40:41], v[32:33], v[40:41]
	v_pk_mul_f32 v[32:33], v[32:33], v[32:33]
	v_pk_mul_f32 v[42:43], v[34:35], v[42:43]
	v_pk_mul_f32 v[34:35], v[34:35], v[34:35]
	v_add_f32_e32 v32, v32, v33
	v_add_f32_e32 v32, v34, v32
	v_add_f32_e32 v32, v35, v32
	v_cvt_pk_bf16_f32 v40, v40, v41
	v_cvt_pk_bf16_f32 v41, v42, v43
	v_add_f32_dpp v32, v32, v32 quad_perm:[1,0,3,2] row_mask:0xf bank_mask:0xf bound_ctrl:1
	global_store_dwordx2 v[36:37], v[40:41], off
	s_nop 0
	v_add_f32_dpp v32, v32, v32 quad_perm:[2,3,0,1] row_mask:0xf bank_mask:0xf bound_ctrl:1
	s_nop 1
	v_add_f32_dpp v32, v32, v32 row_half_mirror row_mask:0xf bank_mask:0xf bound_ctrl:1
	s_nop 1
	v_mov_b32_dpp v33, v32 row_mirror row_mask:0xf bank_mask:0xf bound_ctrl:1
	s_and_saveexec_b64 s[4:5], s[36:37]
	s_cbranch_execz .LBB0_721
	v_mov_b32_e32 v71, v129
	v_ashrrev_i32_e32 v97, 31, v96
	v_lshl_add_u64 v[34:35], s[52:53], 0, v[68:69]
	v_lshl_add_u64 v[36:37], v[96:97], 0, v[70:71]
	v_lshl_add_u64 v[34:35], v[36:37], 2, v[34:35]
	v_add_f32_e32 v32, v32, v33
	global_store_dword v[34:35], v32, off offset:128

.LBB0_722:
	v_or_b32_e32 v36, v66, v72
	v_ashrrev_i32_e32 v37, 31, v36
	v_lshlrev_b64 v[32:33], 12, v[36:37]
	v_lshl_add_u64 v[32:33], s[40:41], 0, v[32:33]
	v_lshl_add_u64 v[48:49], v[98:99], 2, v[32:33]
	s_movk_i32 s4, 0x1000
	v_cmp_gt_i32_e32 vcc, s4, v36
	s_nop 1
	v_cndmask_b32_e32 v39, v38, v102, vcc
	v_and_b32_e32 v39, 1, v39
	v_cmp_eq_u32_e32 vcc, 1, v39
	s_nop 1
	v_cndmask_b32_e64 v39, v171, 0, vcc
	v_add_u32_e32 v39, v103, v39
	ds_read_b128 v[40:43], v86 offset:2176
	ds_read_b128 v[44:47], v39
	s_and_b64 vcc, exec, s[0:1]
	s_waitcnt vmcnt(23) lgkmcnt(0)
	v_pk_fma_f32 v[34:35], v[42:43], v[46:47], v[194:195]
	v_pk_fma_f32 v[32:33], v[40:41], v[44:45], v[192:193]
	global_store_dwordx4 v[48:49], v[32:35], off nt
	s_cbranch_vccnz .LBB0_726
	ds_read_b128 v[40:43], v39 offset:2048
	v_lshlrev_b64 v[36:37], 10, v[36:37]
	v_lshl_add_u64 v[36:37], v[36:37], 1, s[42:43]
	v_lshl_add_u64 v[36:37], v[98:99], 1, v[36:37]
	s_waitcnt lgkmcnt(0)
	v_pk_mul_f32 v[40:41], v[32:33], v[40:41]
	v_pk_mul_f32 v[32:33], v[32:33], v[32:33]
	v_pk_mul_f32 v[42:43], v[34:35], v[42:43]
	v_pk_mul_f32 v[34:35], v[34:35], v[34:35]
	v_add_f32_e32 v32, v32, v33
	v_add_f32_e32 v32, v34, v32
	v_add_f32_e32 v32, v35, v32
	v_cvt_pk_bf16_f32 v40, v40, v41
	v_cvt_pk_bf16_f32 v41, v42, v43
	v_add_f32_dpp v32, v32, v32 quad_perm:[1,0,3,2] row_mask:0xf bank_mask:0xf bound_ctrl:1
	global_store_dwordx2 v[36:37], v[40:41], off
	s_nop 0
	v_add_f32_dpp v32, v32, v32 quad_perm:[2,3,0,1] row_mask:0xf bank_mask:0xf bound_ctrl:1
	s_nop 1
	v_add_f32_dpp v32, v32, v32 row_half_mirror row_mask:0xf bank_mask:0xf bound_ctrl:1
	s_nop 1
	v_mov_b32_dpp v33, v32 row_mirror row_mask:0xf bank_mask:0xf bound_ctrl:1
	s_and_saveexec_b64 s[4:5], s[36:37]
	s_cbranch_execz .LBB0_725
	v_mov_b32_e32 v73, v129
	v_ashrrev_i32_e32 v97, 31, v96
	v_lshl_add_u64 v[34:35], s[52:53], 0, v[68:69]
	v_lshl_add_u64 v[36:37], v[96:97], 0, v[72:73]
	v_lshl_add_u64 v[34:35], v[36:37], 2, v[34:35]
	v_add_f32_e32 v32, v32, v33
	global_store_dword v[34:35], v32, off offset:128

.LBB0_726:
	v_or_b32_e32 v36, v66, v74
	v_ashrrev_i32_e32 v37, 31, v36
	v_lshlrev_b64 v[32:33], 12, v[36:37]
	v_lshl_add_u64 v[32:33], s[40:41], 0, v[32:33]
	v_lshl_add_u64 v[48:49], v[98:99], 2, v[32:33]
	s_movk_i32 s4, 0x1000
	v_cmp_gt_i32_e32 vcc, s4, v36
	s_nop 1
	v_cndmask_b32_e32 v39, v38, v102, vcc
	v_and_b32_e32 v39, 1, v39
	v_cmp_eq_u32_e32 vcc, 1, v39
	s_nop 1
	v_cndmask_b32_e64 v39, v171, 0, vcc
	v_add_u32_e32 v39, v103, v39
	ds_read_b128 v[40:43], v86 offset:3264
	ds_read_b128 v[44:47], v39
	s_and_b64 vcc, exec, s[0:1]
	s_waitcnt vmcnt(23) lgkmcnt(0)
	v_pk_fma_f32 v[34:35], v[42:43], v[46:47], v[118:119]
	v_pk_fma_f32 v[32:33], v[40:41], v[44:45], v[116:117]
	global_store_dwordx4 v[48:49], v[32:35], off nt
	s_cbranch_vccnz .LBB0_730
	ds_read_b128 v[40:43], v39 offset:2048
	v_lshlrev_b64 v[36:37], 10, v[36:37]
	v_lshl_add_u64 v[36:37], v[36:37], 1, s[42:43]
	v_lshl_add_u64 v[36:37], v[98:99], 1, v[36:37]
	s_waitcnt lgkmcnt(0)
	v_pk_mul_f32 v[40:41], v[32:33], v[40:41]
	v_pk_mul_f32 v[32:33], v[32:33], v[32:33]
	v_pk_mul_f32 v[42:43], v[34:35], v[42:43]
	v_pk_mul_f32 v[34:35], v[34:35], v[34:35]
	v_add_f32_e32 v32, v32, v33
	v_add_f32_e32 v32, v34, v32
	v_add_f32_e32 v32, v35, v32
	v_cvt_pk_bf16_f32 v40, v40, v41
	v_cvt_pk_bf16_f32 v41, v42, v43
	v_add_f32_dpp v32, v32, v32 quad_perm:[1,0,3,2] row_mask:0xf bank_mask:0xf bound_ctrl:1
	global_store_dwordx2 v[36:37], v[40:41], off
	s_nop 0
	v_add_f32_dpp v32, v32, v32 quad_perm:[2,3,0,1] row_mask:0xf bank_mask:0xf bound_ctrl:1
	s_nop 1
	v_add_f32_dpp v32, v32, v32 row_half_mirror row_mask:0xf bank_mask:0xf bound_ctrl:1
	s_nop 1
	v_mov_b32_dpp v33, v32 row_mirror row_mask:0xf bank_mask:0xf bound_ctrl:1
	s_and_saveexec_b64 s[4:5], s[36:37]
	s_cbranch_execz .LBB0_729
	v_mov_b32_e32 v75, v129
	v_ashrrev_i32_e32 v97, 31, v96
	v_lshl_add_u64 v[34:35], s[52:53], 0, v[68:69]
	v_lshl_add_u64 v[36:37], v[96:97], 0, v[74:75]
	v_lshl_add_u64 v[34:35], v[36:37], 2, v[34:35]
	v_add_f32_e32 v32, v32, v33
	global_store_dword v[34:35], v32, off offset:128

.LBB0_730:
	v_or_b32_e32 v36, v66, v76
	v_ashrrev_i32_e32 v37, 31, v36
	v_lshlrev_b64 v[32:33], 12, v[36:37]
	v_lshl_add_u64 v[32:33], s[40:41], 0, v[32:33]
	v_lshl_add_u64 v[48:49], v[98:99], 2, v[32:33]
	s_movk_i32 s4, 0x1000
	v_cmp_gt_i32_e32 vcc, s4, v36
	s_nop 1
	v_cndmask_b32_e32 v39, v38, v102, vcc
	v_and_b32_e32 v39, 1, v39
	v_cmp_eq_u32_e32 vcc, 1, v39
	s_nop 1
	v_cndmask_b32_e64 v39, v171, 0, vcc
	v_add_u32_e32 v39, v103, v39
	ds_read_b128 v[40:43], v86 offset:4352
	ds_read_b128 v[44:47], v39
	s_and_b64 vcc, exec, s[0:1]
	s_waitcnt vmcnt(23) lgkmcnt(0)
	v_pk_fma_f32 v[34:35], v[42:43], v[46:47], v[122:123]
	v_pk_fma_f32 v[32:33], v[40:41], v[44:45], v[120:121]
	global_store_dwordx4 v[48:49], v[32:35], off nt
	s_cbranch_vccnz .LBB0_734
	ds_read_b128 v[40:43], v39 offset:2048
	v_lshlrev_b64 v[36:37], 10, v[36:37]
	v_lshl_add_u64 v[36:37], v[36:37], 1, s[42:43]
	v_lshl_add_u64 v[36:37], v[98:99], 1, v[36:37]
	s_waitcnt lgkmcnt(0)
	v_pk_mul_f32 v[40:41], v[32:33], v[40:41]
	v_pk_mul_f32 v[32:33], v[32:33], v[32:33]
	v_pk_mul_f32 v[42:43], v[34:35], v[42:43]
	v_pk_mul_f32 v[34:35], v[34:35], v[34:35]
	v_add_f32_e32 v32, v32, v33
	v_add_f32_e32 v32, v34, v32
	v_add_f32_e32 v32, v35, v32
	v_cvt_pk_bf16_f32 v40, v40, v41
	v_cvt_pk_bf16_f32 v41, v42, v43
	v_add_f32_dpp v32, v32, v32 quad_perm:[1,0,3,2] row_mask:0xf bank_mask:0xf bound_ctrl:1
	global_store_dwordx2 v[36:37], v[40:41], off
	s_nop 0
	v_add_f32_dpp v32, v32, v32 quad_perm:[2,3,0,1] row_mask:0xf bank_mask:0xf bound_ctrl:1
	s_nop 1
	v_add_f32_dpp v32, v32, v32 row_half_mirror row_mask:0xf bank_mask:0xf bound_ctrl:1
	s_nop 1
	v_mov_b32_dpp v33, v32 row_mirror row_mask:0xf bank_mask:0xf bound_ctrl:1
	s_and_saveexec_b64 s[4:5], s[36:37]
	s_cbranch_execz .LBB0_733
	v_mov_b32_e32 v77, v129
	v_ashrrev_i32_e32 v97, 31, v96
	v_lshl_add_u64 v[34:35], s[52:53], 0, v[68:69]
	v_lshl_add_u64 v[36:37], v[96:97], 0, v[76:77]
	v_lshl_add_u64 v[34:35], v[36:37], 2, v[34:35]
	v_add_f32_e32 v32, v32, v33
	global_store_dword v[34:35], v32, off offset:128

.LBB0_734:
	v_or_b32_e32 v36, v66, v78
	v_ashrrev_i32_e32 v37, 31, v36
	v_lshlrev_b64 v[32:33], 12, v[36:37]
	v_lshl_add_u64 v[32:33], s[40:41], 0, v[32:33]
	v_lshl_add_u64 v[48:49], v[98:99], 2, v[32:33]
	s_movk_i32 s4, 0x1000
	v_cmp_gt_i32_e32 vcc, s4, v36
	s_nop 1
	v_cndmask_b32_e32 v39, v38, v102, vcc
	v_and_b32_e32 v39, 1, v39
	v_cmp_eq_u32_e32 vcc, 1, v39
	s_nop 1
	v_cndmask_b32_e64 v39, v171, 0, vcc
	v_add_u32_e32 v39, v103, v39
	ds_read_b128 v[40:43], v86 offset:5440
	ds_read_b128 v[44:47], v39
	s_and_b64 vcc, exec, s[0:1]
	s_waitcnt vmcnt(23) lgkmcnt(0)
	v_pk_fma_f32 v[34:35], v[42:43], v[46:47], v[126:127]
	v_pk_fma_f32 v[32:33], v[40:41], v[44:45], v[124:125]
	global_store_dwordx4 v[48:49], v[32:35], off nt
	s_cbranch_vccnz .LBB0_738
	ds_read_b128 v[40:43], v39 offset:2048
	v_lshlrev_b64 v[36:37], 10, v[36:37]
	v_lshl_add_u64 v[36:37], v[36:37], 1, s[42:43]
	v_lshl_add_u64 v[36:37], v[98:99], 1, v[36:37]
	s_waitcnt lgkmcnt(0)
	v_pk_mul_f32 v[40:41], v[32:33], v[40:41]
	v_pk_mul_f32 v[32:33], v[32:33], v[32:33]
	v_pk_mul_f32 v[42:43], v[34:35], v[42:43]
	v_pk_mul_f32 v[34:35], v[34:35], v[34:35]
	v_add_f32_e32 v32, v32, v33
	v_add_f32_e32 v32, v34, v32
	v_add_f32_e32 v32, v35, v32
	v_cvt_pk_bf16_f32 v40, v40, v41
	v_cvt_pk_bf16_f32 v41, v42, v43
	v_add_f32_dpp v32, v32, v32 quad_perm:[1,0,3,2] row_mask:0xf bank_mask:0xf bound_ctrl:1
	global_store_dwordx2 v[36:37], v[40:41], off
	s_nop 0
	v_add_f32_dpp v32, v32, v32 quad_perm:[2,3,0,1] row_mask:0xf bank_mask:0xf bound_ctrl:1
	s_nop 1
	v_add_f32_dpp v32, v32, v32 row_half_mirror row_mask:0xf bank_mask:0xf bound_ctrl:1
	s_nop 1
	v_mov_b32_dpp v33, v32 row_mirror row_mask:0xf bank_mask:0xf bound_ctrl:1
	s_and_saveexec_b64 s[4:5], s[36:37]
	s_cbranch_execz .LBB0_737
	v_mov_b32_e32 v79, v129
	v_ashrrev_i32_e32 v97, 31, v96
	v_lshl_add_u64 v[34:35], s[52:53], 0, v[68:69]
	v_lshl_add_u64 v[36:37], v[96:97], 0, v[78:79]
	v_lshl_add_u64 v[34:35], v[36:37], 2, v[34:35]
	v_add_f32_e32 v32, v32, v33
	global_store_dword v[34:35], v32, off offset:128

.LBB0_738:
	v_or_b32_e32 v36, v66, v80
	v_ashrrev_i32_e32 v37, 31, v36
	v_lshlrev_b64 v[32:33], 12, v[36:37]
	v_lshl_add_u64 v[32:33], s[40:41], 0, v[32:33]
	v_lshl_add_u64 v[48:49], v[98:99], 2, v[32:33]
	s_movk_i32 s4, 0x1000
	v_cmp_gt_i32_e32 vcc, s4, v36
	s_nop 1
	v_cndmask_b32_e32 v39, v38, v102, vcc
	v_and_b32_e32 v39, 1, v39
	v_cmp_eq_u32_e32 vcc, 1, v39
	s_nop 1
	v_cndmask_b32_e64 v39, v171, 0, vcc
	v_add_u32_e32 v39, v103, v39
	ds_read_b128 v[40:43], v86 offset:6528
	ds_read_b128 v[44:47], v39
	s_and_b64 vcc, exec, s[0:1]
	s_waitcnt vmcnt(23) lgkmcnt(0)
	v_pk_fma_f32 v[34:35], v[42:43], v[46:47], v[132:133]
	v_pk_fma_f32 v[32:33], v[40:41], v[44:45], v[130:131]
	global_store_dwordx4 v[48:49], v[32:35], off nt
	s_cbranch_vccnz .LBB0_742
	ds_read_b128 v[40:43], v39 offset:2048
	v_lshlrev_b64 v[36:37], 10, v[36:37]
	v_lshl_add_u64 v[36:37], v[36:37], 1, s[42:43]
	v_lshl_add_u64 v[36:37], v[98:99], 1, v[36:37]
	s_waitcnt lgkmcnt(0)
	v_pk_mul_f32 v[40:41], v[32:33], v[40:41]
	v_pk_mul_f32 v[32:33], v[32:33], v[32:33]
	v_pk_mul_f32 v[42:43], v[34:35], v[42:43]
	v_pk_mul_f32 v[34:35], v[34:35], v[34:35]
	v_add_f32_e32 v32, v32, v33
	v_add_f32_e32 v32, v34, v32
	v_add_f32_e32 v32, v35, v32
	v_cvt_pk_bf16_f32 v40, v40, v41
	v_cvt_pk_bf16_f32 v41, v42, v43
	v_add_f32_dpp v32, v32, v32 quad_perm:[1,0,3,2] row_mask:0xf bank_mask:0xf bound_ctrl:1
	global_store_dwordx2 v[36:37], v[40:41], off
	s_nop 0
	v_add_f32_dpp v32, v32, v32 quad_perm:[2,3,0,1] row_mask:0xf bank_mask:0xf bound_ctrl:1
	s_nop 1
	v_add_f32_dpp v32, v32, v32 row_half_mirror row_mask:0xf bank_mask:0xf bound_ctrl:1
	s_nop 1
	v_mov_b32_dpp v33, v32 row_mirror row_mask:0xf bank_mask:0xf bound_ctrl:1
	s_and_saveexec_b64 s[4:5], s[36:37]
	s_cbranch_execz .LBB0_741
	v_mov_b32_e32 v81, v129
	v_ashrrev_i32_e32 v97, 31, v96
	v_lshl_add_u64 v[34:35], s[52:53], 0, v[68:69]
	v_lshl_add_u64 v[36:37], v[96:97], 0, v[80:81]
	v_lshl_add_u64 v[34:35], v[36:37], 2, v[34:35]
	v_add_f32_e32 v32, v32, v33
	global_store_dword v[34:35], v32, off offset:128

.LBB0_742:
	v_or_b32_e32 v36, v66, v82
	v_ashrrev_i32_e32 v37, 31, v36
	v_lshlrev_b64 v[32:33], 12, v[36:37]
	v_lshl_add_u64 v[32:33], s[40:41], 0, v[32:33]
	v_lshl_add_u64 v[48:49], v[98:99], 2, v[32:33]
	s_movk_i32 s4, 0x1000
	v_cmp_gt_i32_e32 vcc, s4, v36
	s_nop 1
	v_cndmask_b32_e32 v38, v38, v102, vcc
	v_and_b32_e32 v38, 1, v38
	v_cmp_eq_u32_e32 vcc, 1, v38
	s_nop 1
	v_cndmask_b32_e64 v38, v171, 0, vcc
	v_add_u32_e32 v38, v103, v38
	ds_read_b128 v[40:43], v86 offset:7616
	ds_read_b128 v[44:47], v38
	s_and_b64 vcc, exec, s[0:1]
	s_waitcnt vmcnt(23) lgkmcnt(0)
	v_pk_fma_f32 v[34:35], v[42:43], v[46:47], v[136:137]
	v_pk_fma_f32 v[32:33], v[40:41], v[44:45], v[134:135]
	global_store_dwordx4 v[48:49], v[32:35], off nt
	s_cbranch_vccnz .LBB0_746
	ds_read_b128 v[38:41], v38 offset:2048
	v_lshlrev_b64 v[36:37], 10, v[36:37]
	v_lshl_add_u64 v[36:37], v[36:37], 1, s[42:43]
	v_lshl_add_u64 v[36:37], v[98:99], 1, v[36:37]
	s_waitcnt lgkmcnt(0)
	v_pk_mul_f32 v[38:39], v[32:33], v[38:39]
	v_pk_mul_f32 v[32:33], v[32:33], v[32:33]
	v_pk_mul_f32 v[40:41], v[34:35], v[40:41]
	v_pk_mul_f32 v[34:35], v[34:35], v[34:35]
	v_add_f32_e32 v32, v32, v33
	v_add_f32_e32 v32, v34, v32
	v_add_f32_e32 v32, v35, v32
	v_cvt_pk_bf16_f32 v38, v38, v39
	v_cvt_pk_bf16_f32 v39, v40, v41
	v_add_f32_dpp v32, v32, v32 quad_perm:[1,0,3,2] row_mask:0xf bank_mask:0xf bound_ctrl:1
	global_store_dwordx2 v[36:37], v[38:39], off
	s_nop 0
	v_add_f32_dpp v32, v32, v32 quad_perm:[2,3,0,1] row_mask:0xf bank_mask:0xf bound_ctrl:1
	s_nop 1
	v_add_f32_dpp v32, v32, v32 row_half_mirror row_mask:0xf bank_mask:0xf bound_ctrl:1
	s_nop 1
	v_mov_b32_dpp v33, v32 row_mirror row_mask:0xf bank_mask:0xf bound_ctrl:1
	s_and_saveexec_b64 s[4:5], s[36:37]
	s_cbranch_execz .LBB0_745
	v_mov_b32_e32 v83, v129
	v_ashrrev_i32_e32 v97, 31, v96
	v_lshl_add_u64 v[34:35], s[52:53], 0, v[68:69]
	v_lshl_add_u64 v[36:37], v[96:97], 0, v[82:83]
	v_lshl_add_u64 v[34:35], v[36:37], 2, v[34:35]
	v_add_f32_e32 v32, v32, v33
	global_store_dword v[34:35], v32, off offset:128

.LBB0_746:
	s_nop 0
	v_add_u32_e32 v34, 64, v96
	v_or_b32_e32 v32, v34, v128
	v_ashrrev_i32_e32 v33, 31, v32
	v_lshlrev_b64 v[36:37], 12, v[32:33]
	v_lshl_add_u64 v[36:37], s[40:41], 0, v[36:37]
	v_lshl_add_u64 v[40:41], v[98:99], 2, v[36:37]
	ds_write_b128 v104, v[0:3]
	ds_write_b128 v104, v[4:7] offset:32
	ds_write_b128 v104, v[8:11] offset:64
	ds_write_b128 v104, v[12:15] offset:96
	ds_write_b128 v104, v[16:19] offset:128
	ds_write_b128 v104, v[20:23] offset:160
	ds_write_b128 v104, v[24:27] offset:192
	ds_write_b128 v104, v[28:31] offset:224
	v_add_u32_e32 v0, 0xfffff040, v96
	v_xor_b32_e32 v0, s7, v0
	s_movk_i32 s4, 0x400
	v_cmp_gt_u32_e32 vcc, s4, v0
	s_and_b64 s[2:3], s[2:3], vcc
	v_cndmask_b32_e64 v6, 0, 1, s[2:3]
	s_movk_i32 s2, 0x1000
	v_cmp_gt_i32_e32 vcc, s2, v32
	s_nop 1
	v_cndmask_b32_e32 v0, v6, v102, vcc
	v_and_b32_e32 v0, 1, v0
	v_cmp_eq_u32_e32 vcc, 1, v0
	s_nop 1
	v_cndmask_b32_e64 v0, v171, 0, vcc
	v_add_u32_e32 v4, v103, v0
	ds_read_b128 v[0:3], v86
	ds_read_b128 v[8:11], v4
	s_and_b64 vcc, exec, s[0:1]
	s_waitcnt vmcnt(15) lgkmcnt(0)
	v_pk_fma_f32 v[2:3], v[2:3], v[10:11], v[200:201]
	v_pk_fma_f32 v[0:1], v[0:1], v[8:9], v[198:199]
	global_store_dwordx4 v[40:41], v[0:3], off nt
	s_cbranch_vccnz .LBB0_750
	ds_read_b128 v[8:11], v4 offset:2048
	v_lshlrev_b64 v[4:5], 10, v[32:33]
	v_lshl_add_u64 v[4:5], v[4:5], 1, s[42:43]
	v_lshl_add_u64 v[4:5], v[98:99], 1, v[4:5]
	s_waitcnt lgkmcnt(0)
	v_pk_mul_f32 v[8:9], v[0:1], v[8:9]
	v_pk_mul_f32 v[0:1], v[0:1], v[0:1]
	v_pk_mul_f32 v[10:11], v[2:3], v[10:11]
	v_pk_mul_f32 v[2:3], v[2:3], v[2:3]
	v_add_f32_e32 v0, v0, v1
	v_add_f32_e32 v0, v2, v0
	v_add_f32_e32 v0, v3, v0
	v_cvt_pk_bf16_f32 v8, v8, v9
	v_cvt_pk_bf16_f32 v9, v10, v11
	v_add_f32_dpp v0, v0, v0 quad_perm:[1,0,3,2] row_mask:0xf bank_mask:0xf bound_ctrl:1
	global_store_dwordx2 v[4:5], v[8:9], off
	s_nop 0
	v_add_f32_dpp v0, v0, v0 quad_perm:[2,3,0,1] row_mask:0xf bank_mask:0xf bound_ctrl:1
	s_nop 1
	v_add_f32_dpp v0, v0, v0 row_half_mirror row_mask:0xf bank_mask:0xf bound_ctrl:1
	s_nop 1
	v_mov_b32_dpp v1, v0 row_mirror row_mask:0xf bank_mask:0xf bound_ctrl:1
	s_and_saveexec_b64 s[2:3], s[36:37]
	s_cbranch_execz .LBB0_749
	v_ashrrev_i32_e32 v97, 31, v96
	v_lshl_add_u64 v[2:3], s[52:53], 0, v[68:69]
	v_lshl_add_u64 v[4:5], v[96:97], 0, v[128:129]
	v_lshl_add_u64 v[2:3], v[4:5], 2, v[2:3]
	v_add_f32_e32 v0, v0, v1
	global_store_dword v[2:3], v0, off offset:256

.LBB0_750:
	v_or_b32_e32 v4, v34, v70
	v_ashrrev_i32_e32 v5, 31, v4
	v_lshlrev_b64 v[0:1], 12, v[4:5]
	v_lshl_add_u64 v[0:1], s[40:41], 0, v[0:1]
	v_lshl_add_u64 v[16:17], v[98:99], 2, v[0:1]
	s_movk_i32 s2, 0x1000
	v_cmp_gt_i32_e32 vcc, s2, v4
	s_nop 1
	v_cndmask_b32_e32 v7, v6, v102, vcc
	v_and_b32_e32 v7, 1, v7
	v_cmp_eq_u32_e32 vcc, 1, v7
	s_nop 1
	v_cndmask_b32_e64 v7, v171, 0, vcc
	v_add_u32_e32 v7, v103, v7
	ds_read_b128 v[8:11], v86 offset:1088
	ds_read_b128 v[12:15], v7
	s_and_b64 vcc, exec, s[0:1]
	s_waitcnt vmcnt(15) lgkmcnt(0)
	v_pk_fma_f32 v[2:3], v[10:11], v[14:15], v[204:205]
	v_pk_fma_f32 v[0:1], v[8:9], v[12:13], v[202:203]
	global_store_dwordx4 v[16:17], v[0:3], off nt
	s_cbranch_vccnz .LBB0_754
	ds_read_b128 v[8:11], v7 offset:2048
	v_lshlrev_b64 v[4:5], 10, v[4:5]
	v_lshl_add_u64 v[4:5], v[4:5], 1, s[42:43]
	v_lshl_add_u64 v[4:5], v[98:99], 1, v[4:5]
	s_waitcnt lgkmcnt(0)
	v_pk_mul_f32 v[8:9], v[0:1], v[8:9]
	v_pk_mul_f32 v[0:1], v[0:1], v[0:1]
	v_pk_mul_f32 v[10:11], v[2:3], v[10:11]
	v_pk_mul_f32 v[2:3], v[2:3], v[2:3]
	v_add_f32_e32 v0, v0, v1
	v_add_f32_e32 v0, v2, v0
	v_add_f32_e32 v0, v3, v0
	v_cvt_pk_bf16_f32 v8, v8, v9
	v_cvt_pk_bf16_f32 v9, v10, v11
	v_add_f32_dpp v0, v0, v0 quad_perm:[1,0,3,2] row_mask:0xf bank_mask:0xf bound_ctrl:1
	global_store_dwordx2 v[4:5], v[8:9], off
	s_nop 0
	v_add_f32_dpp v0, v0, v0 quad_perm:[2,3,0,1] row_mask:0xf bank_mask:0xf bound_ctrl:1
	s_nop 1
	v_add_f32_dpp v0, v0, v0 row_half_mirror row_mask:0xf bank_mask:0xf bound_ctrl:1
	s_nop 1
	v_mov_b32_dpp v1, v0 row_mirror row_mask:0xf bank_mask:0xf bound_ctrl:1
	s_and_saveexec_b64 s[2:3], s[36:37]
	s_cbranch_execz .LBB0_753
	v_mov_b32_e32 v71, v129
	v_ashrrev_i32_e32 v97, 31, v96
	v_lshl_add_u64 v[2:3], s[52:53], 0, v[68:69]
	v_lshl_add_u64 v[4:5], v[96:97], 0, v[70:71]
	v_lshl_add_u64 v[2:3], v[4:5], 2, v[2:3]
	v_add_f32_e32 v0, v0, v1
	global_store_dword v[2:3], v0, off offset:256

.LBB0_754:
	v_or_b32_e32 v4, v34, v72
	v_ashrrev_i32_e32 v5, 31, v4
	v_lshlrev_b64 v[0:1], 12, v[4:5]
	v_lshl_add_u64 v[0:1], s[40:41], 0, v[0:1]
	v_lshl_add_u64 v[16:17], v[98:99], 2, v[0:1]
	s_movk_i32 s2, 0x1000
	v_cmp_gt_i32_e32 vcc, s2, v4
	s_nop 1
	v_cndmask_b32_e32 v7, v6, v102, vcc
	v_and_b32_e32 v7, 1, v7
	v_cmp_eq_u32_e32 vcc, 1, v7
	s_nop 1
	v_cndmask_b32_e64 v7, v171, 0, vcc
	v_add_u32_e32 v7, v103, v7
	ds_read_b128 v[8:11], v86 offset:2176
	ds_read_b128 v[12:15], v7
	s_and_b64 vcc, exec, s[0:1]
	s_waitcnt vmcnt(15) lgkmcnt(0)
	v_pk_fma_f32 v[2:3], v[10:11], v[14:15], v[208:209]
	v_pk_fma_f32 v[0:1], v[8:9], v[12:13], v[206:207]
	global_store_dwordx4 v[16:17], v[0:3], off nt
	s_cbranch_vccnz .LBB0_758
	ds_read_b128 v[8:11], v7 offset:2048
	v_lshlrev_b64 v[4:5], 10, v[4:5]
	v_lshl_add_u64 v[4:5], v[4:5], 1, s[42:43]
	v_lshl_add_u64 v[4:5], v[98:99], 1, v[4:5]
	s_waitcnt lgkmcnt(0)
	v_pk_mul_f32 v[8:9], v[0:1], v[8:9]
	v_pk_mul_f32 v[0:1], v[0:1], v[0:1]
	v_pk_mul_f32 v[10:11], v[2:3], v[10:11]
	v_pk_mul_f32 v[2:3], v[2:3], v[2:3]
	v_add_f32_e32 v0, v0, v1
	v_add_f32_e32 v0, v2, v0
	v_add_f32_e32 v0, v3, v0
	v_cvt_pk_bf16_f32 v8, v8, v9
	v_cvt_pk_bf16_f32 v9, v10, v11
	v_add_f32_dpp v0, v0, v0 quad_perm:[1,0,3,2] row_mask:0xf bank_mask:0xf bound_ctrl:1
	global_store_dwordx2 v[4:5], v[8:9], off
	s_nop 0
	v_add_f32_dpp v0, v0, v0 quad_perm:[2,3,0,1] row_mask:0xf bank_mask:0xf bound_ctrl:1
	s_nop 1
	v_add_f32_dpp v0, v0, v0 row_half_mirror row_mask:0xf bank_mask:0xf bound_ctrl:1
	s_nop 1
	v_mov_b32_dpp v1, v0 row_mirror row_mask:0xf bank_mask:0xf bound_ctrl:1
	s_and_saveexec_b64 s[2:3], s[36:37]
	s_cbranch_execz .LBB0_757
	v_mov_b32_e32 v73, v129
	v_ashrrev_i32_e32 v97, 31, v96
	v_lshl_add_u64 v[2:3], s[52:53], 0, v[68:69]
	v_lshl_add_u64 v[4:5], v[96:97], 0, v[72:73]
	v_lshl_add_u64 v[2:3], v[4:5], 2, v[2:3]
	v_add_f32_e32 v0, v0, v1
	global_store_dword v[2:3], v0, off offset:256

.LBB0_758:
	v_or_b32_e32 v4, v34, v74
	v_ashrrev_i32_e32 v5, 31, v4
	v_lshlrev_b64 v[0:1], 12, v[4:5]
	v_lshl_add_u64 v[0:1], s[40:41], 0, v[0:1]
	v_lshl_add_u64 v[16:17], v[98:99], 2, v[0:1]
	s_movk_i32 s2, 0x1000
	v_cmp_gt_i32_e32 vcc, s2, v4
	s_nop 1
	v_cndmask_b32_e32 v7, v6, v102, vcc
	v_and_b32_e32 v7, 1, v7
	v_cmp_eq_u32_e32 vcc, 1, v7
	s_nop 1
	v_cndmask_b32_e64 v7, v171, 0, vcc
	v_add_u32_e32 v7, v103, v7
	ds_read_b128 v[8:11], v86 offset:3264
	ds_read_b128 v[12:15], v7
	s_and_b64 vcc, exec, s[0:1]
	s_waitcnt vmcnt(15) lgkmcnt(0)
	v_pk_fma_f32 v[2:3], v[10:11], v[14:15], v[212:213]
	v_pk_fma_f32 v[0:1], v[8:9], v[12:13], v[210:211]
	global_store_dwordx4 v[16:17], v[0:3], off nt
	s_cbranch_vccnz .LBB0_762
	ds_read_b128 v[8:11], v7 offset:2048
	v_lshlrev_b64 v[4:5], 10, v[4:5]
	v_lshl_add_u64 v[4:5], v[4:5], 1, s[42:43]
	v_lshl_add_u64 v[4:5], v[98:99], 1, v[4:5]
	s_waitcnt lgkmcnt(0)
	v_pk_mul_f32 v[8:9], v[0:1], v[8:9]
	v_pk_mul_f32 v[0:1], v[0:1], v[0:1]
	v_pk_mul_f32 v[10:11], v[2:3], v[10:11]
	v_pk_mul_f32 v[2:3], v[2:3], v[2:3]
	v_add_f32_e32 v0, v0, v1
	v_add_f32_e32 v0, v2, v0
	v_add_f32_e32 v0, v3, v0
	v_cvt_pk_bf16_f32 v8, v8, v9
	v_cvt_pk_bf16_f32 v9, v10, v11
	v_add_f32_dpp v0, v0, v0 quad_perm:[1,0,3,2] row_mask:0xf bank_mask:0xf bound_ctrl:1
	global_store_dwordx2 v[4:5], v[8:9], off
	s_nop 0
	v_add_f32_dpp v0, v0, v0 quad_perm:[2,3,0,1] row_mask:0xf bank_mask:0xf bound_ctrl:1
	s_nop 1
	v_add_f32_dpp v0, v0, v0 row_half_mirror row_mask:0xf bank_mask:0xf bound_ctrl:1
	s_nop 1
	v_mov_b32_dpp v1, v0 row_mirror row_mask:0xf bank_mask:0xf bound_ctrl:1
	s_and_saveexec_b64 s[2:3], s[36:37]
	s_cbranch_execz .LBB0_761
	v_mov_b32_e32 v75, v129
	v_ashrrev_i32_e32 v97, 31, v96
	v_lshl_add_u64 v[2:3], s[52:53], 0, v[68:69]
	v_lshl_add_u64 v[4:5], v[96:97], 0, v[74:75]
	v_lshl_add_u64 v[2:3], v[4:5], 2, v[2:3]
	v_add_f32_e32 v0, v0, v1
	global_store_dword v[2:3], v0, off offset:256

.LBB0_762:
	v_or_b32_e32 v4, v34, v76
	v_ashrrev_i32_e32 v5, 31, v4
	v_lshlrev_b64 v[0:1], 12, v[4:5]
	v_lshl_add_u64 v[0:1], s[40:41], 0, v[0:1]
	v_lshl_add_u64 v[16:17], v[98:99], 2, v[0:1]
	s_movk_i32 s2, 0x1000
	v_cmp_gt_i32_e32 vcc, s2, v4
	s_nop 1
	v_cndmask_b32_e32 v7, v6, v102, vcc
	v_and_b32_e32 v7, 1, v7
	v_cmp_eq_u32_e32 vcc, 1, v7
	s_nop 1
	v_cndmask_b32_e64 v7, v171, 0, vcc
	v_add_u32_e32 v7, v103, v7
	ds_read_b128 v[8:11], v86 offset:4352
	ds_read_b128 v[12:15], v7
	s_and_b64 vcc, exec, s[0:1]
	s_waitcnt vmcnt(15) lgkmcnt(0)
	v_pk_fma_f32 v[2:3], v[10:11], v[14:15], v[216:217]
	v_pk_fma_f32 v[0:1], v[8:9], v[12:13], v[214:215]
	global_store_dwordx4 v[16:17], v[0:3], off nt
	s_cbranch_vccnz .LBB0_766
	ds_read_b128 v[8:11], v7 offset:2048
	v_lshlrev_b64 v[4:5], 10, v[4:5]
	v_lshl_add_u64 v[4:5], v[4:5], 1, s[42:43]
	v_lshl_add_u64 v[4:5], v[98:99], 1, v[4:5]
	s_waitcnt lgkmcnt(0)
	v_pk_mul_f32 v[8:9], v[0:1], v[8:9]
	v_pk_mul_f32 v[0:1], v[0:1], v[0:1]
	v_pk_mul_f32 v[10:11], v[2:3], v[10:11]
	v_pk_mul_f32 v[2:3], v[2:3], v[2:3]
	v_add_f32_e32 v0, v0, v1
	v_add_f32_e32 v0, v2, v0
	v_add_f32_e32 v0, v3, v0
	v_cvt_pk_bf16_f32 v8, v8, v9
	v_cvt_pk_bf16_f32 v9, v10, v11
	v_add_f32_dpp v0, v0, v0 quad_perm:[1,0,3,2] row_mask:0xf bank_mask:0xf bound_ctrl:1
	global_store_dwordx2 v[4:5], v[8:9], off
	s_nop 0
	v_add_f32_dpp v0, v0, v0 quad_perm:[2,3,0,1] row_mask:0xf bank_mask:0xf bound_ctrl:1
	s_nop 1
	v_add_f32_dpp v0, v0, v0 row_half_mirror row_mask:0xf bank_mask:0xf bound_ctrl:1
	s_nop 1
	v_mov_b32_dpp v1, v0 row_mirror row_mask:0xf bank_mask:0xf bound_ctrl:1
	s_and_saveexec_b64 s[2:3], s[36:37]
	s_cbranch_execz .LBB0_765
	v_mov_b32_e32 v77, v129
	v_ashrrev_i32_e32 v97, 31, v96
	v_lshl_add_u64 v[2:3], s[52:53], 0, v[68:69]
	v_lshl_add_u64 v[4:5], v[96:97], 0, v[76:77]
	v_lshl_add_u64 v[2:3], v[4:5], 2, v[2:3]
	v_add_f32_e32 v0, v0, v1
	global_store_dword v[2:3], v0, off offset:256

.LBB0_766:
	v_or_b32_e32 v4, v34, v78
	v_ashrrev_i32_e32 v5, 31, v4
	v_lshlrev_b64 v[0:1], 12, v[4:5]
	v_lshl_add_u64 v[0:1], s[40:41], 0, v[0:1]
	v_lshl_add_u64 v[16:17], v[98:99], 2, v[0:1]
	s_movk_i32 s2, 0x1000
	v_cmp_gt_i32_e32 vcc, s2, v4
	s_nop 1
	v_cndmask_b32_e32 v7, v6, v102, vcc
	v_and_b32_e32 v7, 1, v7
	v_cmp_eq_u32_e32 vcc, 1, v7
	s_nop 1
	v_cndmask_b32_e64 v7, v171, 0, vcc
	v_add_u32_e32 v7, v103, v7
	ds_read_b128 v[8:11], v86 offset:5440
	ds_read_b128 v[12:15], v7
	s_and_b64 vcc, exec, s[0:1]
	s_waitcnt vmcnt(15) lgkmcnt(0)
	v_pk_fma_f32 v[2:3], v[10:11], v[14:15], v[220:221]
	v_pk_fma_f32 v[0:1], v[8:9], v[12:13], v[218:219]
	global_store_dwordx4 v[16:17], v[0:3], off nt
	s_cbranch_vccnz .LBB0_770
	ds_read_b128 v[8:11], v7 offset:2048
	v_lshlrev_b64 v[4:5], 10, v[4:5]
	v_lshl_add_u64 v[4:5], v[4:5], 1, s[42:43]
	v_lshl_add_u64 v[4:5], v[98:99], 1, v[4:5]
	s_waitcnt lgkmcnt(0)
	v_pk_mul_f32 v[8:9], v[0:1], v[8:9]
	v_pk_mul_f32 v[0:1], v[0:1], v[0:1]
	v_pk_mul_f32 v[10:11], v[2:3], v[10:11]
	v_pk_mul_f32 v[2:3], v[2:3], v[2:3]
	v_add_f32_e32 v0, v0, v1
	v_add_f32_e32 v0, v2, v0
	v_add_f32_e32 v0, v3, v0
	v_cvt_pk_bf16_f32 v8, v8, v9
	v_cvt_pk_bf16_f32 v9, v10, v11
	v_add_f32_dpp v0, v0, v0 quad_perm:[1,0,3,2] row_mask:0xf bank_mask:0xf bound_ctrl:1
	global_store_dwordx2 v[4:5], v[8:9], off
	s_nop 0
	v_add_f32_dpp v0, v0, v0 quad_perm:[2,3,0,1] row_mask:0xf bank_mask:0xf bound_ctrl:1
	s_nop 1
	v_add_f32_dpp v0, v0, v0 row_half_mirror row_mask:0xf bank_mask:0xf bound_ctrl:1
	s_nop 1
	v_mov_b32_dpp v1, v0 row_mirror row_mask:0xf bank_mask:0xf bound_ctrl:1
	s_and_saveexec_b64 s[2:3], s[36:37]
	s_cbranch_execz .LBB0_769
	v_mov_b32_e32 v79, v129
	v_ashrrev_i32_e32 v97, 31, v96
	v_lshl_add_u64 v[2:3], s[52:53], 0, v[68:69]
	v_lshl_add_u64 v[4:5], v[96:97], 0, v[78:79]
	v_lshl_add_u64 v[2:3], v[4:5], 2, v[2:3]
	v_add_f32_e32 v0, v0, v1
	global_store_dword v[2:3], v0, off offset:256

.LBB0_770:
	v_or_b32_e32 v4, v34, v80
	v_ashrrev_i32_e32 v5, 31, v4
	v_lshlrev_b64 v[0:1], 12, v[4:5]
	v_lshl_add_u64 v[0:1], s[40:41], 0, v[0:1]
	v_lshl_add_u64 v[16:17], v[98:99], 2, v[0:1]
	s_movk_i32 s2, 0x1000
	v_cmp_gt_i32_e32 vcc, s2, v4
	s_nop 1
	v_cndmask_b32_e32 v7, v6, v102, vcc
	v_and_b32_e32 v7, 1, v7
	v_cmp_eq_u32_e32 vcc, 1, v7
	s_nop 1
	v_cndmask_b32_e64 v7, v171, 0, vcc
	v_add_u32_e32 v7, v103, v7
	ds_read_b128 v[8:11], v86 offset:6528
	ds_read_b128 v[12:15], v7
	s_and_b64 vcc, exec, s[0:1]
	s_waitcnt vmcnt(15) lgkmcnt(0)
	v_pk_fma_f32 v[2:3], v[10:11], v[14:15], v[224:225]
	v_pk_fma_f32 v[0:1], v[8:9], v[12:13], v[222:223]
	global_store_dwordx4 v[16:17], v[0:3], off nt
	s_cbranch_vccnz .LBB0_774
	ds_read_b128 v[8:11], v7 offset:2048
	v_lshlrev_b64 v[4:5], 10, v[4:5]
	v_lshl_add_u64 v[4:5], v[4:5], 1, s[42:43]
	v_lshl_add_u64 v[4:5], v[98:99], 1, v[4:5]
	s_waitcnt lgkmcnt(0)
	v_pk_mul_f32 v[8:9], v[0:1], v[8:9]
	v_pk_mul_f32 v[0:1], v[0:1], v[0:1]
	v_pk_mul_f32 v[10:11], v[2:3], v[10:11]
	v_pk_mul_f32 v[2:3], v[2:3], v[2:3]
	v_add_f32_e32 v0, v0, v1
	v_add_f32_e32 v0, v2, v0
	v_add_f32_e32 v0, v3, v0
	v_cvt_pk_bf16_f32 v8, v8, v9
	v_cvt_pk_bf16_f32 v9, v10, v11
	v_add_f32_dpp v0, v0, v0 quad_perm:[1,0,3,2] row_mask:0xf bank_mask:0xf bound_ctrl:1
	global_store_dwordx2 v[4:5], v[8:9], off
	s_nop 0
	v_add_f32_dpp v0, v0, v0 quad_perm:[2,3,0,1] row_mask:0xf bank_mask:0xf bound_ctrl:1
	s_nop 1
	v_add_f32_dpp v0, v0, v0 row_half_mirror row_mask:0xf bank_mask:0xf bound_ctrl:1
	s_nop 1
	v_mov_b32_dpp v1, v0 row_mirror row_mask:0xf bank_mask:0xf bound_ctrl:1
	s_and_saveexec_b64 s[2:3], s[36:37]
	s_cbranch_execz .LBB0_773
	v_mov_b32_e32 v81, v129
	v_ashrrev_i32_e32 v97, 31, v96
	v_lshl_add_u64 v[2:3], s[52:53], 0, v[68:69]
	v_lshl_add_u64 v[4:5], v[96:97], 0, v[80:81]
	v_lshl_add_u64 v[2:3], v[4:5], 2, v[2:3]
	v_add_f32_e32 v0, v0, v1
	global_store_dword v[2:3], v0, off offset:256

.LBB0_774:
	v_or_b32_e32 v4, v34, v82
	v_ashrrev_i32_e32 v5, 31, v4
	v_lshlrev_b64 v[0:1], 12, v[4:5]
	v_lshl_add_u64 v[0:1], s[40:41], 0, v[0:1]
	v_lshl_add_u64 v[16:17], v[98:99], 2, v[0:1]
	s_movk_i32 s2, 0x1000
	v_cmp_gt_i32_e32 vcc, s2, v4
	s_nop 1
	v_cndmask_b32_e32 v6, v6, v102, vcc
	v_and_b32_e32 v6, 1, v6
	v_cmp_eq_u32_e32 vcc, 1, v6
	s_nop 1
	v_cndmask_b32_e64 v6, v171, 0, vcc
	v_add_u32_e32 v6, v103, v6
	ds_read_b128 v[8:11], v86 offset:7616
	ds_read_b128 v[12:15], v6
	s_and_b64 vcc, exec, s[0:1]
	s_waitcnt vmcnt(15) lgkmcnt(0)
	v_pk_fma_f32 v[2:3], v[10:11], v[14:15], v[228:229]
	v_pk_fma_f32 v[0:1], v[8:9], v[12:13], v[226:227]
	global_store_dwordx4 v[16:17], v[0:3], off nt
	s_cbranch_vccnz .LBB0_677
	ds_read_b128 v[6:9], v6 offset:2048
	v_lshlrev_b64 v[4:5], 10, v[4:5]
	v_lshl_add_u64 v[4:5], v[4:5], 1, s[42:43]
	v_lshl_add_u64 v[4:5], v[98:99], 1, v[4:5]
	s_waitcnt lgkmcnt(0)
	v_pk_mul_f32 v[6:7], v[0:1], v[6:7]
	v_pk_mul_f32 v[0:1], v[0:1], v[0:1]
	v_pk_mul_f32 v[8:9], v[2:3], v[8:9]
	v_pk_mul_f32 v[2:3], v[2:3], v[2:3]
	v_add_f32_e32 v0, v0, v1
	v_add_f32_e32 v0, v2, v0
	v_add_f32_e32 v0, v3, v0
	v_cvt_pk_bf16_f32 v6, v6, v7
	v_cvt_pk_bf16_f32 v7, v8, v9
	v_add_f32_dpp v0, v0, v0 quad_perm:[1,0,3,2] row_mask:0xf bank_mask:0xf bound_ctrl:1
	global_store_dwordx2 v[4:5], v[6:7], off
	s_nop 0
	v_add_f32_dpp v0, v0, v0 quad_perm:[2,3,0,1] row_mask:0xf bank_mask:0xf bound_ctrl:1
	s_nop 1
	v_add_f32_dpp v0, v0, v0 row_half_mirror row_mask:0xf bank_mask:0xf bound_ctrl:1
	s_nop 1
	v_mov_b32_dpp v1, v0 row_mirror row_mask:0xf bank_mask:0xf bound_ctrl:1
	s_and_saveexec_b64 s[0:1], s[36:37]
	s_cbranch_execz .LBB0_676
	v_mov_b32_e32 v83, v129
	v_ashrrev_i32_e32 v97, 31, v96
	v_lshl_add_u64 v[2:3], s[52:53], 0, v[68:69]
	v_lshl_add_u64 v[4:5], v[96:97], 0, v[82:83]
	v_lshl_add_u64 v[2:3], v[4:5], 2, v[2:3]
	v_add_f32_e32 v0, v0, v1
	global_store_dword v[2:3], v0, off offset:256
	s_branch .LBB0_676

.LBB0_1223:
	s_add_i32 s9, s7, 1
	s_bitcmp1_b32 s9, 0
	s_cselect_b32 s10, 0xe000, 0
	v_add_u32_e32 v246, s10, v109
	s_bitcmp1_b32 s7, 0
	s_cselect_b32 s10, 0xe000, 0
	v_add_u32_e32 v153, s10, v114
	v_add_u32_e32 v154, s10, v113
	s_waitcnt vmcnt(0) lgkmcnt(0)
	s_barrier
	v_add_u32_e32 v181, v153, v111
	ds_read_b128 v[116:119], v181 offset:0x0
	ds_read_b128 v[120:123], v181 offset:0x1000
	v_add_u32_e32 v181, v154, v111
	ds_read_b128 v[124:127], v181 offset:0x0
	ds_read_b128 v[130:133], v181 offset:0x1000
	ds_read_b128 v[134:137], v181 offset:0x2000
	v_mfma_f32_32x32x16_bf16 v[64:79], v[144:147], v[182:185], v[64:79]
	v_mfma_f32_32x32x16_bf16 v[32:47], v[144:147], v[186:189], v[32:47]
	v_lshl_add_u64 v[244:245], v[98:99], 0, s[2:3]
	v_lshl_add_u64 v[244:245], v[244:245], 0, s[12:13]
	v_readfirstlane_b32 s10, v246
	s_mov_b32 m0, s10
	s_nop 0
	global_load_lds_dwordx4 v[244:245], off
	v_mfma_f32_32x32x16_bf16 v[0:15], v[144:147], v[190:193], v[0:15]
	v_mfma_f32_32x32x16_bf16 v[80:95], v[148:151], v[182:185], v[80:95]
	v_add_u32_e32 v243, 0x2000, v246
	v_lshl_add_u64 v[244:245], v[98:99], 0, s[2:3]
	v_lshl_add_u64 v[244:245], v[244:245], 0, s[16:17]
	v_readfirstlane_b32 s10, v243
	s_mov_b32 m0, s10
	s_nop 0
	global_load_lds_dwordx4 v[244:245], off
	v_mfma_f32_32x32x16_bf16 v[48:63], v[148:151], v[186:189], v[48:63]
	v_mfma_f32_32x32x16_bf16 v[16:31], v[148:151], v[190:193], v[16:31]
	v_add_u32_e32 v243, 0x4000, v246
	v_lshl_add_u64 v[244:245], v[98:99], 0, s[2:3]
	v_lshl_add_u64 v[244:245], v[244:245], 0, s[18:19]
	v_readfirstlane_b32 s10, v243
	s_mov_b32 m0, s10
	s_nop 0
	global_load_lds_dwordx4 v[244:245], off
	v_add_u32_e32 v181, v153, v110
	ds_read_b128 v[144:147], v181 offset:0x0
	ds_read_b128 v[148:151], v181 offset:0x1000
	v_add_u32_e32 v181, v154, v110
	ds_read_b128 v[182:185], v181 offset:0x0
	ds_read_b128 v[186:189], v181 offset:0x1000
	ds_read_b128 v[190:193], v181 offset:0x2000
	s_waitcnt lgkmcnt(5)
	v_mfma_f32_32x32x16_bf16 v[64:79], v[116:119], v[124:127], v[64:79]
	v_mfma_f32_32x32x16_bf16 v[32:47], v[116:119], v[130:133], v[32:47]
	v_add_u32_e32 v243, 0x6000, v246
	s_mov_b64 s[10:11], 0x5f14080
	v_lshl_add_u64 v[244:245], v[96:97], 0, s[2:3]
	v_lshl_add_u64 v[244:245], v[244:245], 0, s[10:11]
	v_readfirstlane_b32 s10, v243
	s_mov_b32 m0, s10
	s_nop 0
	global_load_lds_dwordx4 v[244:245], off
	v_mfma_f32_32x32x16_bf16 v[0:15], v[116:119], v[134:137], v[0:15]
	v_mfma_f32_32x32x16_bf16 v[80:95], v[120:123], v[124:127], v[80:95]
	v_add_u32_e32 v243, 0x8000, v246
	s_mov_b64 s[10:11], 0x5f34080
	v_lshl_add_u64 v[244:245], v[96:97], 0, s[2:3]
	v_lshl_add_u64 v[244:245], v[244:245], 0, s[10:11]
	v_readfirstlane_b32 s10, v243
	s_mov_b32 m0, s10
	s_nop 0
	global_load_lds_dwordx4 v[244:245], off
	v_mfma_f32_32x32x16_bf16 v[48:63], v[120:123], v[130:133], v[48:63]
	v_mfma_f32_32x32x16_bf16 v[16:31], v[120:123], v[134:137], v[16:31]
	v_add_u32_e32 v243, 0xa000, v246
	s_mov_b64 s[10:11], 0x5f54080
	v_lshl_add_u64 v[244:245], v[96:97], 0, s[2:3]
	v_lshl_add_u64 v[244:245], v[244:245], 0, s[10:11]
	v_readfirstlane_b32 s10, v243
	s_mov_b32 m0, s10
	s_nop 0
	global_load_lds_dwordx4 v[244:245], off
	v_add_u32_e32 v181, v153, v108
	ds_read_b128 v[116:119], v181 offset:0x0
	ds_read_b128 v[120:123], v181 offset:0x1000
	v_add_u32_e32 v181, v154, v108
	ds_read_b128 v[124:127], v181 offset:0x0
	ds_read_b128 v[130:133], v181 offset:0x1000
	ds_read_b128 v[134:137], v181 offset:0x2000
	s_waitcnt lgkmcnt(5)
	v_mfma_f32_32x32x16_bf16 v[64:79], v[144:147], v[182:185], v[64:79]
	v_mfma_f32_32x32x16_bf16 v[32:47], v[144:147], v[186:189], v[32:47]
	v_add_u32_e32 v243, 0xc000, v246
	s_mov_b64 s[10:11], 0x5f74080
	v_lshl_add_u64 v[244:245], v[96:97], 0, s[2:3]
	v_lshl_add_u64 v[244:245], v[244:245], 0, s[10:11]
	v_readfirstlane_b32 s10, v243
	s_mov_b32 m0, s10
	s_nop 0
	global_load_lds_dwordx4 v[244:245], off
	v_mfma_f32_32x32x16_bf16 v[0:15], v[144:147], v[190:193], v[0:15]
	v_mfma_f32_32x32x16_bf16 v[80:95], v[148:151], v[182:185], v[80:95]
	v_mfma_f32_32x32x16_bf16 v[48:63], v[148:151], v[186:189], v[48:63]
	v_mfma_f32_32x32x16_bf16 v[16:31], v[148:151], v[190:193], v[16:31]
	v_add_u32_e32 v181, v153, v107
	ds_read_b128 v[144:147], v181 offset:0x0
	ds_read_b128 v[148:151], v181 offset:0x1000
	v_add_u32_e32 v181, v154, v107
	ds_read_b128 v[182:185], v181 offset:0x0
	ds_read_b128 v[186:189], v181 offset:0x1000
	ds_read_b128 v[190:193], v181 offset:0x2000
	s_waitcnt lgkmcnt(5)
	v_mfma_f32_32x32x16_bf16 v[64:79], v[116:119], v[124:127], v[64:79]
	v_mfma_f32_32x32x16_bf16 v[32:47], v[116:119], v[130:133], v[32:47]
	v_mfma_f32_32x32x16_bf16 v[0:15], v[116:119], v[134:137], v[0:15]
	v_mfma_f32_32x32x16_bf16 v[80:95], v[120:123], v[124:127], v[80:95]
	v_mfma_f32_32x32x16_bf16 v[48:63], v[120:123], v[130:133], v[48:63]
	v_mfma_f32_32x32x16_bf16 v[16:31], v[120:123], v[134:137], v[16:31]
	s_waitcnt lgkmcnt(0)
	s_add_u32 s2, s2, 0x80
	s_addc_u32 s3, s3, 0
	s_mov_b32 s7, s9
	s_cmpk_lg_i32 s2, 0x780
	s_cbranch_scc1 .LBB0_1223
	s_bitcmp1_b32 s7, 0
	s_cselect_b32 s10, 0xe000, 0
	v_add_u32_e32 v153, s10, v114
	v_add_u32_e32 v154, s10, v113
	s_waitcnt vmcnt(0) lgkmcnt(0)
	s_barrier
	v_add_u32_e32 v181, v153, v111
	ds_read_b128 v[116:119], v181 offset:0x0
	ds_read_b128 v[120:123], v181 offset:0x1000
	v_add_u32_e32 v181, v154, v111
	ds_read_b128 v[124:127], v181 offset:0x0
	ds_read_b128 v[130:133], v181 offset:0x1000
	ds_read_b128 v[134:137], v181 offset:0x2000
	v_mfma_f32_32x32x16_bf16 v[64:79], v[144:147], v[182:185], v[64:79]
	v_mfma_f32_32x32x16_bf16 v[32:47], v[144:147], v[186:189], v[32:47]
	v_mfma_f32_32x32x16_bf16 v[0:15], v[144:147], v[190:193], v[0:15]
	v_mfma_f32_32x32x16_bf16 v[80:95], v[148:151], v[182:185], v[80:95]
	v_mfma_f32_32x32x16_bf16 v[48:63], v[148:151], v[186:189], v[48:63]
	v_mfma_f32_32x32x16_bf16 v[16:31], v[148:151], v[190:193], v[16:31]
	v_add_u32_e32 v181, v153, v110
	ds_read_b128 v[144:147], v181 offset:0x0
	ds_read_b128 v[148:151], v181 offset:0x1000
	v_add_u32_e32 v181, v154, v110
	ds_read_b128 v[182:185], v181 offset:0x0
	ds_read_b128 v[186:189], v181 offset:0x1000
	ds_read_b128 v[190:193], v181 offset:0x2000
	s_waitcnt lgkmcnt(5)
	v_mfma_f32_32x32x16_bf16 v[64:79], v[116:119], v[124:127], v[64:79]
	v_mfma_f32_32x32x16_bf16 v[32:47], v[116:119], v[130:133], v[32:47]
	v_mfma_f32_32x32x16_bf16 v[0:15], v[116:119], v[134:137], v[0:15]
	v_mfma_f32_32x32x16_bf16 v[80:95], v[120:123], v[124:127], v[80:95]
	v_mfma_f32_32x32x16_bf16 v[48:63], v[120:123], v[130:133], v[48:63]
	v_mfma_f32_32x32x16_bf16 v[16:31], v[120:123], v[134:137], v[16:31]
	v_add_u32_e32 v181, v153, v108
	ds_read_b128 v[116:119], v181 offset:0x0
	ds_read_b128 v[120:123], v181 offset:0x1000
	v_add_u32_e32 v181, v154, v108
	ds_read_b128 v[124:127], v181 offset:0x0
	ds_read_b128 v[130:133], v181 offset:0x1000
	ds_read_b128 v[134:137], v181 offset:0x2000
	s_waitcnt lgkmcnt(5)
	v_mfma_f32_32x32x16_bf16 v[64:79], v[144:147], v[182:185], v[64:79]
	v_mfma_f32_32x32x16_bf16 v[32:47], v[144:147], v[186:189], v[32:47]
	v_mfma_f32_32x32x16_bf16 v[0:15], v[144:147], v[190:193], v[0:15]
	v_mfma_f32_32x32x16_bf16 v[80:95], v[148:151], v[182:185], v[80:95]
	v_mfma_f32_32x32x16_bf16 v[48:63], v[148:151], v[186:189], v[48:63]
	v_mfma_f32_32x32x16_bf16 v[16:31], v[148:151], v[190:193], v[16:31]
	v_add_u32_e32 v181, v153, v107
	ds_read_b128 v[144:147], v181 offset:0x0
	ds_read_b128 v[148:151], v181 offset:0x1000
	v_add_u32_e32 v181, v154, v107
	ds_read_b128 v[182:185], v181 offset:0x0
	ds_read_b128 v[186:189], v181 offset:0x1000
	ds_read_b128 v[190:193], v181 offset:0x2000
	s_waitcnt lgkmcnt(5)
	v_mfma_f32_32x32x16_bf16 v[64:79], v[116:119], v[124:127], v[64:79]
	v_mfma_f32_32x32x16_bf16 v[32:47], v[116:119], v[130:133], v[32:47]
	v_mfma_f32_32x32x16_bf16 v[0:15], v[116:119], v[134:137], v[0:15]
	v_mfma_f32_32x32x16_bf16 v[80:95], v[120:123], v[124:127], v[80:95]
	v_mfma_f32_32x32x16_bf16 v[48:63], v[120:123], v[130:133], v[48:63]
	v_mfma_f32_32x32x16_bf16 v[16:31], v[120:123], v[134:137], v[16:31]
	s_waitcnt lgkmcnt(0)
	v_mfma_f32_32x32x16_bf16 v[64:79], v[144:147], v[182:185], v[64:79]
	v_mfma_f32_32x32x16_bf16 v[32:47], v[144:147], v[186:189], v[32:47]
	v_mfma_f32_32x32x16_bf16 v[0:15], v[144:147], v[190:193], v[0:15]
	v_mfma_f32_32x32x16_bf16 v[80:95], v[148:151], v[182:185], v[80:95]
	v_mfma_f32_32x32x16_bf16 v[48:63], v[148:151], v[186:189], v[48:63]
	v_mfma_f32_32x32x16_bf16 v[16:31], v[148:151], v[190:193], v[16:31]
	v_add_u32_e32 v96, s4, v106
	v_lshrrev_b32_e32 v128, 4, v101
	v_and_b32_e32 v112, 15, v100
	v_or_b32_e32 v100, v96, v128
	v_add_u32_e32 v105, s8, v105
	v_ashrrev_i32_e32 v101, 31, v100
	v_lshl_or_b32 v98, v112, 2, v105
	v_lshlrev_b64 v[106:107], 12, v[100:101]
	v_ashrrev_i32_e32 v99, 31, v98
	v_lshl_add_u64 v[106:107], s[42:43], 0, v[106:107]
	v_lshl_add_u64 v[110:111], v[98:99], 2, v[106:107]
	s_barrier
	v_add_co_u32_e32 v182, vcc, 0x20000, v110
	s_nop 1
	v_addc_co_u32_e32 v183, vcc, 0, v111, vcc
	global_load_dwordx4 v[184:187], v[182:183], off
	v_add_co_u32_e32 v182, vcc, 0x4000, v182
	s_nop 1
	v_addc_co_u32_e32 v183, vcc, 0, v183, vcc
	global_load_dwordx4 v[188:191], v[182:183], off
	v_add_co_u32_e32 v182, vcc, 0x4000, v182
	s_nop 1
	v_addc_co_u32_e32 v183, vcc, 0, v183, vcc
	global_load_dwordx4 v[192:195], v[182:183], off
	v_add_co_u32_e32 v182, vcc, 0x4000, v182
	s_nop 1
	v_addc_co_u32_e32 v183, vcc, 0, v183, vcc
	global_load_dwordx4 v[116:119], v[182:183], off
	v_add_co_u32_e32 v182, vcc, 0x4000, v182
	s_nop 1
	v_addc_co_u32_e32 v183, vcc, 0, v183, vcc
	global_load_dwordx4 v[120:123], v[182:183], off
	v_add_co_u32_e32 v182, vcc, 0x4000, v182
	s_nop 1
	v_addc_co_u32_e32 v183, vcc, 0, v183, vcc
	global_load_dwordx4 v[124:127], v[182:183], off
	v_add_co_u32_e32 v182, vcc, 0x4000, v182
	s_nop 1
	v_addc_co_u32_e32 v183, vcc, 0, v183, vcc
	global_load_dwordx4 v[130:133], v[182:183], off
	v_add_co_u32_e32 v182, vcc, 0x4000, v182
	s_nop 1
	v_addc_co_u32_e32 v183, vcc, 0, v183, vcc
	global_load_dwordx4 v[134:137], v[182:183], off
	s_movk_i32 s2, 0x2400
	s_cmp_lt_i32 s5, 22
	v_mul_lo_u32 v97, v103, s2
	s_cselect_b64 s[2:3], -1, 0
	s_cmp_gt_i32 s5, 21
	s_movk_i32 s5, 0x110
	v_and_b32_e32 v103, 16, v104
	v_mad_u32_u24 v104, v102, s5, v97
	v_add_u32_e32 v113, 0xfffff000, v96
	v_cndmask_b32_e64 v102, 0, 1, s[2:3]
	s_cselect_b64 s[2:3], -1, 0
	s_add_i32 s7, s4, 0xfffff000
	v_add_u32_e32 v104, v104, v103
	ds_write_b128 v104, v[64:67]
	ds_write_b128 v104, v[68:71] offset:32
	ds_write_b128 v104, v[72:75] offset:64
	ds_write_b128 v104, v[76:79] offset:96
	ds_write_b128 v104, v[80:83] offset:128
	ds_write_b128 v104, v[84:87] offset:160
	ds_write_b128 v104, v[88:91] offset:192
	ds_write_b128 v104, v[92:95] offset:224
	v_xor_b32_e32 v64, s7, v113
	s_movk_i32 s4, 0x400
	v_lshl_or_b32 v97, v112, 4, v97
	v_cmp_gt_u32_e32 vcc, s4, v64
	v_mad_u32_u24 v115, v128, s5, v97
	s_and_b64 s[4:5], s[2:3], vcc
	v_cndmask_b32_e64 v71, 0, 1, s[4:5]
	s_movk_i32 s4, 0x1000
	v_cmp_gt_i32_e32 vcc, s4, v100
	v_subrev_u32_e32 v114, s8, v98
	v_lshl_add_u32 v103, v114, 2, v167
	v_cndmask_b32_e32 v64, v71, v102, vcc
	v_and_b32_e32 v64, 1, v64
	v_cmp_eq_u32_e32 vcc, 1, v64
	v_ashrrev_i32_e32 v68, 6, v105
	s_mov_b32 s4, 0xc000
	v_cndmask_b32_e64 v64, v171, 0, vcc
	v_add_u32_e32 v70, v103, v64
	ds_read_b128 v[64:67], v115
	ds_read_b128 v[72:75], v70
	v_cmp_eq_u32_e64 s[40:41], 0, v112
	v_mad_i64_i32 v[68:69], s[4:5], v68, s4, 0
	s_and_b64 vcc, exec, s[0:1]
	s_waitcnt lgkmcnt(0)
	v_pk_fma_f32 v[66:67], v[66:67], v[74:75], v[200:201]
	v_pk_fma_f32 v[64:65], v[64:65], v[72:73], v[198:199]
	global_store_dwordx4 v[110:111], v[64:67], off nt
	s_cbranch_vccnz .LBB0_1228
	ds_read_b128 v[72:75], v70 offset:2048
	v_lshlrev_b64 v[76:77], 10, v[100:101]
	v_lshl_add_u64 v[76:77], v[76:77], 1, s[44:45]
	v_lshl_add_u64 v[76:77], v[98:99], 1, v[76:77]
	s_waitcnt lgkmcnt(0)
	v_pk_mul_f32 v[72:73], v[64:65], v[72:73]
	v_pk_mul_f32 v[64:65], v[64:65], v[64:65]
	v_pk_mul_f32 v[74:75], v[66:67], v[74:75]
	v_pk_mul_f32 v[66:67], v[66:67], v[66:67]
	v_add_f32_e32 v64, v64, v65
	v_add_f32_e32 v64, v66, v64
	v_add_f32_e32 v64, v67, v64
	v_cvt_pk_bf16_f32 v72, v72, v73
	v_cvt_pk_bf16_f32 v73, v74, v75
	v_add_f32_dpp v64, v64, v64 quad_perm:[1,0,3,2] row_mask:0xf bank_mask:0xf bound_ctrl:1
	global_store_dwordx2 v[76:77], v[72:73], off
	s_nop 0
	v_add_f32_dpp v64, v64, v64 quad_perm:[2,3,0,1] row_mask:0xf bank_mask:0xf bound_ctrl:1
	s_nop 1
	v_add_f32_dpp v64, v64, v64 row_half_mirror row_mask:0xf bank_mask:0xf bound_ctrl:1
	s_nop 1
	v_mov_b32_dpp v65, v64 row_mirror row_mask:0xf bank_mask:0xf bound_ctrl:1
	s_and_saveexec_b64 s[4:5], s[40:41]
	s_cbranch_execz .LBB0_1227
	v_lshl_add_u64 v[66:67], s[48:49], 0, v[68:69]
	v_lshl_add_u64 v[66:67], v[100:101], 2, v[66:67]
	v_add_f32_e32 v64, v64, v65
	global_store_dword v[66:67], v64, off

.LBB0_1228:
	v_or_b32_e32 v70, 4, v128
	v_or_b32_e32 v72, v96, v70
	v_ashrrev_i32_e32 v73, 31, v72
	v_lshlrev_b64 v[64:65], 12, v[72:73]
	v_lshl_add_u64 v[64:65], s[42:43], 0, v[64:65]
	v_lshl_add_u64 v[84:85], v[98:99], 2, v[64:65]
	s_movk_i32 s4, 0x1000
	v_mul_u32_u24_e32 v74, 0x110, v128
	v_cmp_gt_i32_e32 vcc, s4, v72
	v_add_u32_e32 v86, v74, v97
	s_nop 0
	v_cndmask_b32_e32 v74, v71, v102, vcc
	v_and_b32_e32 v74, 1, v74
	v_cmp_eq_u32_e32 vcc, 1, v74
	s_nop 1
	v_cndmask_b32_e64 v74, v171, 0, vcc
	v_add_u32_e32 v74, v103, v74
	ds_read_b128 v[76:79], v86 offset:1088
	ds_read_b128 v[80:83], v74
	s_and_b64 vcc, exec, s[0:1]
	s_waitcnt lgkmcnt(0)
	v_pk_fma_f32 v[66:67], v[78:79], v[82:83], v[204:205]
	v_pk_fma_f32 v[64:65], v[76:77], v[80:81], v[202:203]
	global_store_dwordx4 v[84:85], v[64:67], off nt
	s_cbranch_vccnz .LBB0_1232
	ds_read_b128 v[74:77], v74 offset:2048
	v_lshlrev_b64 v[72:73], 10, v[72:73]
	v_lshl_add_u64 v[72:73], v[72:73], 1, s[44:45]
	v_lshl_add_u64 v[72:73], v[98:99], 1, v[72:73]
	s_waitcnt lgkmcnt(0)
	v_pk_mul_f32 v[74:75], v[64:65], v[74:75]
	v_pk_mul_f32 v[64:65], v[64:65], v[64:65]
	v_pk_mul_f32 v[76:77], v[66:67], v[76:77]
	v_pk_mul_f32 v[66:67], v[66:67], v[66:67]
	v_add_f32_e32 v64, v64, v65
	v_add_f32_e32 v64, v66, v64
	v_add_f32_e32 v64, v67, v64
	v_cvt_pk_bf16_f32 v74, v74, v75
	v_cvt_pk_bf16_f32 v75, v76, v77
	v_add_f32_dpp v64, v64, v64 quad_perm:[1,0,3,2] row_mask:0xf bank_mask:0xf bound_ctrl:1
	global_store_dwordx2 v[72:73], v[74:75], off
	s_nop 0
	v_add_f32_dpp v64, v64, v64 quad_perm:[2,3,0,1] row_mask:0xf bank_mask:0xf bound_ctrl:1
	s_nop 1
	v_add_f32_dpp v64, v64, v64 row_half_mirror row_mask:0xf bank_mask:0xf bound_ctrl:1
	s_nop 1
	v_mov_b32_dpp v65, v64 row_mirror row_mask:0xf bank_mask:0xf bound_ctrl:1
	s_and_saveexec_b64 s[4:5], s[40:41]
	s_cbranch_execz .LBB0_1231
	v_ashrrev_i32_e32 v97, 31, v96
	v_lshl_add_u64 v[66:67], s[48:49], 0, v[68:69]
	v_lshl_add_u64 v[72:73], v[96:97], 0, v[128:129]
	v_lshl_add_u64 v[66:67], v[72:73], 2, v[66:67]
	v_add_f32_e32 v64, v64, v65
	global_store_dword v[66:67], v64, off offset:16

.LBB0_1232:
	v_or_b32_e32 v72, 8, v128
	v_or_b32_e32 v74, v96, v72
	v_ashrrev_i32_e32 v75, 31, v74
	v_lshlrev_b64 v[64:65], 12, v[74:75]
	v_lshl_add_u64 v[64:65], s[42:43], 0, v[64:65]
	v_lshl_add_u64 v[84:85], v[98:99], 2, v[64:65]
	s_movk_i32 s4, 0x1000
	v_cmp_gt_i32_e32 vcc, s4, v74
	s_nop 1
	v_cndmask_b32_e32 v73, v71, v102, vcc
	v_and_b32_e32 v73, 1, v73
	v_cmp_eq_u32_e32 vcc, 1, v73
	s_nop 1
	v_cndmask_b32_e64 v73, v171, 0, vcc
	v_add_u32_e32 v73, v103, v73
	ds_read_b128 v[76:79], v86 offset:2176
	ds_read_b128 v[80:83], v73
	s_and_b64 vcc, exec, s[0:1]
	s_waitcnt lgkmcnt(0)
	v_pk_fma_f32 v[66:67], v[78:79], v[82:83], v[208:209]
	v_pk_fma_f32 v[64:65], v[76:77], v[80:81], v[206:207]
	global_store_dwordx4 v[84:85], v[64:67], off nt
	s_cbranch_vccnz .LBB0_1236
	ds_read_b128 v[76:79], v73 offset:2048
	v_lshlrev_b64 v[74:75], 10, v[74:75]
	v_lshl_add_u64 v[74:75], v[74:75], 1, s[44:45]
	v_lshl_add_u64 v[74:75], v[98:99], 1, v[74:75]
	s_waitcnt lgkmcnt(0)
	v_pk_mul_f32 v[76:77], v[64:65], v[76:77]
	v_pk_mul_f32 v[64:65], v[64:65], v[64:65]
	v_pk_mul_f32 v[78:79], v[66:67], v[78:79]
	v_pk_mul_f32 v[66:67], v[66:67], v[66:67]
	v_add_f32_e32 v64, v64, v65
	v_add_f32_e32 v64, v66, v64
	v_add_f32_e32 v64, v67, v64
	v_cvt_pk_bf16_f32 v76, v76, v77
	v_cvt_pk_bf16_f32 v77, v78, v79
	v_add_f32_dpp v64, v64, v64 quad_perm:[1,0,3,2] row_mask:0xf bank_mask:0xf bound_ctrl:1
	global_store_dwordx2 v[74:75], v[76:77], off
	s_nop 0
	v_add_f32_dpp v64, v64, v64 quad_perm:[2,3,0,1] row_mask:0xf bank_mask:0xf bound_ctrl:1
	s_nop 1
	v_add_f32_dpp v64, v64, v64 row_half_mirror row_mask:0xf bank_mask:0xf bound_ctrl:1
	s_nop 1
	v_mov_b32_dpp v65, v64 row_mirror row_mask:0xf bank_mask:0xf bound_ctrl:1
	s_and_saveexec_b64 s[4:5], s[40:41]
	s_cbranch_execz .LBB0_1235
	v_ashrrev_i32_e32 v97, 31, v96
	v_lshl_add_u64 v[66:67], s[48:49], 0, v[68:69]
	v_lshl_add_u64 v[74:75], v[96:97], 0, v[128:129]
	v_lshl_add_u64 v[66:67], v[74:75], 2, v[66:67]
	v_add_f32_e32 v64, v64, v65
	global_store_dword v[66:67], v64, off offset:32

.LBB0_1236:
	v_or_b32_e32 v74, 12, v128
	v_or_b32_e32 v76, v96, v74
	v_ashrrev_i32_e32 v77, 31, v76
	v_lshlrev_b64 v[64:65], 12, v[76:77]
	v_lshl_add_u64 v[64:65], s[42:43], 0, v[64:65]
	v_lshl_add_u64 v[88:89], v[98:99], 2, v[64:65]
	s_movk_i32 s4, 0x1000
	v_cmp_gt_i32_e32 vcc, s4, v76
	s_nop 1
	v_cndmask_b32_e32 v73, v71, v102, vcc
	v_and_b32_e32 v73, 1, v73
	v_cmp_eq_u32_e32 vcc, 1, v73
	s_nop 1
	v_cndmask_b32_e64 v73, v171, 0, vcc
	v_add_u32_e32 v73, v103, v73
	ds_read_b128 v[78:81], v86 offset:3264
	ds_read_b128 v[82:85], v73
	s_and_b64 vcc, exec, s[0:1]
	s_waitcnt lgkmcnt(0)
	v_pk_fma_f32 v[66:67], v[80:81], v[84:85], v[212:213]
	v_pk_fma_f32 v[64:65], v[78:79], v[82:83], v[210:211]
	global_store_dwordx4 v[88:89], v[64:67], off nt
	s_cbranch_vccnz .LBB0_1240
	ds_read_b128 v[78:81], v73 offset:2048
	v_lshlrev_b64 v[76:77], 10, v[76:77]
	v_lshl_add_u64 v[76:77], v[76:77], 1, s[44:45]
	v_lshl_add_u64 v[76:77], v[98:99], 1, v[76:77]
	s_waitcnt lgkmcnt(0)
	v_pk_mul_f32 v[78:79], v[64:65], v[78:79]
	v_pk_mul_f32 v[64:65], v[64:65], v[64:65]
	v_pk_mul_f32 v[80:81], v[66:67], v[80:81]
	v_pk_mul_f32 v[66:67], v[66:67], v[66:67]
	v_add_f32_e32 v64, v64, v65
	v_add_f32_e32 v64, v66, v64
	v_add_f32_e32 v64, v67, v64
	v_cvt_pk_bf16_f32 v78, v78, v79
	v_cvt_pk_bf16_f32 v79, v80, v81
	v_add_f32_dpp v64, v64, v64 quad_perm:[1,0,3,2] row_mask:0xf bank_mask:0xf bound_ctrl:1
	global_store_dwordx2 v[76:77], v[78:79], off
	s_nop 0
	v_add_f32_dpp v64, v64, v64 quad_perm:[2,3,0,1] row_mask:0xf bank_mask:0xf bound_ctrl:1
	s_nop 1
	v_add_f32_dpp v64, v64, v64 row_half_mirror row_mask:0xf bank_mask:0xf bound_ctrl:1
	s_nop 1
	v_mov_b32_dpp v65, v64 row_mirror row_mask:0xf bank_mask:0xf bound_ctrl:1
	s_and_saveexec_b64 s[4:5], s[40:41]
	s_cbranch_execz .LBB0_1239
	v_ashrrev_i32_e32 v97, 31, v96
	v_lshl_add_u64 v[66:67], s[48:49], 0, v[68:69]
	v_lshl_add_u64 v[76:77], v[96:97], 0, v[128:129]
	v_lshl_add_u64 v[66:67], v[76:77], 2, v[66:67]
	v_add_f32_e32 v64, v64, v65
	global_store_dword v[66:67], v64, off offset:48

.LBB0_1240:
	v_or_b32_e32 v76, 16, v128
	v_or_b32_e32 v78, v96, v76
	v_ashrrev_i32_e32 v79, 31, v78
	v_lshlrev_b64 v[64:65], 12, v[78:79]
	v_lshl_add_u64 v[64:65], s[42:43], 0, v[64:65]
	v_lshl_add_u64 v[84:85], v[98:99], 2, v[64:65]
	s_movk_i32 s4, 0x1000
	v_cmp_gt_i32_e32 vcc, s4, v78
	s_nop 1
	v_cndmask_b32_e32 v73, v71, v102, vcc
	v_and_b32_e32 v73, 1, v73
	v_cmp_eq_u32_e32 vcc, 1, v73
	s_nop 1
	v_cndmask_b32_e64 v73, v171, 0, vcc
	v_add_u32_e32 v73, v103, v73
	ds_read_b128 v[80:83], v86 offset:4352
	ds_read_b128 v[88:91], v73
	s_and_b64 vcc, exec, s[0:1]
	s_waitcnt lgkmcnt(0)
	v_pk_fma_f32 v[66:67], v[82:83], v[90:91], v[216:217]
	v_pk_fma_f32 v[64:65], v[80:81], v[88:89], v[214:215]
	global_store_dwordx4 v[84:85], v[64:67], off nt
	s_cbranch_vccnz .LBB0_1244
	ds_read_b128 v[80:83], v73 offset:2048
	v_lshlrev_b64 v[78:79], 10, v[78:79]
	v_lshl_add_u64 v[78:79], v[78:79], 1, s[44:45]
	v_lshl_add_u64 v[78:79], v[98:99], 1, v[78:79]
	s_waitcnt lgkmcnt(0)
	v_pk_mul_f32 v[80:81], v[64:65], v[80:81]
	v_pk_mul_f32 v[64:65], v[64:65], v[64:65]
	v_pk_mul_f32 v[82:83], v[66:67], v[82:83]
	v_pk_mul_f32 v[66:67], v[66:67], v[66:67]
	v_add_f32_e32 v64, v64, v65
	v_add_f32_e32 v64, v66, v64
	v_add_f32_e32 v64, v67, v64
	v_cvt_pk_bf16_f32 v80, v80, v81
	v_cvt_pk_bf16_f32 v81, v82, v83
	v_add_f32_dpp v64, v64, v64 quad_perm:[1,0,3,2] row_mask:0xf bank_mask:0xf bound_ctrl:1
	global_store_dwordx2 v[78:79], v[80:81], off
	s_nop 0
	v_add_f32_dpp v64, v64, v64 quad_perm:[2,3,0,1] row_mask:0xf bank_mask:0xf bound_ctrl:1
	s_nop 1
	v_add_f32_dpp v64, v64, v64 row_half_mirror row_mask:0xf bank_mask:0xf bound_ctrl:1
	s_nop 1
	v_mov_b32_dpp v65, v64 row_mirror row_mask:0xf bank_mask:0xf bound_ctrl:1
	s_and_saveexec_b64 s[4:5], s[40:41]
	s_cbranch_execz .LBB0_1243
	v_ashrrev_i32_e32 v97, 31, v96
	v_lshl_add_u64 v[66:67], s[48:49], 0, v[68:69]
	v_lshl_add_u64 v[78:79], v[96:97], 0, v[128:129]
	v_lshl_add_u64 v[66:67], v[78:79], 2, v[66:67]
	v_add_f32_e32 v64, v64, v65
	global_store_dword v[66:67], v64, off offset:64

.LBB0_1244:
	v_or_b32_e32 v78, 20, v128
	v_or_b32_e32 v80, v96, v78
	v_ashrrev_i32_e32 v81, 31, v80
	v_lshlrev_b64 v[64:65], 12, v[80:81]
	v_lshl_add_u64 v[64:65], s[42:43], 0, v[64:65]
	v_lshl_add_u64 v[92:93], v[98:99], 2, v[64:65]
	s_movk_i32 s4, 0x1000
	v_cmp_gt_i32_e32 vcc, s4, v80
	s_nop 1
	v_cndmask_b32_e32 v73, v71, v102, vcc
	v_and_b32_e32 v73, 1, v73
	v_cmp_eq_u32_e32 vcc, 1, v73
	s_nop 1
	v_cndmask_b32_e64 v73, v171, 0, vcc
	v_add_u32_e32 v73, v103, v73
	ds_read_b128 v[82:85], v86 offset:5440
	ds_read_b128 v[88:91], v73
	s_and_b64 vcc, exec, s[0:1]
	s_waitcnt lgkmcnt(0)
	v_pk_fma_f32 v[66:67], v[84:85], v[90:91], v[220:221]
	v_pk_fma_f32 v[64:65], v[82:83], v[88:89], v[218:219]
	global_store_dwordx4 v[92:93], v[64:67], off nt
	s_cbranch_vccnz .LBB0_1248
	ds_read_b128 v[82:85], v73 offset:2048
	v_lshlrev_b64 v[80:81], 10, v[80:81]
	v_lshl_add_u64 v[80:81], v[80:81], 1, s[44:45]
	v_lshl_add_u64 v[80:81], v[98:99], 1, v[80:81]
	s_waitcnt lgkmcnt(0)
	v_pk_mul_f32 v[82:83], v[64:65], v[82:83]
	v_pk_mul_f32 v[64:65], v[64:65], v[64:65]
	v_pk_mul_f32 v[84:85], v[66:67], v[84:85]
	v_pk_mul_f32 v[66:67], v[66:67], v[66:67]
	v_add_f32_e32 v64, v64, v65
	v_add_f32_e32 v64, v66, v64
	v_add_f32_e32 v64, v67, v64
	v_cvt_pk_bf16_f32 v82, v82, v83
	v_cvt_pk_bf16_f32 v83, v84, v85
	v_add_f32_dpp v64, v64, v64 quad_perm:[1,0,3,2] row_mask:0xf bank_mask:0xf bound_ctrl:1
	global_store_dwordx2 v[80:81], v[82:83], off
	s_nop 0
	v_add_f32_dpp v64, v64, v64 quad_perm:[2,3,0,1] row_mask:0xf bank_mask:0xf bound_ctrl:1
	s_nop 1
	v_add_f32_dpp v64, v64, v64 row_half_mirror row_mask:0xf bank_mask:0xf bound_ctrl:1
	s_nop 1
	v_mov_b32_dpp v65, v64 row_mirror row_mask:0xf bank_mask:0xf bound_ctrl:1
	s_and_saveexec_b64 s[4:5], s[40:41]
	s_cbranch_execz .LBB0_1247
	v_ashrrev_i32_e32 v97, 31, v96
	v_lshl_add_u64 v[66:67], s[48:49], 0, v[68:69]
	v_lshl_add_u64 v[80:81], v[96:97], 0, v[128:129]
	v_lshl_add_u64 v[66:67], v[80:81], 2, v[66:67]
	v_add_f32_e32 v64, v64, v65
	global_store_dword v[66:67], v64, off offset:80

.LBB0_1248:
	v_or_b32_e32 v80, 24, v128
	v_or_b32_e32 v82, v96, v80
	v_ashrrev_i32_e32 v83, 31, v82
	v_lshlrev_b64 v[64:65], 12, v[82:83]
	v_lshl_add_u64 v[64:65], s[42:43], 0, v[64:65]
	v_lshl_add_u64 v[84:85], v[98:99], 2, v[64:65]
	s_movk_i32 s4, 0x1000
	v_cmp_gt_i32_e32 vcc, s4, v82
	s_nop 1
	v_cndmask_b32_e32 v73, v71, v102, vcc
	v_and_b32_e32 v73, 1, v73
	v_cmp_eq_u32_e32 vcc, 1, v73
	s_nop 1
	v_cndmask_b32_e64 v73, v171, 0, vcc
	v_add_u32_e32 v73, v103, v73
	ds_read_b128 v[88:91], v86 offset:6528
	ds_read_b128 v[92:95], v73
	s_and_b64 vcc, exec, s[0:1]
	s_waitcnt lgkmcnt(0)
	v_pk_fma_f32 v[66:67], v[90:91], v[94:95], v[224:225]
	v_pk_fma_f32 v[64:65], v[88:89], v[92:93], v[222:223]
	global_store_dwordx4 v[84:85], v[64:67], off nt
	s_cbranch_vccnz .LBB0_1252
	ds_read_b128 v[88:91], v73 offset:2048
	v_lshlrev_b64 v[82:83], 10, v[82:83]
	v_lshl_add_u64 v[82:83], v[82:83], 1, s[44:45]
	v_lshl_add_u64 v[82:83], v[98:99], 1, v[82:83]
	s_waitcnt lgkmcnt(0)
	v_pk_mul_f32 v[88:89], v[64:65], v[88:89]
	v_pk_mul_f32 v[64:65], v[64:65], v[64:65]
	v_pk_mul_f32 v[84:85], v[66:67], v[90:91]
	v_pk_mul_f32 v[66:67], v[66:67], v[66:67]
	v_add_f32_e32 v64, v64, v65
	v_add_f32_e32 v64, v66, v64
	v_add_f32_e32 v64, v67, v64
	v_cvt_pk_bf16_f32 v88, v88, v89
	v_cvt_pk_bf16_f32 v89, v84, v85
	v_add_f32_dpp v64, v64, v64 quad_perm:[1,0,3,2] row_mask:0xf bank_mask:0xf bound_ctrl:1
	global_store_dwordx2 v[82:83], v[88:89], off
	s_nop 0
	v_add_f32_dpp v64, v64, v64 quad_perm:[2,3,0,1] row_mask:0xf bank_mask:0xf bound_ctrl:1
	s_nop 1
	v_add_f32_dpp v64, v64, v64 row_half_mirror row_mask:0xf bank_mask:0xf bound_ctrl:1
	s_nop 1
	v_mov_b32_dpp v65, v64 row_mirror row_mask:0xf bank_mask:0xf bound_ctrl:1
	s_and_saveexec_b64 s[4:5], s[40:41]
	s_cbranch_execz .LBB0_1251
	v_ashrrev_i32_e32 v97, 31, v96
	v_lshl_add_u64 v[66:67], s[48:49], 0, v[68:69]
	v_lshl_add_u64 v[82:83], v[96:97], 0, v[128:129]
	v_lshl_add_u64 v[66:67], v[82:83], 2, v[66:67]
	v_add_f32_e32 v64, v64, v65
	global_store_dword v[66:67], v64, off offset:96

.LBB0_1252:
	v_or_b32_e32 v82, 28, v128
	v_or_b32_e32 v84, v96, v82
	v_ashrrev_i32_e32 v85, 31, v84
	v_lshlrev_b64 v[64:65], 12, v[84:85]
	v_lshl_add_u64 v[64:65], s[42:43], 0, v[64:65]
	v_lshl_add_u64 v[100:101], v[98:99], 2, v[64:65]
	s_movk_i32 s4, 0x1000
	v_cmp_gt_i32_e32 vcc, s4, v84
	s_nop 1
	v_cndmask_b32_e32 v71, v71, v102, vcc
	v_and_b32_e32 v71, 1, v71
	v_cmp_eq_u32_e32 vcc, 1, v71
	s_nop 1
	v_cndmask_b32_e64 v71, v171, 0, vcc
	v_add_u32_e32 v71, v103, v71
	ds_read_b128 v[88:91], v86 offset:7616
	ds_read_b128 v[92:95], v71
	s_and_b64 vcc, exec, s[0:1]
	s_waitcnt lgkmcnt(0)
	v_pk_fma_f32 v[66:67], v[90:91], v[94:95], v[228:229]
	v_pk_fma_f32 v[64:65], v[88:89], v[92:93], v[226:227]
	global_store_dwordx4 v[100:101], v[64:67], off nt
	s_cbranch_vccnz .LBB0_1256
	ds_read_b128 v[88:91], v71 offset:2048
	v_lshlrev_b64 v[84:85], 10, v[84:85]
	v_lshl_add_u64 v[84:85], v[84:85], 1, s[44:45]
	v_lshl_add_u64 v[84:85], v[98:99], 1, v[84:85]
	s_waitcnt lgkmcnt(0)
	v_pk_mul_f32 v[88:89], v[64:65], v[88:89]
	v_pk_mul_f32 v[64:65], v[64:65], v[64:65]
	v_pk_mul_f32 v[90:91], v[66:67], v[90:91]
	v_pk_mul_f32 v[66:67], v[66:67], v[66:67]
	v_add_f32_e32 v64, v64, v65
	v_add_f32_e32 v64, v66, v64
	v_add_f32_e32 v64, v67, v64
	v_cvt_pk_bf16_f32 v88, v88, v89
	v_cvt_pk_bf16_f32 v89, v90, v91
	v_add_f32_dpp v64, v64, v64 quad_perm:[1,0,3,2] row_mask:0xf bank_mask:0xf bound_ctrl:1
	global_store_dwordx2 v[84:85], v[88:89], off
	s_nop 0
	v_add_f32_dpp v64, v64, v64 quad_perm:[2,3,0,1] row_mask:0xf bank_mask:0xf bound_ctrl:1
	s_nop 1
	v_add_f32_dpp v64, v64, v64 row_half_mirror row_mask:0xf bank_mask:0xf bound_ctrl:1
	s_nop 1
	v_mov_b32_dpp v65, v64 row_mirror row_mask:0xf bank_mask:0xf bound_ctrl:1
	s_and_saveexec_b64 s[4:5], s[40:41]
	s_cbranch_execz .LBB0_1255
	v_ashrrev_i32_e32 v97, 31, v96
	v_lshl_add_u64 v[66:67], s[48:49], 0, v[68:69]
	v_lshl_add_u64 v[84:85], v[96:97], 0, v[128:129]
	v_lshl_add_u64 v[66:67], v[84:85], 2, v[66:67]
	v_add_f32_e32 v64, v64, v65
	global_store_dword v[66:67], v64, off offset:112

.LBB0_1256:
	s_nop 0
	v_add_u32_e32 v66, 32, v96
	v_or_b32_e32 v64, v66, v128
	v_ashrrev_i32_e32 v65, 31, v64
	v_lshlrev_b64 v[84:85], 12, v[64:65]
	v_lshl_add_u64 v[84:85], s[42:43], 0, v[84:85]
	v_lshl_add_u64 v[84:85], v[98:99], 2, v[84:85]
	v_add_co_u32_e32 v182, vcc, 0x20000, v84
	s_nop 1
	v_addc_co_u32_e32 v183, vcc, 0, v85, vcc
	global_load_dwordx4 v[198:201], v[182:183], off
	v_add_co_u32_e32 v182, vcc, 0x4000, v182
	s_nop 1
	v_addc_co_u32_e32 v183, vcc, 0, v183, vcc
	global_load_dwordx4 v[202:205], v[182:183], off
	v_add_co_u32_e32 v182, vcc, 0x4000, v182
	s_nop 1
	v_addc_co_u32_e32 v183, vcc, 0, v183, vcc
	global_load_dwordx4 v[206:209], v[182:183], off
	v_add_co_u32_e32 v182, vcc, 0x4000, v182
	s_nop 1
	v_addc_co_u32_e32 v183, vcc, 0, v183, vcc
	global_load_dwordx4 v[210:213], v[182:183], off
	v_add_co_u32_e32 v182, vcc, 0x4000, v182
	s_nop 1
	v_addc_co_u32_e32 v183, vcc, 0, v183, vcc
	global_load_dwordx4 v[214:217], v[182:183], off
	v_add_co_u32_e32 v182, vcc, 0x4000, v182
	s_nop 1
	v_addc_co_u32_e32 v183, vcc, 0, v183, vcc
	global_load_dwordx4 v[218:221], v[182:183], off
	v_add_co_u32_e32 v182, vcc, 0x4000, v182
	s_nop 1
	v_addc_co_u32_e32 v183, vcc, 0, v183, vcc
	global_load_dwordx4 v[222:225], v[182:183], off
	v_add_co_u32_e32 v182, vcc, 0x4000, v182
	s_nop 1
	v_addc_co_u32_e32 v183, vcc, 0, v183, vcc
	global_load_dwordx4 v[226:229], v[182:183], off
	ds_write_b128 v104, v[32:35]
	ds_write_b128 v104, v[36:39] offset:32
	ds_write_b128 v104, v[40:43] offset:64
	ds_write_b128 v104, v[44:47] offset:96
	ds_write_b128 v104, v[48:51] offset:128
	ds_write_b128 v104, v[52:55] offset:160
	ds_write_b128 v104, v[56:59] offset:192
	ds_write_b128 v104, v[60:63] offset:224
	v_add_u32_e32 v32, 0xfffff020, v96
	v_xor_b32_e32 v32, s7, v32
	s_movk_i32 s4, 0x400
	v_cmp_gt_u32_e32 vcc, s4, v32
	s_and_b64 s[4:5], s[2:3], vcc
	v_cndmask_b32_e64 v38, 0, 1, s[4:5]
	s_movk_i32 s4, 0x1000
	v_cmp_gt_i32_e32 vcc, s4, v64
	s_nop 1
	v_cndmask_b32_e32 v32, v38, v102, vcc
	v_and_b32_e32 v32, 1, v32
	v_cmp_eq_u32_e32 vcc, 1, v32
	s_nop 1
	v_cndmask_b32_e64 v32, v171, 0, vcc
	v_add_u32_e32 v36, v103, v32
	ds_read_b128 v[32:35], v86
	ds_read_b128 v[40:43], v36
	s_and_b64 vcc, exec, s[0:1]
	s_waitcnt vmcnt(23) lgkmcnt(0)
	v_pk_fma_f32 v[34:35], v[34:35], v[42:43], v[186:187]
	v_pk_fma_f32 v[32:33], v[32:33], v[40:41], v[184:185]
	global_store_dwordx4 v[84:85], v[32:35], off nt
	s_cbranch_vccnz .LBB0_1260
	ds_read_b128 v[40:43], v36 offset:2048
	v_lshlrev_b64 v[36:37], 10, v[64:65]
	v_lshl_add_u64 v[36:37], v[36:37], 1, s[44:45]
	v_lshl_add_u64 v[36:37], v[98:99], 1, v[36:37]
	s_waitcnt lgkmcnt(0)
	v_pk_mul_f32 v[40:41], v[32:33], v[40:41]
	v_pk_mul_f32 v[32:33], v[32:33], v[32:33]
	v_pk_mul_f32 v[42:43], v[34:35], v[42:43]
	v_pk_mul_f32 v[34:35], v[34:35], v[34:35]
	v_add_f32_e32 v32, v32, v33
	v_add_f32_e32 v32, v34, v32
	v_add_f32_e32 v32, v35, v32
	v_cvt_pk_bf16_f32 v40, v40, v41
	v_cvt_pk_bf16_f32 v41, v42, v43
	v_add_f32_dpp v32, v32, v32 quad_perm:[1,0,3,2] row_mask:0xf bank_mask:0xf bound_ctrl:1
	global_store_dwordx2 v[36:37], v[40:41], off
	s_nop 0
	v_add_f32_dpp v32, v32, v32 quad_perm:[2,3,0,1] row_mask:0xf bank_mask:0xf bound_ctrl:1
	s_nop 1
	v_add_f32_dpp v32, v32, v32 row_half_mirror row_mask:0xf bank_mask:0xf bound_ctrl:1
	s_nop 1
	v_mov_b32_dpp v33, v32 row_mirror row_mask:0xf bank_mask:0xf bound_ctrl:1
	s_and_saveexec_b64 s[4:5], s[40:41]
	s_cbranch_execz .LBB0_1259
	v_ashrrev_i32_e32 v97, 31, v96
	v_lshl_add_u64 v[34:35], s[48:49], 0, v[68:69]
	v_lshl_add_u64 v[36:37], v[96:97], 0, v[128:129]
	v_lshl_add_u64 v[34:35], v[36:37], 2, v[34:35]
	v_add_f32_e32 v32, v32, v33
	global_store_dword v[34:35], v32, off offset:128

.LBB0_1260:
	v_or_b32_e32 v36, v66, v70
	v_ashrrev_i32_e32 v37, 31, v36
	v_lshlrev_b64 v[32:33], 12, v[36:37]
	v_lshl_add_u64 v[32:33], s[42:43], 0, v[32:33]
	v_lshl_add_u64 v[48:49], v[98:99], 2, v[32:33]
	s_movk_i32 s4, 0x1000
	v_cmp_gt_i32_e32 vcc, s4, v36
	s_nop 1
	v_cndmask_b32_e32 v39, v38, v102, vcc
	v_and_b32_e32 v39, 1, v39
	v_cmp_eq_u32_e32 vcc, 1, v39
	s_nop 1
	v_cndmask_b32_e64 v39, v171, 0, vcc
	v_add_u32_e32 v39, v103, v39
	ds_read_b128 v[40:43], v86 offset:1088
	ds_read_b128 v[44:47], v39
	s_and_b64 vcc, exec, s[0:1]
	s_waitcnt vmcnt(23) lgkmcnt(0)
	v_pk_fma_f32 v[34:35], v[42:43], v[46:47], v[190:191]
	v_pk_fma_f32 v[32:33], v[40:41], v[44:45], v[188:189]
	global_store_dwordx4 v[48:49], v[32:35], off nt
	s_cbranch_vccnz .LBB0_1264
	ds_read_b128 v[40:43], v39 offset:2048
	v_lshlrev_b64 v[36:37], 10, v[36:37]
	v_lshl_add_u64 v[36:37], v[36:37], 1, s[44:45]
	v_lshl_add_u64 v[36:37], v[98:99], 1, v[36:37]
	s_waitcnt lgkmcnt(0)
	v_pk_mul_f32 v[40:41], v[32:33], v[40:41]
	v_pk_mul_f32 v[32:33], v[32:33], v[32:33]
	v_pk_mul_f32 v[42:43], v[34:35], v[42:43]
	v_pk_mul_f32 v[34:35], v[34:35], v[34:35]
	v_add_f32_e32 v32, v32, v33
	v_add_f32_e32 v32, v34, v32
	v_add_f32_e32 v32, v35, v32
	v_cvt_pk_bf16_f32 v40, v40, v41
	v_cvt_pk_bf16_f32 v41, v42, v43
	v_add_f32_dpp v32, v32, v32 quad_perm:[1,0,3,2] row_mask:0xf bank_mask:0xf bound_ctrl:1
	global_store_dwordx2 v[36:37], v[40:41], off
	s_nop 0
	v_add_f32_dpp v32, v32, v32 quad_perm:[2,3,0,1] row_mask:0xf bank_mask:0xf bound_ctrl:1
	s_nop 1
	v_add_f32_dpp v32, v32, v32 row_half_mirror row_mask:0xf bank_mask:0xf bound_ctrl:1
	s_nop 1
	v_mov_b32_dpp v33, v32 row_mirror row_mask:0xf bank_mask:0xf bound_ctrl:1
	s_and_saveexec_b64 s[4:5], s[40:41]
	s_cbranch_execz .LBB0_1263
	v_mov_b32_e32 v71, v129
	v_ashrrev_i32_e32 v97, 31, v96
	v_lshl_add_u64 v[34:35], s[48:49], 0, v[68:69]
	v_lshl_add_u64 v[36:37], v[96:97], 0, v[70:71]
	v_lshl_add_u64 v[34:35], v[36:37], 2, v[34:35]
	v_add_f32_e32 v32, v32, v33
	global_store_dword v[34:35], v32, off offset:128

.LBB0_1264:
	v_or_b32_e32 v36, v66, v72
	v_ashrrev_i32_e32 v37, 31, v36
	v_lshlrev_b64 v[32:33], 12, v[36:37]
	v_lshl_add_u64 v[32:33], s[42:43], 0, v[32:33]
	v_lshl_add_u64 v[48:49], v[98:99], 2, v[32:33]
	s_movk_i32 s4, 0x1000
	v_cmp_gt_i32_e32 vcc, s4, v36
	s_nop 1
	v_cndmask_b32_e32 v39, v38, v102, vcc
	v_and_b32_e32 v39, 1, v39
	v_cmp_eq_u32_e32 vcc, 1, v39
	s_nop 1
	v_cndmask_b32_e64 v39, v171, 0, vcc
	v_add_u32_e32 v39, v103, v39
	ds_read_b128 v[40:43], v86 offset:2176
	ds_read_b128 v[44:47], v39
	s_and_b64 vcc, exec, s[0:1]
	s_waitcnt vmcnt(23) lgkmcnt(0)
	v_pk_fma_f32 v[34:35], v[42:43], v[46:47], v[194:195]
	v_pk_fma_f32 v[32:33], v[40:41], v[44:45], v[192:193]
	global_store_dwordx4 v[48:49], v[32:35], off nt
	s_cbranch_vccnz .LBB0_1268
	ds_read_b128 v[40:43], v39 offset:2048
	v_lshlrev_b64 v[36:37], 10, v[36:37]
	v_lshl_add_u64 v[36:37], v[36:37], 1, s[44:45]
	v_lshl_add_u64 v[36:37], v[98:99], 1, v[36:37]
	s_waitcnt lgkmcnt(0)
	v_pk_mul_f32 v[40:41], v[32:33], v[40:41]
	v_pk_mul_f32 v[32:33], v[32:33], v[32:33]
	v_pk_mul_f32 v[42:43], v[34:35], v[42:43]
	v_pk_mul_f32 v[34:35], v[34:35], v[34:35]
	v_add_f32_e32 v32, v32, v33
	v_add_f32_e32 v32, v34, v32
	v_add_f32_e32 v32, v35, v32
	v_cvt_pk_bf16_f32 v40, v40, v41
	v_cvt_pk_bf16_f32 v41, v42, v43
	v_add_f32_dpp v32, v32, v32 quad_perm:[1,0,3,2] row_mask:0xf bank_mask:0xf bound_ctrl:1
	global_store_dwordx2 v[36:37], v[40:41], off
	s_nop 0
	v_add_f32_dpp v32, v32, v32 quad_perm:[2,3,0,1] row_mask:0xf bank_mask:0xf bound_ctrl:1
	s_nop 1
	v_add_f32_dpp v32, v32, v32 row_half_mirror row_mask:0xf bank_mask:0xf bound_ctrl:1
	s_nop 1
	v_mov_b32_dpp v33, v32 row_mirror row_mask:0xf bank_mask:0xf bound_ctrl:1
	s_and_saveexec_b64 s[4:5], s[40:41]
	s_cbranch_execz .LBB0_1267
	v_mov_b32_e32 v73, v129
	v_ashrrev_i32_e32 v97, 31, v96
	v_lshl_add_u64 v[34:35], s[48:49], 0, v[68:69]
	v_lshl_add_u64 v[36:37], v[96:97], 0, v[72:73]
	v_lshl_add_u64 v[34:35], v[36:37], 2, v[34:35]
	v_add_f32_e32 v32, v32, v33
	global_store_dword v[34:35], v32, off offset:128

.LBB0_1268:
	v_or_b32_e32 v36, v66, v74
	v_ashrrev_i32_e32 v37, 31, v36
	v_lshlrev_b64 v[32:33], 12, v[36:37]
	v_lshl_add_u64 v[32:33], s[42:43], 0, v[32:33]
	v_lshl_add_u64 v[48:49], v[98:99], 2, v[32:33]
	s_movk_i32 s4, 0x1000
	v_cmp_gt_i32_e32 vcc, s4, v36
	s_nop 1
	v_cndmask_b32_e32 v39, v38, v102, vcc
	v_and_b32_e32 v39, 1, v39
	v_cmp_eq_u32_e32 vcc, 1, v39
	s_nop 1
	v_cndmask_b32_e64 v39, v171, 0, vcc
	v_add_u32_e32 v39, v103, v39
	ds_read_b128 v[40:43], v86 offset:3264
	ds_read_b128 v[44:47], v39
	s_and_b64 vcc, exec, s[0:1]
	s_waitcnt vmcnt(23) lgkmcnt(0)
	v_pk_fma_f32 v[34:35], v[42:43], v[46:47], v[118:119]
	v_pk_fma_f32 v[32:33], v[40:41], v[44:45], v[116:117]
	global_store_dwordx4 v[48:49], v[32:35], off nt
	s_cbranch_vccnz .LBB0_1272
	ds_read_b128 v[40:43], v39 offset:2048
	v_lshlrev_b64 v[36:37], 10, v[36:37]
	v_lshl_add_u64 v[36:37], v[36:37], 1, s[44:45]
	v_lshl_add_u64 v[36:37], v[98:99], 1, v[36:37]
	s_waitcnt lgkmcnt(0)
	v_pk_mul_f32 v[40:41], v[32:33], v[40:41]
	v_pk_mul_f32 v[32:33], v[32:33], v[32:33]
	v_pk_mul_f32 v[42:43], v[34:35], v[42:43]
	v_pk_mul_f32 v[34:35], v[34:35], v[34:35]
	v_add_f32_e32 v32, v32, v33
	v_add_f32_e32 v32, v34, v32
	v_add_f32_e32 v32, v35, v32
	v_cvt_pk_bf16_f32 v40, v40, v41
	v_cvt_pk_bf16_f32 v41, v42, v43
	v_add_f32_dpp v32, v32, v32 quad_perm:[1,0,3,2] row_mask:0xf bank_mask:0xf bound_ctrl:1
	global_store_dwordx2 v[36:37], v[40:41], off
	s_nop 0
	v_add_f32_dpp v32, v32, v32 quad_perm:[2,3,0,1] row_mask:0xf bank_mask:0xf bound_ctrl:1
	s_nop 1
	v_add_f32_dpp v32, v32, v32 row_half_mirror row_mask:0xf bank_mask:0xf bound_ctrl:1
	s_nop 1
	v_mov_b32_dpp v33, v32 row_mirror row_mask:0xf bank_mask:0xf bound_ctrl:1
	s_and_saveexec_b64 s[4:5], s[40:41]
	s_cbranch_execz .LBB0_1271
	v_mov_b32_e32 v75, v129
	v_ashrrev_i32_e32 v97, 31, v96
	v_lshl_add_u64 v[34:35], s[48:49], 0, v[68:69]
	v_lshl_add_u64 v[36:37], v[96:97], 0, v[74:75]
	v_lshl_add_u64 v[34:35], v[36:37], 2, v[34:35]
	v_add_f32_e32 v32, v32, v33
	global_store_dword v[34:35], v32, off offset:128

.LBB0_1272:
	v_or_b32_e32 v36, v66, v76
	v_ashrrev_i32_e32 v37, 31, v36
	v_lshlrev_b64 v[32:33], 12, v[36:37]
	v_lshl_add_u64 v[32:33], s[42:43], 0, v[32:33]
	v_lshl_add_u64 v[48:49], v[98:99], 2, v[32:33]
	s_movk_i32 s4, 0x1000
	v_cmp_gt_i32_e32 vcc, s4, v36
	s_nop 1
	v_cndmask_b32_e32 v39, v38, v102, vcc
	v_and_b32_e32 v39, 1, v39
	v_cmp_eq_u32_e32 vcc, 1, v39
	s_nop 1
	v_cndmask_b32_e64 v39, v171, 0, vcc
	v_add_u32_e32 v39, v103, v39
	ds_read_b128 v[40:43], v86 offset:4352
	ds_read_b128 v[44:47], v39
	s_and_b64 vcc, exec, s[0:1]
	s_waitcnt vmcnt(23) lgkmcnt(0)
	v_pk_fma_f32 v[34:35], v[42:43], v[46:47], v[122:123]
	v_pk_fma_f32 v[32:33], v[40:41], v[44:45], v[120:121]
	global_store_dwordx4 v[48:49], v[32:35], off nt
	s_cbranch_vccnz .LBB0_1276
	ds_read_b128 v[40:43], v39 offset:2048
	v_lshlrev_b64 v[36:37], 10, v[36:37]
	v_lshl_add_u64 v[36:37], v[36:37], 1, s[44:45]
	v_lshl_add_u64 v[36:37], v[98:99], 1, v[36:37]
	s_waitcnt lgkmcnt(0)
	v_pk_mul_f32 v[40:41], v[32:33], v[40:41]
	v_pk_mul_f32 v[32:33], v[32:33], v[32:33]
	v_pk_mul_f32 v[42:43], v[34:35], v[42:43]
	v_pk_mul_f32 v[34:35], v[34:35], v[34:35]
	v_add_f32_e32 v32, v32, v33
	v_add_f32_e32 v32, v34, v32
	v_add_f32_e32 v32, v35, v32
	v_cvt_pk_bf16_f32 v40, v40, v41
	v_cvt_pk_bf16_f32 v41, v42, v43
	v_add_f32_dpp v32, v32, v32 quad_perm:[1,0,3,2] row_mask:0xf bank_mask:0xf bound_ctrl:1
	global_store_dwordx2 v[36:37], v[40:41], off
	s_nop 0
	v_add_f32_dpp v32, v32, v32 quad_perm:[2,3,0,1] row_mask:0xf bank_mask:0xf bound_ctrl:1
	s_nop 1
	v_add_f32_dpp v32, v32, v32 row_half_mirror row_mask:0xf bank_mask:0xf bound_ctrl:1
	s_nop 1
	v_mov_b32_dpp v33, v32 row_mirror row_mask:0xf bank_mask:0xf bound_ctrl:1
	s_and_saveexec_b64 s[4:5], s[40:41]
	s_cbranch_execz .LBB0_1275
	v_mov_b32_e32 v77, v129
	v_ashrrev_i32_e32 v97, 31, v96
	v_lshl_add_u64 v[34:35], s[48:49], 0, v[68:69]
	v_lshl_add_u64 v[36:37], v[96:97], 0, v[76:77]
	v_lshl_add_u64 v[34:35], v[36:37], 2, v[34:35]
	v_add_f32_e32 v32, v32, v33
	global_store_dword v[34:35], v32, off offset:128

.LBB0_1276:
	v_or_b32_e32 v36, v66, v78
	v_ashrrev_i32_e32 v37, 31, v36
	v_lshlrev_b64 v[32:33], 12, v[36:37]
	v_lshl_add_u64 v[32:33], s[42:43], 0, v[32:33]
	v_lshl_add_u64 v[48:49], v[98:99], 2, v[32:33]
	s_movk_i32 s4, 0x1000
	v_cmp_gt_i32_e32 vcc, s4, v36
	s_nop 1
	v_cndmask_b32_e32 v39, v38, v102, vcc
	v_and_b32_e32 v39, 1, v39
	v_cmp_eq_u32_e32 vcc, 1, v39
	s_nop 1
	v_cndmask_b32_e64 v39, v171, 0, vcc
	v_add_u32_e32 v39, v103, v39
	ds_read_b128 v[40:43], v86 offset:5440
	ds_read_b128 v[44:47], v39
	s_and_b64 vcc, exec, s[0:1]
	s_waitcnt vmcnt(23) lgkmcnt(0)
	v_pk_fma_f32 v[34:35], v[42:43], v[46:47], v[126:127]
	v_pk_fma_f32 v[32:33], v[40:41], v[44:45], v[124:125]
	global_store_dwordx4 v[48:49], v[32:35], off nt
	s_cbranch_vccnz .LBB0_1280
	ds_read_b128 v[40:43], v39 offset:2048
	v_lshlrev_b64 v[36:37], 10, v[36:37]
	v_lshl_add_u64 v[36:37], v[36:37], 1, s[44:45]
	v_lshl_add_u64 v[36:37], v[98:99], 1, v[36:37]
	s_waitcnt lgkmcnt(0)
	v_pk_mul_f32 v[40:41], v[32:33], v[40:41]
	v_pk_mul_f32 v[32:33], v[32:33], v[32:33]
	v_pk_mul_f32 v[42:43], v[34:35], v[42:43]
	v_pk_mul_f32 v[34:35], v[34:35], v[34:35]
	v_add_f32_e32 v32, v32, v33
	v_add_f32_e32 v32, v34, v32
	v_add_f32_e32 v32, v35, v32
	v_cvt_pk_bf16_f32 v40, v40, v41
	v_cvt_pk_bf16_f32 v41, v42, v43
	v_add_f32_dpp v32, v32, v32 quad_perm:[1,0,3,2] row_mask:0xf bank_mask:0xf bound_ctrl:1
	global_store_dwordx2 v[36:37], v[40:41], off
	s_nop 0
	v_add_f32_dpp v32, v32, v32 quad_perm:[2,3,0,1] row_mask:0xf bank_mask:0xf bound_ctrl:1
	s_nop 1
	v_add_f32_dpp v32, v32, v32 row_half_mirror row_mask:0xf bank_mask:0xf bound_ctrl:1
	s_nop 1
	v_mov_b32_dpp v33, v32 row_mirror row_mask:0xf bank_mask:0xf bound_ctrl:1
	s_and_saveexec_b64 s[4:5], s[40:41]
	s_cbranch_execz .LBB0_1279
	v_mov_b32_e32 v79, v129
	v_ashrrev_i32_e32 v97, 31, v96
	v_lshl_add_u64 v[34:35], s[48:49], 0, v[68:69]
	v_lshl_add_u64 v[36:37], v[96:97], 0, v[78:79]
	v_lshl_add_u64 v[34:35], v[36:37], 2, v[34:35]
	v_add_f32_e32 v32, v32, v33
	global_store_dword v[34:35], v32, off offset:128

.LBB0_1280:
	v_or_b32_e32 v36, v66, v80
	v_ashrrev_i32_e32 v37, 31, v36
	v_lshlrev_b64 v[32:33], 12, v[36:37]
	v_lshl_add_u64 v[32:33], s[42:43], 0, v[32:33]
	v_lshl_add_u64 v[48:49], v[98:99], 2, v[32:33]
	s_movk_i32 s4, 0x1000
	v_cmp_gt_i32_e32 vcc, s4, v36
	s_nop 1
	v_cndmask_b32_e32 v39, v38, v102, vcc
	v_and_b32_e32 v39, 1, v39
	v_cmp_eq_u32_e32 vcc, 1, v39
	s_nop 1
	v_cndmask_b32_e64 v39, v171, 0, vcc
	v_add_u32_e32 v39, v103, v39
	ds_read_b128 v[40:43], v86 offset:6528
	ds_read_b128 v[44:47], v39
	s_and_b64 vcc, exec, s[0:1]
	s_waitcnt vmcnt(23) lgkmcnt(0)
	v_pk_fma_f32 v[34:35], v[42:43], v[46:47], v[132:133]
	v_pk_fma_f32 v[32:33], v[40:41], v[44:45], v[130:131]
	global_store_dwordx4 v[48:49], v[32:35], off nt
	s_cbranch_vccnz .LBB0_1284
	ds_read_b128 v[40:43], v39 offset:2048
	v_lshlrev_b64 v[36:37], 10, v[36:37]
	v_lshl_add_u64 v[36:37], v[36:37], 1, s[44:45]
	v_lshl_add_u64 v[36:37], v[98:99], 1, v[36:37]
	s_waitcnt lgkmcnt(0)
	v_pk_mul_f32 v[40:41], v[32:33], v[40:41]
	v_pk_mul_f32 v[32:33], v[32:33], v[32:33]
	v_pk_mul_f32 v[42:43], v[34:35], v[42:43]
	v_pk_mul_f32 v[34:35], v[34:35], v[34:35]
	v_add_f32_e32 v32, v32, v33
	v_add_f32_e32 v32, v34, v32
	v_add_f32_e32 v32, v35, v32
	v_cvt_pk_bf16_f32 v40, v40, v41
	v_cvt_pk_bf16_f32 v41, v42, v43
	v_add_f32_dpp v32, v32, v32 quad_perm:[1,0,3,2] row_mask:0xf bank_mask:0xf bound_ctrl:1
	global_store_dwordx2 v[36:37], v[40:41], off
	s_nop 0
	v_add_f32_dpp v32, v32, v32 quad_perm:[2,3,0,1] row_mask:0xf bank_mask:0xf bound_ctrl:1
	s_nop 1
	v_add_f32_dpp v32, v32, v32 row_half_mirror row_mask:0xf bank_mask:0xf bound_ctrl:1
	s_nop 1
	v_mov_b32_dpp v33, v32 row_mirror row_mask:0xf bank_mask:0xf bound_ctrl:1
	s_and_saveexec_b64 s[4:5], s[40:41]
	s_cbranch_execz .LBB0_1283
	v_mov_b32_e32 v81, v129
	v_ashrrev_i32_e32 v97, 31, v96
	v_lshl_add_u64 v[34:35], s[48:49], 0, v[68:69]
	v_lshl_add_u64 v[36:37], v[96:97], 0, v[80:81]
	v_lshl_add_u64 v[34:35], v[36:37], 2, v[34:35]
	v_add_f32_e32 v32, v32, v33
	global_store_dword v[34:35], v32, off offset:128

.LBB0_1284:
	v_or_b32_e32 v36, v66, v82
	v_ashrrev_i32_e32 v37, 31, v36
	v_lshlrev_b64 v[32:33], 12, v[36:37]
	v_lshl_add_u64 v[32:33], s[42:43], 0, v[32:33]
	v_lshl_add_u64 v[48:49], v[98:99], 2, v[32:33]
	s_movk_i32 s4, 0x1000
	v_cmp_gt_i32_e32 vcc, s4, v36
	s_nop 1
	v_cndmask_b32_e32 v38, v38, v102, vcc
	v_and_b32_e32 v38, 1, v38
	v_cmp_eq_u32_e32 vcc, 1, v38
	s_nop 1
	v_cndmask_b32_e64 v38, v171, 0, vcc
	v_add_u32_e32 v38, v103, v38
	ds_read_b128 v[40:43], v86 offset:7616
	ds_read_b128 v[44:47], v38
	s_and_b64 vcc, exec, s[0:1]
	s_waitcnt vmcnt(23) lgkmcnt(0)
	v_pk_fma_f32 v[34:35], v[42:43], v[46:47], v[136:137]
	v_pk_fma_f32 v[32:33], v[40:41], v[44:45], v[134:135]
	global_store_dwordx4 v[48:49], v[32:35], off nt
	s_cbranch_vccnz .LBB0_1288
	ds_read_b128 v[38:41], v38 offset:2048
	v_lshlrev_b64 v[36:37], 10, v[36:37]
	v_lshl_add_u64 v[36:37], v[36:37], 1, s[44:45]
	v_lshl_add_u64 v[36:37], v[98:99], 1, v[36:37]
	s_waitcnt lgkmcnt(0)
	v_pk_mul_f32 v[38:39], v[32:33], v[38:39]
	v_pk_mul_f32 v[32:33], v[32:33], v[32:33]
	v_pk_mul_f32 v[40:41], v[34:35], v[40:41]
	v_pk_mul_f32 v[34:35], v[34:35], v[34:35]
	v_add_f32_e32 v32, v32, v33
	v_add_f32_e32 v32, v34, v32
	v_add_f32_e32 v32, v35, v32
	v_cvt_pk_bf16_f32 v38, v38, v39
	v_cvt_pk_bf16_f32 v39, v40, v41
	v_add_f32_dpp v32, v32, v32 quad_perm:[1,0,3,2] row_mask:0xf bank_mask:0xf bound_ctrl:1
	global_store_dwordx2 v[36:37], v[38:39], off
	s_nop 0
	v_add_f32_dpp v32, v32, v32 quad_perm:[2,3,0,1] row_mask:0xf bank_mask:0xf bound_ctrl:1
	s_nop 1
	v_add_f32_dpp v32, v32, v32 row_half_mirror row_mask:0xf bank_mask:0xf bound_ctrl:1
	s_nop 1
	v_mov_b32_dpp v33, v32 row_mirror row_mask:0xf bank_mask:0xf bound_ctrl:1
	s_and_saveexec_b64 s[4:5], s[40:41]
	s_cbranch_execz .LBB0_1287
	v_mov_b32_e32 v83, v129
	v_ashrrev_i32_e32 v97, 31, v96
	v_lshl_add_u64 v[34:35], s[48:49], 0, v[68:69]
	v_lshl_add_u64 v[36:37], v[96:97], 0, v[82:83]
	v_lshl_add_u64 v[34:35], v[36:37], 2, v[34:35]
	v_add_f32_e32 v32, v32, v33
	global_store_dword v[34:35], v32, off offset:128

.LBB0_1288:
	s_nop 0
	v_add_u32_e32 v34, 64, v96
	v_or_b32_e32 v32, v34, v128
	v_ashrrev_i32_e32 v33, 31, v32
	v_lshlrev_b64 v[36:37], 12, v[32:33]
	v_lshl_add_u64 v[36:37], s[42:43], 0, v[36:37]
	v_lshl_add_u64 v[40:41], v[98:99], 2, v[36:37]
	ds_write_b128 v104, v[0:3]
	ds_write_b128 v104, v[4:7] offset:32
	ds_write_b128 v104, v[8:11] offset:64
	ds_write_b128 v104, v[12:15] offset:96
	ds_write_b128 v104, v[16:19] offset:128
	ds_write_b128 v104, v[20:23] offset:160
	ds_write_b128 v104, v[24:27] offset:192
	ds_write_b128 v104, v[28:31] offset:224
	v_add_u32_e32 v0, 0xfffff040, v96
	v_xor_b32_e32 v0, s7, v0
	s_movk_i32 s4, 0x400
	v_cmp_gt_u32_e32 vcc, s4, v0
	s_and_b64 s[2:3], s[2:3], vcc
	v_cndmask_b32_e64 v6, 0, 1, s[2:3]
	s_movk_i32 s2, 0x1000
	v_cmp_gt_i32_e32 vcc, s2, v32
	s_nop 1
	v_cndmask_b32_e32 v0, v6, v102, vcc
	v_and_b32_e32 v0, 1, v0
	v_cmp_eq_u32_e32 vcc, 1, v0
	s_nop 1
	v_cndmask_b32_e64 v0, v171, 0, vcc
	v_add_u32_e32 v4, v103, v0
	ds_read_b128 v[0:3], v86
	ds_read_b128 v[8:11], v4
	s_and_b64 vcc, exec, s[0:1]
	s_waitcnt vmcnt(15) lgkmcnt(0)
	v_pk_fma_f32 v[2:3], v[2:3], v[10:11], v[200:201]
	v_pk_fma_f32 v[0:1], v[0:1], v[8:9], v[198:199]
	global_store_dwordx4 v[40:41], v[0:3], off nt
	s_cbranch_vccnz .LBB0_1292
	ds_read_b128 v[8:11], v4 offset:2048
	v_lshlrev_b64 v[4:5], 10, v[32:33]
	v_lshl_add_u64 v[4:5], v[4:5], 1, s[44:45]
	v_lshl_add_u64 v[4:5], v[98:99], 1, v[4:5]
	s_waitcnt lgkmcnt(0)
	v_pk_mul_f32 v[8:9], v[0:1], v[8:9]
	v_pk_mul_f32 v[0:1], v[0:1], v[0:1]
	v_pk_mul_f32 v[10:11], v[2:3], v[10:11]
	v_pk_mul_f32 v[2:3], v[2:3], v[2:3]
	v_add_f32_e32 v0, v0, v1
	v_add_f32_e32 v0, v2, v0
	v_add_f32_e32 v0, v3, v0
	v_cvt_pk_bf16_f32 v8, v8, v9
	v_cvt_pk_bf16_f32 v9, v10, v11
	v_add_f32_dpp v0, v0, v0 quad_perm:[1,0,3,2] row_mask:0xf bank_mask:0xf bound_ctrl:1
	global_store_dwordx2 v[4:5], v[8:9], off
	s_nop 0
	v_add_f32_dpp v0, v0, v0 quad_perm:[2,3,0,1] row_mask:0xf bank_mask:0xf bound_ctrl:1
	s_nop 1
	v_add_f32_dpp v0, v0, v0 row_half_mirror row_mask:0xf bank_mask:0xf bound_ctrl:1
	s_nop 1
	v_mov_b32_dpp v1, v0 row_mirror row_mask:0xf bank_mask:0xf bound_ctrl:1
	s_and_saveexec_b64 s[2:3], s[40:41]
	s_cbranch_execz .LBB0_1291
	v_ashrrev_i32_e32 v97, 31, v96
	v_lshl_add_u64 v[2:3], s[48:49], 0, v[68:69]
	v_lshl_add_u64 v[4:5], v[96:97], 0, v[128:129]
	v_lshl_add_u64 v[2:3], v[4:5], 2, v[2:3]
	v_add_f32_e32 v0, v0, v1
	global_store_dword v[2:3], v0, off offset:256

.LBB0_1292:
	v_or_b32_e32 v4, v34, v70
	v_ashrrev_i32_e32 v5, 31, v4
	v_lshlrev_b64 v[0:1], 12, v[4:5]
	v_lshl_add_u64 v[0:1], s[42:43], 0, v[0:1]
	v_lshl_add_u64 v[16:17], v[98:99], 2, v[0:1]
	s_movk_i32 s2, 0x1000
	v_cmp_gt_i32_e32 vcc, s2, v4
	s_nop 1
	v_cndmask_b32_e32 v7, v6, v102, vcc
	v_and_b32_e32 v7, 1, v7
	v_cmp_eq_u32_e32 vcc, 1, v7
	s_nop 1
	v_cndmask_b32_e64 v7, v171, 0, vcc
	v_add_u32_e32 v7, v103, v7
	ds_read_b128 v[8:11], v86 offset:1088
	ds_read_b128 v[12:15], v7
	s_and_b64 vcc, exec, s[0:1]
	s_waitcnt vmcnt(15) lgkmcnt(0)
	v_pk_fma_f32 v[2:3], v[10:11], v[14:15], v[204:205]
	v_pk_fma_f32 v[0:1], v[8:9], v[12:13], v[202:203]
	global_store_dwordx4 v[16:17], v[0:3], off nt
	s_cbranch_vccnz .LBB0_1296
	ds_read_b128 v[8:11], v7 offset:2048
	v_lshlrev_b64 v[4:5], 10, v[4:5]
	v_lshl_add_u64 v[4:5], v[4:5], 1, s[44:45]
	v_lshl_add_u64 v[4:5], v[98:99], 1, v[4:5]
	s_waitcnt lgkmcnt(0)
	v_pk_mul_f32 v[8:9], v[0:1], v[8:9]
	v_pk_mul_f32 v[0:1], v[0:1], v[0:1]
	v_pk_mul_f32 v[10:11], v[2:3], v[10:11]
	v_pk_mul_f32 v[2:3], v[2:3], v[2:3]
	v_add_f32_e32 v0, v0, v1
	v_add_f32_e32 v0, v2, v0
	v_add_f32_e32 v0, v3, v0
	v_cvt_pk_bf16_f32 v8, v8, v9
	v_cvt_pk_bf16_f32 v9, v10, v11
	v_add_f32_dpp v0, v0, v0 quad_perm:[1,0,3,2] row_mask:0xf bank_mask:0xf bound_ctrl:1
	global_store_dwordx2 v[4:5], v[8:9], off
	s_nop 0
	v_add_f32_dpp v0, v0, v0 quad_perm:[2,3,0,1] row_mask:0xf bank_mask:0xf bound_ctrl:1
	s_nop 1
	v_add_f32_dpp v0, v0, v0 row_half_mirror row_mask:0xf bank_mask:0xf bound_ctrl:1
	s_nop 1
	v_mov_b32_dpp v1, v0 row_mirror row_mask:0xf bank_mask:0xf bound_ctrl:1
	s_and_saveexec_b64 s[2:3], s[40:41]
	s_cbranch_execz .LBB0_1295
	v_mov_b32_e32 v71, v129
	v_ashrrev_i32_e32 v97, 31, v96
	v_lshl_add_u64 v[2:3], s[48:49], 0, v[68:69]
	v_lshl_add_u64 v[4:5], v[96:97], 0, v[70:71]
	v_lshl_add_u64 v[2:3], v[4:5], 2, v[2:3]
	v_add_f32_e32 v0, v0, v1
	global_store_dword v[2:3], v0, off offset:256

.LBB0_1296:
	v_or_b32_e32 v4, v34, v72
	v_ashrrev_i32_e32 v5, 31, v4
	v_lshlrev_b64 v[0:1], 12, v[4:5]
	v_lshl_add_u64 v[0:1], s[42:43], 0, v[0:1]
	v_lshl_add_u64 v[16:17], v[98:99], 2, v[0:1]
	s_movk_i32 s2, 0x1000
	v_cmp_gt_i32_e32 vcc, s2, v4
	s_nop 1
	v_cndmask_b32_e32 v7, v6, v102, vcc
	v_and_b32_e32 v7, 1, v7
	v_cmp_eq_u32_e32 vcc, 1, v7
	s_nop 1
	v_cndmask_b32_e64 v7, v171, 0, vcc
	v_add_u32_e32 v7, v103, v7
	ds_read_b128 v[8:11], v86 offset:2176
	ds_read_b128 v[12:15], v7
	s_and_b64 vcc, exec, s[0:1]
	s_waitcnt vmcnt(15) lgkmcnt(0)
	v_pk_fma_f32 v[2:3], v[10:11], v[14:15], v[208:209]
	v_pk_fma_f32 v[0:1], v[8:9], v[12:13], v[206:207]
	global_store_dwordx4 v[16:17], v[0:3], off nt
	s_cbranch_vccnz .LBB0_1300
	ds_read_b128 v[8:11], v7 offset:2048
	v_lshlrev_b64 v[4:5], 10, v[4:5]
	v_lshl_add_u64 v[4:5], v[4:5], 1, s[44:45]
	v_lshl_add_u64 v[4:5], v[98:99], 1, v[4:5]
	s_waitcnt lgkmcnt(0)
	v_pk_mul_f32 v[8:9], v[0:1], v[8:9]
	v_pk_mul_f32 v[0:1], v[0:1], v[0:1]
	v_pk_mul_f32 v[10:11], v[2:3], v[10:11]
	v_pk_mul_f32 v[2:3], v[2:3], v[2:3]
	v_add_f32_e32 v0, v0, v1
	v_add_f32_e32 v0, v2, v0
	v_add_f32_e32 v0, v3, v0
	v_cvt_pk_bf16_f32 v8, v8, v9
	v_cvt_pk_bf16_f32 v9, v10, v11
	v_add_f32_dpp v0, v0, v0 quad_perm:[1,0,3,2] row_mask:0xf bank_mask:0xf bound_ctrl:1
	global_store_dwordx2 v[4:5], v[8:9], off
	s_nop 0
	v_add_f32_dpp v0, v0, v0 quad_perm:[2,3,0,1] row_mask:0xf bank_mask:0xf bound_ctrl:1
	s_nop 1
	v_add_f32_dpp v0, v0, v0 row_half_mirror row_mask:0xf bank_mask:0xf bound_ctrl:1
	s_nop 1
	v_mov_b32_dpp v1, v0 row_mirror row_mask:0xf bank_mask:0xf bound_ctrl:1
	s_and_saveexec_b64 s[2:3], s[40:41]
	s_cbranch_execz .LBB0_1299
	v_mov_b32_e32 v73, v129
	v_ashrrev_i32_e32 v97, 31, v96
	v_lshl_add_u64 v[2:3], s[48:49], 0, v[68:69]
	v_lshl_add_u64 v[4:5], v[96:97], 0, v[72:73]
	v_lshl_add_u64 v[2:3], v[4:5], 2, v[2:3]
	v_add_f32_e32 v0, v0, v1
	global_store_dword v[2:3], v0, off offset:256

.LBB0_1300:
	v_or_b32_e32 v4, v34, v74
	v_ashrrev_i32_e32 v5, 31, v4
	v_lshlrev_b64 v[0:1], 12, v[4:5]
	v_lshl_add_u64 v[0:1], s[42:43], 0, v[0:1]
	v_lshl_add_u64 v[16:17], v[98:99], 2, v[0:1]
	s_movk_i32 s2, 0x1000
	v_cmp_gt_i32_e32 vcc, s2, v4
	s_nop 1
	v_cndmask_b32_e32 v7, v6, v102, vcc
	v_and_b32_e32 v7, 1, v7
	v_cmp_eq_u32_e32 vcc, 1, v7
	s_nop 1
	v_cndmask_b32_e64 v7, v171, 0, vcc
	v_add_u32_e32 v7, v103, v7
	ds_read_b128 v[8:11], v86 offset:3264
	ds_read_b128 v[12:15], v7
	s_and_b64 vcc, exec, s[0:1]
	s_waitcnt vmcnt(15) lgkmcnt(0)
	v_pk_fma_f32 v[2:3], v[10:11], v[14:15], v[212:213]
	v_pk_fma_f32 v[0:1], v[8:9], v[12:13], v[210:211]
	global_store_dwordx4 v[16:17], v[0:3], off nt
	s_cbranch_vccnz .LBB0_1304
	ds_read_b128 v[8:11], v7 offset:2048
	v_lshlrev_b64 v[4:5], 10, v[4:5]
	v_lshl_add_u64 v[4:5], v[4:5], 1, s[44:45]
	v_lshl_add_u64 v[4:5], v[98:99], 1, v[4:5]
	s_waitcnt lgkmcnt(0)
	v_pk_mul_f32 v[8:9], v[0:1], v[8:9]
	v_pk_mul_f32 v[0:1], v[0:1], v[0:1]
	v_pk_mul_f32 v[10:11], v[2:3], v[10:11]
	v_pk_mul_f32 v[2:3], v[2:3], v[2:3]
	v_add_f32_e32 v0, v0, v1
	v_add_f32_e32 v0, v2, v0
	v_add_f32_e32 v0, v3, v0
	v_cvt_pk_bf16_f32 v8, v8, v9
	v_cvt_pk_bf16_f32 v9, v10, v11
	v_add_f32_dpp v0, v0, v0 quad_perm:[1,0,3,2] row_mask:0xf bank_mask:0xf bound_ctrl:1
	global_store_dwordx2 v[4:5], v[8:9], off
	s_nop 0
	v_add_f32_dpp v0, v0, v0 quad_perm:[2,3,0,1] row_mask:0xf bank_mask:0xf bound_ctrl:1
	s_nop 1
	v_add_f32_dpp v0, v0, v0 row_half_mirror row_mask:0xf bank_mask:0xf bound_ctrl:1
	s_nop 1
	v_mov_b32_dpp v1, v0 row_mirror row_mask:0xf bank_mask:0xf bound_ctrl:1
	s_and_saveexec_b64 s[2:3], s[40:41]
	s_cbranch_execz .LBB0_1303
	v_mov_b32_e32 v75, v129
	v_ashrrev_i32_e32 v97, 31, v96
	v_lshl_add_u64 v[2:3], s[48:49], 0, v[68:69]
	v_lshl_add_u64 v[4:5], v[96:97], 0, v[74:75]
	v_lshl_add_u64 v[2:3], v[4:5], 2, v[2:3]
	v_add_f32_e32 v0, v0, v1
	global_store_dword v[2:3], v0, off offset:256

.LBB0_1304:
	v_or_b32_e32 v4, v34, v76
	v_ashrrev_i32_e32 v5, 31, v4
	v_lshlrev_b64 v[0:1], 12, v[4:5]
	v_lshl_add_u64 v[0:1], s[42:43], 0, v[0:1]
	v_lshl_add_u64 v[16:17], v[98:99], 2, v[0:1]
	s_movk_i32 s2, 0x1000
	v_cmp_gt_i32_e32 vcc, s2, v4
	s_nop 1
	v_cndmask_b32_e32 v7, v6, v102, vcc
	v_and_b32_e32 v7, 1, v7
	v_cmp_eq_u32_e32 vcc, 1, v7
	s_nop 1
	v_cndmask_b32_e64 v7, v171, 0, vcc
	v_add_u32_e32 v7, v103, v7
	ds_read_b128 v[8:11], v86 offset:4352
	ds_read_b128 v[12:15], v7
	s_and_b64 vcc, exec, s[0:1]
	s_waitcnt vmcnt(15) lgkmcnt(0)
	v_pk_fma_f32 v[2:3], v[10:11], v[14:15], v[216:217]
	v_pk_fma_f32 v[0:1], v[8:9], v[12:13], v[214:215]
	global_store_dwordx4 v[16:17], v[0:3], off nt
	s_cbranch_vccnz .LBB0_1308
	ds_read_b128 v[8:11], v7 offset:2048
	v_lshlrev_b64 v[4:5], 10, v[4:5]
	v_lshl_add_u64 v[4:5], v[4:5], 1, s[44:45]
	v_lshl_add_u64 v[4:5], v[98:99], 1, v[4:5]
	s_waitcnt lgkmcnt(0)
	v_pk_mul_f32 v[8:9], v[0:1], v[8:9]
	v_pk_mul_f32 v[0:1], v[0:1], v[0:1]
	v_pk_mul_f32 v[10:11], v[2:3], v[10:11]
	v_pk_mul_f32 v[2:3], v[2:3], v[2:3]
	v_add_f32_e32 v0, v0, v1
	v_add_f32_e32 v0, v2, v0
	v_add_f32_e32 v0, v3, v0
	v_cvt_pk_bf16_f32 v8, v8, v9
	v_cvt_pk_bf16_f32 v9, v10, v11
	v_add_f32_dpp v0, v0, v0 quad_perm:[1,0,3,2] row_mask:0xf bank_mask:0xf bound_ctrl:1
	global_store_dwordx2 v[4:5], v[8:9], off
	s_nop 0
	v_add_f32_dpp v0, v0, v0 quad_perm:[2,3,0,1] row_mask:0xf bank_mask:0xf bound_ctrl:1
	s_nop 1
	v_add_f32_dpp v0, v0, v0 row_half_mirror row_mask:0xf bank_mask:0xf bound_ctrl:1
	s_nop 1
	v_mov_b32_dpp v1, v0 row_mirror row_mask:0xf bank_mask:0xf bound_ctrl:1
	s_and_saveexec_b64 s[2:3], s[40:41]
	s_cbranch_execz .LBB0_1307
	v_mov_b32_e32 v77, v129
	v_ashrrev_i32_e32 v97, 31, v96
	v_lshl_add_u64 v[2:3], s[48:49], 0, v[68:69]
	v_lshl_add_u64 v[4:5], v[96:97], 0, v[76:77]
	v_lshl_add_u64 v[2:3], v[4:5], 2, v[2:3]
	v_add_f32_e32 v0, v0, v1
	global_store_dword v[2:3], v0, off offset:256

.LBB0_1308:
	v_or_b32_e32 v4, v34, v78
	v_ashrrev_i32_e32 v5, 31, v4
	v_lshlrev_b64 v[0:1], 12, v[4:5]
	v_lshl_add_u64 v[0:1], s[42:43], 0, v[0:1]
	v_lshl_add_u64 v[16:17], v[98:99], 2, v[0:1]
	s_movk_i32 s2, 0x1000
	v_cmp_gt_i32_e32 vcc, s2, v4
	s_nop 1
	v_cndmask_b32_e32 v7, v6, v102, vcc
	v_and_b32_e32 v7, 1, v7
	v_cmp_eq_u32_e32 vcc, 1, v7
	s_nop 1
	v_cndmask_b32_e64 v7, v171, 0, vcc
	v_add_u32_e32 v7, v103, v7
	ds_read_b128 v[8:11], v86 offset:5440
	ds_read_b128 v[12:15], v7
	s_and_b64 vcc, exec, s[0:1]
	s_waitcnt vmcnt(15) lgkmcnt(0)
	v_pk_fma_f32 v[2:3], v[10:11], v[14:15], v[220:221]
	v_pk_fma_f32 v[0:1], v[8:9], v[12:13], v[218:219]
	global_store_dwordx4 v[16:17], v[0:3], off nt
	s_cbranch_vccnz .LBB0_1312
	ds_read_b128 v[8:11], v7 offset:2048
	v_lshlrev_b64 v[4:5], 10, v[4:5]
	v_lshl_add_u64 v[4:5], v[4:5], 1, s[44:45]
	v_lshl_add_u64 v[4:5], v[98:99], 1, v[4:5]
	s_waitcnt lgkmcnt(0)
	v_pk_mul_f32 v[8:9], v[0:1], v[8:9]
	v_pk_mul_f32 v[0:1], v[0:1], v[0:1]
	v_pk_mul_f32 v[10:11], v[2:3], v[10:11]
	v_pk_mul_f32 v[2:3], v[2:3], v[2:3]
	v_add_f32_e32 v0, v0, v1
	v_add_f32_e32 v0, v2, v0
	v_add_f32_e32 v0, v3, v0
	v_cvt_pk_bf16_f32 v8, v8, v9
	v_cvt_pk_bf16_f32 v9, v10, v11
	v_add_f32_dpp v0, v0, v0 quad_perm:[1,0,3,2] row_mask:0xf bank_mask:0xf bound_ctrl:1
	global_store_dwordx2 v[4:5], v[8:9], off
	s_nop 0
	v_add_f32_dpp v0, v0, v0 quad_perm:[2,3,0,1] row_mask:0xf bank_mask:0xf bound_ctrl:1
	s_nop 1
	v_add_f32_dpp v0, v0, v0 row_half_mirror row_mask:0xf bank_mask:0xf bound_ctrl:1
	s_nop 1
	v_mov_b32_dpp v1, v0 row_mirror row_mask:0xf bank_mask:0xf bound_ctrl:1
	s_and_saveexec_b64 s[2:3], s[40:41]
	s_cbranch_execz .LBB0_1311
	v_mov_b32_e32 v79, v129
	v_ashrrev_i32_e32 v97, 31, v96
	v_lshl_add_u64 v[2:3], s[48:49], 0, v[68:69]
	v_lshl_add_u64 v[4:5], v[96:97], 0, v[78:79]
	v_lshl_add_u64 v[2:3], v[4:5], 2, v[2:3]
	v_add_f32_e32 v0, v0, v1
	global_store_dword v[2:3], v0, off offset:256

.LBB0_1312:
	v_or_b32_e32 v4, v34, v80
	v_ashrrev_i32_e32 v5, 31, v4
	v_lshlrev_b64 v[0:1], 12, v[4:5]
	v_lshl_add_u64 v[0:1], s[42:43], 0, v[0:1]
	v_lshl_add_u64 v[16:17], v[98:99], 2, v[0:1]
	s_movk_i32 s2, 0x1000
	v_cmp_gt_i32_e32 vcc, s2, v4
	s_nop 1
	v_cndmask_b32_e32 v7, v6, v102, vcc
	v_and_b32_e32 v7, 1, v7
	v_cmp_eq_u32_e32 vcc, 1, v7
	s_nop 1
	v_cndmask_b32_e64 v7, v171, 0, vcc
	v_add_u32_e32 v7, v103, v7
	ds_read_b128 v[8:11], v86 offset:6528
	ds_read_b128 v[12:15], v7
	s_and_b64 vcc, exec, s[0:1]
	s_waitcnt vmcnt(15) lgkmcnt(0)
	v_pk_fma_f32 v[2:3], v[10:11], v[14:15], v[224:225]
	v_pk_fma_f32 v[0:1], v[8:9], v[12:13], v[222:223]
	global_store_dwordx4 v[16:17], v[0:3], off nt
	s_cbranch_vccnz .LBB0_1316
	ds_read_b128 v[8:11], v7 offset:2048
	v_lshlrev_b64 v[4:5], 10, v[4:5]
	v_lshl_add_u64 v[4:5], v[4:5], 1, s[44:45]
	v_lshl_add_u64 v[4:5], v[98:99], 1, v[4:5]
	s_waitcnt lgkmcnt(0)
	v_pk_mul_f32 v[8:9], v[0:1], v[8:9]
	v_pk_mul_f32 v[0:1], v[0:1], v[0:1]
	v_pk_mul_f32 v[10:11], v[2:3], v[10:11]
	v_pk_mul_f32 v[2:3], v[2:3], v[2:3]
	v_add_f32_e32 v0, v0, v1
	v_add_f32_e32 v0, v2, v0
	v_add_f32_e32 v0, v3, v0
	v_cvt_pk_bf16_f32 v8, v8, v9
	v_cvt_pk_bf16_f32 v9, v10, v11
	v_add_f32_dpp v0, v0, v0 quad_perm:[1,0,3,2] row_mask:0xf bank_mask:0xf bound_ctrl:1
	global_store_dwordx2 v[4:5], v[8:9], off
	s_nop 0
	v_add_f32_dpp v0, v0, v0 quad_perm:[2,3,0,1] row_mask:0xf bank_mask:0xf bound_ctrl:1
	s_nop 1
	v_add_f32_dpp v0, v0, v0 row_half_mirror row_mask:0xf bank_mask:0xf bound_ctrl:1
	s_nop 1
	v_mov_b32_dpp v1, v0 row_mirror row_mask:0xf bank_mask:0xf bound_ctrl:1
	s_and_saveexec_b64 s[2:3], s[40:41]
	s_cbranch_execz .LBB0_1315
	v_mov_b32_e32 v81, v129
	v_ashrrev_i32_e32 v97, 31, v96
	v_lshl_add_u64 v[2:3], s[48:49], 0, v[68:69]
	v_lshl_add_u64 v[4:5], v[96:97], 0, v[80:81]
	v_lshl_add_u64 v[2:3], v[4:5], 2, v[2:3]
	v_add_f32_e32 v0, v0, v1
	global_store_dword v[2:3], v0, off offset:256

.LBB0_1316:
	v_or_b32_e32 v4, v34, v82
	v_ashrrev_i32_e32 v5, 31, v4
	v_lshlrev_b64 v[0:1], 12, v[4:5]
	v_lshl_add_u64 v[0:1], s[42:43], 0, v[0:1]
	v_lshl_add_u64 v[16:17], v[98:99], 2, v[0:1]
	s_movk_i32 s2, 0x1000
	v_cmp_gt_i32_e32 vcc, s2, v4
	s_nop 1
	v_cndmask_b32_e32 v6, v6, v102, vcc
	v_and_b32_e32 v6, 1, v6
	v_cmp_eq_u32_e32 vcc, 1, v6
	s_nop 1
	v_cndmask_b32_e64 v6, v171, 0, vcc
	v_add_u32_e32 v6, v103, v6
	ds_read_b128 v[8:11], v86 offset:7616
	ds_read_b128 v[12:15], v6
	s_and_b64 vcc, exec, s[0:1]
	s_waitcnt vmcnt(15) lgkmcnt(0)
	v_pk_fma_f32 v[2:3], v[10:11], v[14:15], v[228:229]
	v_pk_fma_f32 v[0:1], v[8:9], v[12:13], v[226:227]
	global_store_dwordx4 v[16:17], v[0:3], off nt
	s_cbranch_vccnz .LBB0_1219
	ds_read_b128 v[6:9], v6 offset:2048
	v_lshlrev_b64 v[4:5], 10, v[4:5]
	v_lshl_add_u64 v[4:5], v[4:5], 1, s[44:45]
	v_lshl_add_u64 v[4:5], v[98:99], 1, v[4:5]
	s_waitcnt lgkmcnt(0)
	v_pk_mul_f32 v[6:7], v[0:1], v[6:7]
	v_pk_mul_f32 v[0:1], v[0:1], v[0:1]
	v_pk_mul_f32 v[8:9], v[2:3], v[8:9]
	v_pk_mul_f32 v[2:3], v[2:3], v[2:3]
	v_add_f32_e32 v0, v0, v1
	v_add_f32_e32 v0, v2, v0
	v_add_f32_e32 v0, v3, v0
	v_cvt_pk_bf16_f32 v6, v6, v7
	v_cvt_pk_bf16_f32 v7, v8, v9
	v_add_f32_dpp v0, v0, v0 quad_perm:[1,0,3,2] row_mask:0xf bank_mask:0xf bound_ctrl:1
	global_store_dwordx2 v[4:5], v[6:7], off
	s_nop 0
	v_add_f32_dpp v0, v0, v0 quad_perm:[2,3,0,1] row_mask:0xf bank_mask:0xf bound_ctrl:1
	s_nop 1
	v_add_f32_dpp v0, v0, v0 row_half_mirror row_mask:0xf bank_mask:0xf bound_ctrl:1
	s_nop 1
	v_mov_b32_dpp v1, v0 row_mirror row_mask:0xf bank_mask:0xf bound_ctrl:1
	s_and_saveexec_b64 s[0:1], s[40:41]
	s_cbranch_execz .LBB0_1218
	v_mov_b32_e32 v83, v129
	v_ashrrev_i32_e32 v97, 31, v96
	v_lshl_add_u64 v[2:3], s[48:49], 0, v[68:69]
	v_lshl_add_u64 v[4:5], v[96:97], 0, v[82:83]
	v_lshl_add_u64 v[2:3], v[4:5], 2, v[2:3]
	v_add_f32_e32 v0, v0, v1
	global_store_dword v[2:3], v0, off offset:256
	s_branch .LBB0_1218

.LBB0_1434:
	s_add_i32 s9, s7, 1
	s_bitcmp1_b32 s9, 0
	s_cselect_b32 s10, 0xe000, 0
	v_add_u32_e32 v246, s10, v109
	s_bitcmp1_b32 s7, 0
	s_cselect_b32 s10, 0xe000, 0
	v_add_u32_e32 v153, s10, v114
	v_add_u32_e32 v154, s10, v113
	s_waitcnt vmcnt(0) lgkmcnt(0)
	s_barrier
	v_add_u32_e32 v181, v153, v111
	ds_read_b128 v[116:119], v181 offset:0x0
	ds_read_b128 v[120:123], v181 offset:0x1000
	v_add_u32_e32 v181, v154, v111
	ds_read_b128 v[124:127], v181 offset:0x0
	ds_read_b128 v[130:133], v181 offset:0x1000
	ds_read_b128 v[134:137], v181 offset:0x2000
	v_mfma_f32_32x32x16_bf16 v[64:79], v[144:147], v[182:185], v[64:79]
	v_mfma_f32_32x32x16_bf16 v[32:47], v[144:147], v[186:189], v[32:47]
	s_mov_b64 s[10:11], 0x9f94080
	v_lshl_add_u64 v[244:245], v[98:99], 0, s[2:3]
	v_lshl_add_u64 v[244:245], v[244:245], 0, s[10:11]
	v_readfirstlane_b32 s10, v246
	s_mov_b32 m0, s10
	s_nop 0
	global_load_lds_dwordx4 v[244:245], off
	v_mfma_f32_32x32x16_bf16 v[0:15], v[144:147], v[190:193], v[0:15]
	v_mfma_f32_32x32x16_bf16 v[80:95], v[148:151], v[182:185], v[80:95]
	v_add_u32_e32 v243, 0x2000, v246
	s_mov_b64 s[10:11], 0xa014080
	v_lshl_add_u64 v[244:245], v[98:99], 0, s[2:3]
	v_lshl_add_u64 v[244:245], v[244:245], 0, s[10:11]
	v_readfirstlane_b32 s10, v243
	s_mov_b32 m0, s10
	s_nop 0
	global_load_lds_dwordx4 v[244:245], off
	v_mfma_f32_32x32x16_bf16 v[48:63], v[148:151], v[186:189], v[48:63]
	v_mfma_f32_32x32x16_bf16 v[16:31], v[148:151], v[190:193], v[16:31]
	v_add_u32_e32 v243, 0x4000, v246
	s_mov_b64 s[10:11], 0xa094080
	v_lshl_add_u64 v[244:245], v[98:99], 0, s[2:3]
	v_lshl_add_u64 v[244:245], v[244:245], 0, s[10:11]
	v_readfirstlane_b32 s10, v243
	s_mov_b32 m0, s10
	s_nop 0
	global_load_lds_dwordx4 v[244:245], off
	v_add_u32_e32 v181, v153, v110
	ds_read_b128 v[144:147], v181 offset:0x0
	ds_read_b128 v[148:151], v181 offset:0x1000
	v_add_u32_e32 v181, v154, v110
	ds_read_b128 v[182:185], v181 offset:0x0
	ds_read_b128 v[186:189], v181 offset:0x1000
	ds_read_b128 v[190:193], v181 offset:0x2000
	s_waitcnt lgkmcnt(5)
	v_mfma_f32_32x32x16_bf16 v[64:79], v[116:119], v[124:127], v[64:79]
	v_mfma_f32_32x32x16_bf16 v[32:47], v[116:119], v[130:133], v[32:47]
	v_add_u32_e32 v243, 0x6000, v246
	s_mov_b64 s[10:11], 0x3314080
	v_lshl_add_u64 v[244:245], v[96:97], 0, s[2:3]
	v_lshl_add_u64 v[244:245], v[244:245], 0, s[10:11]
	v_readfirstlane_b32 s10, v243
	s_mov_b32 m0, s10
	s_nop 0
	global_load_lds_dwordx4 v[244:245], off
	v_mfma_f32_32x32x16_bf16 v[0:15], v[116:119], v[134:137], v[0:15]
	v_mfma_f32_32x32x16_bf16 v[80:95], v[120:123], v[124:127], v[80:95]
	v_add_u32_e32 v243, 0x8000, v246
	s_mov_b64 s[10:11], 0x3394080
	v_lshl_add_u64 v[244:245], v[96:97], 0, s[2:3]
	v_lshl_add_u64 v[244:245], v[244:245], 0, s[10:11]
	v_readfirstlane_b32 s10, v243
	s_mov_b32 m0, s10
	s_nop 0
	global_load_lds_dwordx4 v[244:245], off
	v_mfma_f32_32x32x16_bf16 v[48:63], v[120:123], v[130:133], v[48:63]
	v_mfma_f32_32x32x16_bf16 v[16:31], v[120:123], v[134:137], v[16:31]
	v_add_u32_e32 v243, 0xa000, v246
	s_mov_b64 s[10:11], 0x3414080
	v_lshl_add_u64 v[244:245], v[96:97], 0, s[2:3]
	v_lshl_add_u64 v[244:245], v[244:245], 0, s[10:11]
	v_readfirstlane_b32 s10, v243
	s_mov_b32 m0, s10
	s_nop 0
	global_load_lds_dwordx4 v[244:245], off
	v_add_u32_e32 v181, v153, v108
	ds_read_b128 v[116:119], v181 offset:0x0
	ds_read_b128 v[120:123], v181 offset:0x1000
	v_add_u32_e32 v181, v154, v108
	ds_read_b128 v[124:127], v181 offset:0x0
	ds_read_b128 v[130:133], v181 offset:0x1000
	ds_read_b128 v[134:137], v181 offset:0x2000
	s_waitcnt lgkmcnt(5)
	v_mfma_f32_32x32x16_bf16 v[64:79], v[144:147], v[182:185], v[64:79]
	v_mfma_f32_32x32x16_bf16 v[32:47], v[144:147], v[186:189], v[32:47]
	v_add_u32_e32 v243, 0xc000, v246
	s_mov_b64 s[10:11], 0x3494080
	v_lshl_add_u64 v[244:245], v[96:97], 0, s[2:3]
	v_lshl_add_u64 v[244:245], v[244:245], 0, s[10:11]
	v_readfirstlane_b32 s10, v243
	s_mov_b32 m0, s10
	s_nop 0
	global_load_lds_dwordx4 v[244:245], off
	v_mfma_f32_32x32x16_bf16 v[0:15], v[144:147], v[190:193], v[0:15]
	v_mfma_f32_32x32x16_bf16 v[80:95], v[148:151], v[182:185], v[80:95]
	v_mfma_f32_32x32x16_bf16 v[48:63], v[148:151], v[186:189], v[48:63]
	v_mfma_f32_32x32x16_bf16 v[16:31], v[148:151], v[190:193], v[16:31]
	v_add_u32_e32 v181, v153, v107
	ds_read_b128 v[144:147], v181 offset:0x0
	ds_read_b128 v[148:151], v181 offset:0x1000
	v_add_u32_e32 v181, v154, v107
	ds_read_b128 v[182:185], v181 offset:0x0
	ds_read_b128 v[186:189], v181 offset:0x1000
	ds_read_b128 v[190:193], v181 offset:0x2000
	s_waitcnt lgkmcnt(5)
	v_mfma_f32_32x32x16_bf16 v[64:79], v[116:119], v[124:127], v[64:79]
	v_mfma_f32_32x32x16_bf16 v[32:47], v[116:119], v[130:133], v[32:47]
	v_mfma_f32_32x32x16_bf16 v[0:15], v[116:119], v[134:137], v[0:15]
	v_mfma_f32_32x32x16_bf16 v[80:95], v[120:123], v[124:127], v[80:95]
	v_mfma_f32_32x32x16_bf16 v[48:63], v[120:123], v[130:133], v[48:63]
	v_mfma_f32_32x32x16_bf16 v[16:31], v[120:123], v[134:137], v[16:31]
	s_waitcnt lgkmcnt(0)
	s_add_u32 s2, s2, 0x80
	s_addc_u32 s3, s3, 0
	s_mov_b32 s7, s9
	s_cmpk_lg_i32 s2, 0x1f80
	s_cbranch_scc1 .LBB0_1434
	s_bitcmp1_b32 s7, 0
	s_cselect_b32 s10, 0xe000, 0
	v_add_u32_e32 v153, s10, v114
	v_add_u32_e32 v154, s10, v113
	s_waitcnt vmcnt(0) lgkmcnt(0)
	s_barrier
	v_add_u32_e32 v181, v153, v111
	ds_read_b128 v[116:119], v181 offset:0x0
	ds_read_b128 v[120:123], v181 offset:0x1000
	v_add_u32_e32 v181, v154, v111
	ds_read_b128 v[124:127], v181 offset:0x0
	ds_read_b128 v[130:133], v181 offset:0x1000
	ds_read_b128 v[134:137], v181 offset:0x2000
	v_mfma_f32_32x32x16_bf16 v[64:79], v[144:147], v[182:185], v[64:79]
	v_mfma_f32_32x32x16_bf16 v[32:47], v[144:147], v[186:189], v[32:47]
	v_mfma_f32_32x32x16_bf16 v[0:15], v[144:147], v[190:193], v[0:15]
	v_mfma_f32_32x32x16_bf16 v[80:95], v[148:151], v[182:185], v[80:95]
	v_mfma_f32_32x32x16_bf16 v[48:63], v[148:151], v[186:189], v[48:63]
	v_mfma_f32_32x32x16_bf16 v[16:31], v[148:151], v[190:193], v[16:31]
	v_add_u32_e32 v181, v153, v110
	ds_read_b128 v[144:147], v181 offset:0x0
	ds_read_b128 v[148:151], v181 offset:0x1000
	v_add_u32_e32 v181, v154, v110
	ds_read_b128 v[182:185], v181 offset:0x0
	ds_read_b128 v[186:189], v181 offset:0x1000
	ds_read_b128 v[190:193], v181 offset:0x2000
	s_waitcnt lgkmcnt(5)
	v_mfma_f32_32x32x16_bf16 v[64:79], v[116:119], v[124:127], v[64:79]
	v_mfma_f32_32x32x16_bf16 v[32:47], v[116:119], v[130:133], v[32:47]
	v_mfma_f32_32x32x16_bf16 v[0:15], v[116:119], v[134:137], v[0:15]
	v_mfma_f32_32x32x16_bf16 v[80:95], v[120:123], v[124:127], v[80:95]
	v_mfma_f32_32x32x16_bf16 v[48:63], v[120:123], v[130:133], v[48:63]
	v_mfma_f32_32x32x16_bf16 v[16:31], v[120:123], v[134:137], v[16:31]
	v_add_u32_e32 v181, v153, v108
	ds_read_b128 v[116:119], v181 offset:0x0
	ds_read_b128 v[120:123], v181 offset:0x1000
	v_add_u32_e32 v181, v154, v108
	ds_read_b128 v[124:127], v181 offset:0x0
	ds_read_b128 v[130:133], v181 offset:0x1000
	ds_read_b128 v[134:137], v181 offset:0x2000
	s_waitcnt lgkmcnt(5)
	v_mfma_f32_32x32x16_bf16 v[64:79], v[144:147], v[182:185], v[64:79]
	v_mfma_f32_32x32x16_bf16 v[32:47], v[144:147], v[186:189], v[32:47]
	v_mfma_f32_32x32x16_bf16 v[0:15], v[144:147], v[190:193], v[0:15]
	v_mfma_f32_32x32x16_bf16 v[80:95], v[148:151], v[182:185], v[80:95]
	v_mfma_f32_32x32x16_bf16 v[48:63], v[148:151], v[186:189], v[48:63]
	v_mfma_f32_32x32x16_bf16 v[16:31], v[148:151], v[190:193], v[16:31]
	v_add_u32_e32 v181, v153, v107
	ds_read_b128 v[144:147], v181 offset:0x0
	ds_read_b128 v[148:151], v181 offset:0x1000
	v_add_u32_e32 v181, v154, v107
	ds_read_b128 v[182:185], v181 offset:0x0
	ds_read_b128 v[186:189], v181 offset:0x1000
	ds_read_b128 v[190:193], v181 offset:0x2000
	s_waitcnt lgkmcnt(5)
	v_mfma_f32_32x32x16_bf16 v[64:79], v[116:119], v[124:127], v[64:79]
	v_mfma_f32_32x32x16_bf16 v[32:47], v[116:119], v[130:133], v[32:47]
	v_mfma_f32_32x32x16_bf16 v[0:15], v[116:119], v[134:137], v[0:15]
	v_mfma_f32_32x32x16_bf16 v[80:95], v[120:123], v[124:127], v[80:95]
	v_mfma_f32_32x32x16_bf16 v[48:63], v[120:123], v[130:133], v[48:63]
	v_mfma_f32_32x32x16_bf16 v[16:31], v[120:123], v[134:137], v[16:31]
	s_waitcnt lgkmcnt(0)
	v_mfma_f32_32x32x16_bf16 v[64:79], v[144:147], v[182:185], v[64:79]
	v_mfma_f32_32x32x16_bf16 v[32:47], v[144:147], v[186:189], v[32:47]
	v_mfma_f32_32x32x16_bf16 v[0:15], v[144:147], v[190:193], v[0:15]
	v_mfma_f32_32x32x16_bf16 v[80:95], v[148:151], v[182:185], v[80:95]
	v_mfma_f32_32x32x16_bf16 v[48:63], v[148:151], v[186:189], v[48:63]
	v_mfma_f32_32x32x16_bf16 v[16:31], v[148:151], v[190:193], v[16:31]
	v_add_u32_e32 v96, s4, v106
	v_lshrrev_b32_e32 v128, 4, v101
	v_and_b32_e32 v112, 15, v100
	v_or_b32_e32 v100, v96, v128
	v_add_u32_e32 v105, s8, v105
	v_ashrrev_i32_e32 v101, 31, v100
	v_lshl_or_b32 v98, v112, 2, v105
	v_lshlrev_b64 v[106:107], 12, v[100:101]
	v_ashrrev_i32_e32 v99, 31, v98
	v_lshl_add_u64 v[106:107], s[40:41], 0, v[106:107]
	v_lshl_add_u64 v[110:111], v[98:99], 2, v[106:107]
	s_barrier
	v_add_co_u32_e32 v182, vcc, 0x20000, v110
	s_nop 1
	v_addc_co_u32_e32 v183, vcc, 0, v111, vcc
	global_load_dwordx4 v[184:187], v[182:183], off
	v_add_co_u32_e32 v182, vcc, 0x4000, v182
	s_nop 1
	v_addc_co_u32_e32 v183, vcc, 0, v183, vcc
	global_load_dwordx4 v[188:191], v[182:183], off
	v_add_co_u32_e32 v182, vcc, 0x4000, v182
	s_nop 1
	v_addc_co_u32_e32 v183, vcc, 0, v183, vcc
	global_load_dwordx4 v[192:195], v[182:183], off
	v_add_co_u32_e32 v182, vcc, 0x4000, v182
	s_nop 1
	v_addc_co_u32_e32 v183, vcc, 0, v183, vcc
	global_load_dwordx4 v[116:119], v[182:183], off
	v_add_co_u32_e32 v182, vcc, 0x4000, v182
	s_nop 1
	v_addc_co_u32_e32 v183, vcc, 0, v183, vcc
	global_load_dwordx4 v[120:123], v[182:183], off
	v_add_co_u32_e32 v182, vcc, 0x4000, v182
	s_nop 1
	v_addc_co_u32_e32 v183, vcc, 0, v183, vcc
	global_load_dwordx4 v[124:127], v[182:183], off
	v_add_co_u32_e32 v182, vcc, 0x4000, v182
	s_nop 1
	v_addc_co_u32_e32 v183, vcc, 0, v183, vcc
	global_load_dwordx4 v[130:133], v[182:183], off
	v_add_co_u32_e32 v182, vcc, 0x4000, v182
	s_nop 1
	v_addc_co_u32_e32 v183, vcc, 0, v183, vcc
	global_load_dwordx4 v[134:137], v[182:183], off
	s_movk_i32 s2, 0x2400
	s_cmp_lt_i32 s5, 22
	v_mul_lo_u32 v97, v103, s2
	s_cselect_b64 s[2:3], -1, 0
	s_cmp_gt_i32 s5, 21
	s_movk_i32 s5, 0x110
	v_and_b32_e32 v103, 16, v104
	v_mad_u32_u24 v104, v102, s5, v97
	v_add_u32_e32 v113, 0xfffff000, v96
	v_cndmask_b32_e64 v102, 0, 1, s[2:3]
	s_cselect_b64 s[2:3], -1, 0
	s_add_i32 s7, s4, 0xfffff000
	v_add_u32_e32 v104, v104, v103
	ds_write_b128 v104, v[64:67]
	ds_write_b128 v104, v[68:71] offset:32
	ds_write_b128 v104, v[72:75] offset:64
	ds_write_b128 v104, v[76:79] offset:96
	ds_write_b128 v104, v[80:83] offset:128
	ds_write_b128 v104, v[84:87] offset:160
	ds_write_b128 v104, v[88:91] offset:192
	ds_write_b128 v104, v[92:95] offset:224
	v_xor_b32_e32 v64, s7, v113
	s_movk_i32 s4, 0x400
	v_lshl_or_b32 v97, v112, 4, v97
	v_cmp_gt_u32_e32 vcc, s4, v64
	v_mad_u32_u24 v115, v128, s5, v97
	s_and_b64 s[4:5], s[2:3], vcc
	v_cndmask_b32_e64 v71, 0, 1, s[4:5]
	s_movk_i32 s4, 0x1000
	v_cmp_gt_i32_e32 vcc, s4, v100
	v_subrev_u32_e32 v114, s8, v98
	v_lshl_add_u32 v103, v114, 2, v167
	v_cndmask_b32_e32 v64, v71, v102, vcc
	v_and_b32_e32 v64, 1, v64
	v_cmp_eq_u32_e32 vcc, 1, v64
	v_ashrrev_i32_e32 v68, 6, v105
	s_mov_b32 s4, 0xc000
	v_cndmask_b32_e64 v64, v171, 0, vcc
	v_add_u32_e32 v70, v103, v64
	ds_read_b128 v[64:67], v115
	ds_read_b128 v[72:75], v70
	v_cmp_eq_u32_e64 s[36:37], 0, v112
	v_mad_i64_i32 v[68:69], s[4:5], v68, s4, 0
	s_and_b64 vcc, exec, s[0:1]
	s_waitcnt lgkmcnt(0)
	v_pk_fma_f32 v[66:67], v[66:67], v[74:75], v[200:201]
	v_pk_fma_f32 v[64:65], v[64:65], v[72:73], v[198:199]
	global_store_dwordx4 v[110:111], v[64:67], off nt
	s_cbranch_vccnz .LBB0_1439
	ds_read_b128 v[72:75], v70 offset:2048
	v_lshlrev_b64 v[76:77], 10, v[100:101]
	v_lshl_add_u64 v[76:77], v[76:77], 1, s[50:51]
	v_lshl_add_u64 v[76:77], v[98:99], 1, v[76:77]
	s_waitcnt lgkmcnt(0)
	v_pk_mul_f32 v[72:73], v[64:65], v[72:73]
	v_pk_mul_f32 v[64:65], v[64:65], v[64:65]
	v_pk_mul_f32 v[74:75], v[66:67], v[74:75]
	v_pk_mul_f32 v[66:67], v[66:67], v[66:67]
	v_add_f32_e32 v64, v64, v65
	v_add_f32_e32 v64, v66, v64
	v_add_f32_e32 v64, v67, v64
	v_cvt_pk_bf16_f32 v72, v72, v73
	v_cvt_pk_bf16_f32 v73, v74, v75
	v_add_f32_dpp v64, v64, v64 quad_perm:[1,0,3,2] row_mask:0xf bank_mask:0xf bound_ctrl:1
	global_store_dwordx2 v[76:77], v[72:73], off
	s_nop 0
	v_add_f32_dpp v64, v64, v64 quad_perm:[2,3,0,1] row_mask:0xf bank_mask:0xf bound_ctrl:1
	s_nop 1
	v_add_f32_dpp v64, v64, v64 row_half_mirror row_mask:0xf bank_mask:0xf bound_ctrl:1
	s_nop 1
	v_mov_b32_dpp v65, v64 row_mirror row_mask:0xf bank_mask:0xf bound_ctrl:1
	s_and_saveexec_b64 s[4:5], s[36:37]
	s_cbranch_execz .LBB0_1438
	v_lshl_add_u64 v[66:67], s[54:55], 0, v[68:69]
	v_lshl_add_u64 v[66:67], v[100:101], 2, v[66:67]
	v_add_f32_e32 v64, v64, v65
	global_store_dword v[66:67], v64, off

.LBB0_1439:
	v_or_b32_e32 v70, 4, v128
	v_or_b32_e32 v72, v96, v70
	v_ashrrev_i32_e32 v73, 31, v72
	v_lshlrev_b64 v[64:65], 12, v[72:73]
	v_lshl_add_u64 v[64:65], s[40:41], 0, v[64:65]
	v_lshl_add_u64 v[84:85], v[98:99], 2, v[64:65]
	s_movk_i32 s4, 0x1000
	v_mul_u32_u24_e32 v74, 0x110, v128
	v_cmp_gt_i32_e32 vcc, s4, v72
	v_add_u32_e32 v86, v74, v97
	s_nop 0
	v_cndmask_b32_e32 v74, v71, v102, vcc
	v_and_b32_e32 v74, 1, v74
	v_cmp_eq_u32_e32 vcc, 1, v74
	s_nop 1
	v_cndmask_b32_e64 v74, v171, 0, vcc
	v_add_u32_e32 v74, v103, v74
	ds_read_b128 v[76:79], v86 offset:1088
	ds_read_b128 v[80:83], v74
	s_and_b64 vcc, exec, s[0:1]
	s_waitcnt lgkmcnt(0)
	v_pk_fma_f32 v[66:67], v[78:79], v[82:83], v[204:205]
	v_pk_fma_f32 v[64:65], v[76:77], v[80:81], v[202:203]
	global_store_dwordx4 v[84:85], v[64:67], off nt
	s_cbranch_vccnz .LBB0_1443
	ds_read_b128 v[74:77], v74 offset:2048
	v_lshlrev_b64 v[72:73], 10, v[72:73]
	v_lshl_add_u64 v[72:73], v[72:73], 1, s[50:51]
	v_lshl_add_u64 v[72:73], v[98:99], 1, v[72:73]
	s_waitcnt lgkmcnt(0)
	v_pk_mul_f32 v[74:75], v[64:65], v[74:75]
	v_pk_mul_f32 v[64:65], v[64:65], v[64:65]
	v_pk_mul_f32 v[76:77], v[66:67], v[76:77]
	v_pk_mul_f32 v[66:67], v[66:67], v[66:67]
	v_add_f32_e32 v64, v64, v65
	v_add_f32_e32 v64, v66, v64
	v_add_f32_e32 v64, v67, v64
	v_cvt_pk_bf16_f32 v74, v74, v75
	v_cvt_pk_bf16_f32 v75, v76, v77
	v_add_f32_dpp v64, v64, v64 quad_perm:[1,0,3,2] row_mask:0xf bank_mask:0xf bound_ctrl:1
	global_store_dwordx2 v[72:73], v[74:75], off
	s_nop 0
	v_add_f32_dpp v64, v64, v64 quad_perm:[2,3,0,1] row_mask:0xf bank_mask:0xf bound_ctrl:1
	s_nop 1
	v_add_f32_dpp v64, v64, v64 row_half_mirror row_mask:0xf bank_mask:0xf bound_ctrl:1
	s_nop 1
	v_mov_b32_dpp v65, v64 row_mirror row_mask:0xf bank_mask:0xf bound_ctrl:1
	s_and_saveexec_b64 s[4:5], s[36:37]
	s_cbranch_execz .LBB0_1442
	v_ashrrev_i32_e32 v97, 31, v96
	v_lshl_add_u64 v[66:67], s[54:55], 0, v[68:69]
	v_lshl_add_u64 v[72:73], v[96:97], 0, v[128:129]
	v_lshl_add_u64 v[66:67], v[72:73], 2, v[66:67]
	v_add_f32_e32 v64, v64, v65
	global_store_dword v[66:67], v64, off offset:16

.LBB0_1443:
	v_or_b32_e32 v72, 8, v128
	v_or_b32_e32 v74, v96, v72
	v_ashrrev_i32_e32 v75, 31, v74
	v_lshlrev_b64 v[64:65], 12, v[74:75]
	v_lshl_add_u64 v[64:65], s[40:41], 0, v[64:65]
	v_lshl_add_u64 v[84:85], v[98:99], 2, v[64:65]
	s_movk_i32 s4, 0x1000
	v_cmp_gt_i32_e32 vcc, s4, v74
	s_nop 1
	v_cndmask_b32_e32 v73, v71, v102, vcc
	v_and_b32_e32 v73, 1, v73
	v_cmp_eq_u32_e32 vcc, 1, v73
	s_nop 1
	v_cndmask_b32_e64 v73, v171, 0, vcc
	v_add_u32_e32 v73, v103, v73
	ds_read_b128 v[76:79], v86 offset:2176
	ds_read_b128 v[80:83], v73
	s_and_b64 vcc, exec, s[0:1]
	s_waitcnt lgkmcnt(0)
	v_pk_fma_f32 v[66:67], v[78:79], v[82:83], v[208:209]
	v_pk_fma_f32 v[64:65], v[76:77], v[80:81], v[206:207]
	global_store_dwordx4 v[84:85], v[64:67], off nt
	s_cbranch_vccnz .LBB0_1447
	ds_read_b128 v[76:79], v73 offset:2048
	v_lshlrev_b64 v[74:75], 10, v[74:75]
	v_lshl_add_u64 v[74:75], v[74:75], 1, s[50:51]
	v_lshl_add_u64 v[74:75], v[98:99], 1, v[74:75]
	s_waitcnt lgkmcnt(0)
	v_pk_mul_f32 v[76:77], v[64:65], v[76:77]
	v_pk_mul_f32 v[64:65], v[64:65], v[64:65]
	v_pk_mul_f32 v[78:79], v[66:67], v[78:79]
	v_pk_mul_f32 v[66:67], v[66:67], v[66:67]
	v_add_f32_e32 v64, v64, v65
	v_add_f32_e32 v64, v66, v64
	v_add_f32_e32 v64, v67, v64
	v_cvt_pk_bf16_f32 v76, v76, v77
	v_cvt_pk_bf16_f32 v77, v78, v79
	v_add_f32_dpp v64, v64, v64 quad_perm:[1,0,3,2] row_mask:0xf bank_mask:0xf bound_ctrl:1
	global_store_dwordx2 v[74:75], v[76:77], off
	s_nop 0
	v_add_f32_dpp v64, v64, v64 quad_perm:[2,3,0,1] row_mask:0xf bank_mask:0xf bound_ctrl:1
	s_nop 1
	v_add_f32_dpp v64, v64, v64 row_half_mirror row_mask:0xf bank_mask:0xf bound_ctrl:1
	s_nop 1
	v_mov_b32_dpp v65, v64 row_mirror row_mask:0xf bank_mask:0xf bound_ctrl:1
	s_and_saveexec_b64 s[4:5], s[36:37]
	s_cbranch_execz .LBB0_1446
	v_ashrrev_i32_e32 v97, 31, v96
	v_lshl_add_u64 v[66:67], s[54:55], 0, v[68:69]
	v_lshl_add_u64 v[74:75], v[96:97], 0, v[128:129]
	v_lshl_add_u64 v[66:67], v[74:75], 2, v[66:67]
	v_add_f32_e32 v64, v64, v65
	global_store_dword v[66:67], v64, off offset:32

.LBB0_1447:
	v_or_b32_e32 v74, 12, v128
	v_or_b32_e32 v76, v96, v74
	v_ashrrev_i32_e32 v77, 31, v76
	v_lshlrev_b64 v[64:65], 12, v[76:77]
	v_lshl_add_u64 v[64:65], s[40:41], 0, v[64:65]
	v_lshl_add_u64 v[88:89], v[98:99], 2, v[64:65]
	s_movk_i32 s4, 0x1000
	v_cmp_gt_i32_e32 vcc, s4, v76
	s_nop 1
	v_cndmask_b32_e32 v73, v71, v102, vcc
	v_and_b32_e32 v73, 1, v73
	v_cmp_eq_u32_e32 vcc, 1, v73
	s_nop 1
	v_cndmask_b32_e64 v73, v171, 0, vcc
	v_add_u32_e32 v73, v103, v73
	ds_read_b128 v[78:81], v86 offset:3264
	ds_read_b128 v[82:85], v73
	s_and_b64 vcc, exec, s[0:1]
	s_waitcnt lgkmcnt(0)
	v_pk_fma_f32 v[66:67], v[80:81], v[84:85], v[212:213]
	v_pk_fma_f32 v[64:65], v[78:79], v[82:83], v[210:211]
	global_store_dwordx4 v[88:89], v[64:67], off nt
	s_cbranch_vccnz .LBB0_1451
	ds_read_b128 v[78:81], v73 offset:2048
	v_lshlrev_b64 v[76:77], 10, v[76:77]
	v_lshl_add_u64 v[76:77], v[76:77], 1, s[50:51]
	v_lshl_add_u64 v[76:77], v[98:99], 1, v[76:77]
	s_waitcnt lgkmcnt(0)
	v_pk_mul_f32 v[78:79], v[64:65], v[78:79]
	v_pk_mul_f32 v[64:65], v[64:65], v[64:65]
	v_pk_mul_f32 v[80:81], v[66:67], v[80:81]
	v_pk_mul_f32 v[66:67], v[66:67], v[66:67]
	v_add_f32_e32 v64, v64, v65
	v_add_f32_e32 v64, v66, v64
	v_add_f32_e32 v64, v67, v64
	v_cvt_pk_bf16_f32 v78, v78, v79
	v_cvt_pk_bf16_f32 v79, v80, v81
	v_add_f32_dpp v64, v64, v64 quad_perm:[1,0,3,2] row_mask:0xf bank_mask:0xf bound_ctrl:1
	global_store_dwordx2 v[76:77], v[78:79], off
	s_nop 0
	v_add_f32_dpp v64, v64, v64 quad_perm:[2,3,0,1] row_mask:0xf bank_mask:0xf bound_ctrl:1
	s_nop 1
	v_add_f32_dpp v64, v64, v64 row_half_mirror row_mask:0xf bank_mask:0xf bound_ctrl:1
	s_nop 1
	v_mov_b32_dpp v65, v64 row_mirror row_mask:0xf bank_mask:0xf bound_ctrl:1
	s_and_saveexec_b64 s[4:5], s[36:37]
	s_cbranch_execz .LBB0_1450
	v_ashrrev_i32_e32 v97, 31, v96
	v_lshl_add_u64 v[66:67], s[54:55], 0, v[68:69]
	v_lshl_add_u64 v[76:77], v[96:97], 0, v[128:129]
	v_lshl_add_u64 v[66:67], v[76:77], 2, v[66:67]
	v_add_f32_e32 v64, v64, v65
	global_store_dword v[66:67], v64, off offset:48

.LBB0_1451:
	v_or_b32_e32 v76, 16, v128
	v_or_b32_e32 v78, v96, v76
	v_ashrrev_i32_e32 v79, 31, v78
	v_lshlrev_b64 v[64:65], 12, v[78:79]
	v_lshl_add_u64 v[64:65], s[40:41], 0, v[64:65]
	v_lshl_add_u64 v[84:85], v[98:99], 2, v[64:65]
	s_movk_i32 s4, 0x1000
	v_cmp_gt_i32_e32 vcc, s4, v78
	s_nop 1
	v_cndmask_b32_e32 v73, v71, v102, vcc
	v_and_b32_e32 v73, 1, v73
	v_cmp_eq_u32_e32 vcc, 1, v73
	s_nop 1
	v_cndmask_b32_e64 v73, v171, 0, vcc
	v_add_u32_e32 v73, v103, v73
	ds_read_b128 v[80:83], v86 offset:4352
	ds_read_b128 v[88:91], v73
	s_and_b64 vcc, exec, s[0:1]
	s_waitcnt lgkmcnt(0)
	v_pk_fma_f32 v[66:67], v[82:83], v[90:91], v[216:217]
	v_pk_fma_f32 v[64:65], v[80:81], v[88:89], v[214:215]
	global_store_dwordx4 v[84:85], v[64:67], off nt
	s_cbranch_vccnz .LBB0_1455
	ds_read_b128 v[80:83], v73 offset:2048
	v_lshlrev_b64 v[78:79], 10, v[78:79]
	v_lshl_add_u64 v[78:79], v[78:79], 1, s[50:51]
	v_lshl_add_u64 v[78:79], v[98:99], 1, v[78:79]
	s_waitcnt lgkmcnt(0)
	v_pk_mul_f32 v[80:81], v[64:65], v[80:81]
	v_pk_mul_f32 v[64:65], v[64:65], v[64:65]
	v_pk_mul_f32 v[82:83], v[66:67], v[82:83]
	v_pk_mul_f32 v[66:67], v[66:67], v[66:67]
	v_add_f32_e32 v64, v64, v65
	v_add_f32_e32 v64, v66, v64
	v_add_f32_e32 v64, v67, v64
	v_cvt_pk_bf16_f32 v80, v80, v81
	v_cvt_pk_bf16_f32 v81, v82, v83
	v_add_f32_dpp v64, v64, v64 quad_perm:[1,0,3,2] row_mask:0xf bank_mask:0xf bound_ctrl:1
	global_store_dwordx2 v[78:79], v[80:81], off
	s_nop 0
	v_add_f32_dpp v64, v64, v64 quad_perm:[2,3,0,1] row_mask:0xf bank_mask:0xf bound_ctrl:1
	s_nop 1
	v_add_f32_dpp v64, v64, v64 row_half_mirror row_mask:0xf bank_mask:0xf bound_ctrl:1
	s_nop 1
	v_mov_b32_dpp v65, v64 row_mirror row_mask:0xf bank_mask:0xf bound_ctrl:1
	s_and_saveexec_b64 s[4:5], s[36:37]
	s_cbranch_execz .LBB0_1454
	v_ashrrev_i32_e32 v97, 31, v96
	v_lshl_add_u64 v[66:67], s[54:55], 0, v[68:69]
	v_lshl_add_u64 v[78:79], v[96:97], 0, v[128:129]
	v_lshl_add_u64 v[66:67], v[78:79], 2, v[66:67]
	v_add_f32_e32 v64, v64, v65
	global_store_dword v[66:67], v64, off offset:64

.LBB0_1455:
	v_or_b32_e32 v78, 20, v128
	v_or_b32_e32 v80, v96, v78
	v_ashrrev_i32_e32 v81, 31, v80
	v_lshlrev_b64 v[64:65], 12, v[80:81]
	v_lshl_add_u64 v[64:65], s[40:41], 0, v[64:65]
	v_lshl_add_u64 v[92:93], v[98:99], 2, v[64:65]
	s_movk_i32 s4, 0x1000
	v_cmp_gt_i32_e32 vcc, s4, v80
	s_nop 1
	v_cndmask_b32_e32 v73, v71, v102, vcc
	v_and_b32_e32 v73, 1, v73
	v_cmp_eq_u32_e32 vcc, 1, v73
	s_nop 1
	v_cndmask_b32_e64 v73, v171, 0, vcc
	v_add_u32_e32 v73, v103, v73
	ds_read_b128 v[82:85], v86 offset:5440
	ds_read_b128 v[88:91], v73
	s_and_b64 vcc, exec, s[0:1]
	s_waitcnt lgkmcnt(0)
	v_pk_fma_f32 v[66:67], v[84:85], v[90:91], v[220:221]
	v_pk_fma_f32 v[64:65], v[82:83], v[88:89], v[218:219]
	global_store_dwordx4 v[92:93], v[64:67], off nt
	s_cbranch_vccnz .LBB0_1459
	ds_read_b128 v[82:85], v73 offset:2048
	v_lshlrev_b64 v[80:81], 10, v[80:81]
	v_lshl_add_u64 v[80:81], v[80:81], 1, s[50:51]
	v_lshl_add_u64 v[80:81], v[98:99], 1, v[80:81]
	s_waitcnt lgkmcnt(0)
	v_pk_mul_f32 v[82:83], v[64:65], v[82:83]
	v_pk_mul_f32 v[64:65], v[64:65], v[64:65]
	v_pk_mul_f32 v[84:85], v[66:67], v[84:85]
	v_pk_mul_f32 v[66:67], v[66:67], v[66:67]
	v_add_f32_e32 v64, v64, v65
	v_add_f32_e32 v64, v66, v64
	v_add_f32_e32 v64, v67, v64
	v_cvt_pk_bf16_f32 v82, v82, v83
	v_cvt_pk_bf16_f32 v83, v84, v85
	v_add_f32_dpp v64, v64, v64 quad_perm:[1,0,3,2] row_mask:0xf bank_mask:0xf bound_ctrl:1
	global_store_dwordx2 v[80:81], v[82:83], off
	s_nop 0
	v_add_f32_dpp v64, v64, v64 quad_perm:[2,3,0,1] row_mask:0xf bank_mask:0xf bound_ctrl:1
	s_nop 1
	v_add_f32_dpp v64, v64, v64 row_half_mirror row_mask:0xf bank_mask:0xf bound_ctrl:1
	s_nop 1
	v_mov_b32_dpp v65, v64 row_mirror row_mask:0xf bank_mask:0xf bound_ctrl:1
	s_and_saveexec_b64 s[4:5], s[36:37]
	s_cbranch_execz .LBB0_1458
	v_ashrrev_i32_e32 v97, 31, v96
	v_lshl_add_u64 v[66:67], s[54:55], 0, v[68:69]
	v_lshl_add_u64 v[80:81], v[96:97], 0, v[128:129]
	v_lshl_add_u64 v[66:67], v[80:81], 2, v[66:67]
	v_add_f32_e32 v64, v64, v65
	global_store_dword v[66:67], v64, off offset:80

.LBB0_1459:
	v_or_b32_e32 v80, 24, v128
	v_or_b32_e32 v82, v96, v80
	v_ashrrev_i32_e32 v83, 31, v82
	v_lshlrev_b64 v[64:65], 12, v[82:83]
	v_lshl_add_u64 v[64:65], s[40:41], 0, v[64:65]
	v_lshl_add_u64 v[84:85], v[98:99], 2, v[64:65]
	s_movk_i32 s4, 0x1000
	v_cmp_gt_i32_e32 vcc, s4, v82
	s_nop 1
	v_cndmask_b32_e32 v73, v71, v102, vcc
	v_and_b32_e32 v73, 1, v73
	v_cmp_eq_u32_e32 vcc, 1, v73
	s_nop 1
	v_cndmask_b32_e64 v73, v171, 0, vcc
	v_add_u32_e32 v73, v103, v73
	ds_read_b128 v[88:91], v86 offset:6528
	ds_read_b128 v[92:95], v73
	s_and_b64 vcc, exec, s[0:1]
	s_waitcnt lgkmcnt(0)
	v_pk_fma_f32 v[66:67], v[90:91], v[94:95], v[224:225]
	v_pk_fma_f32 v[64:65], v[88:89], v[92:93], v[222:223]
	global_store_dwordx4 v[84:85], v[64:67], off nt
	s_cbranch_vccnz .LBB0_1463
	ds_read_b128 v[88:91], v73 offset:2048
	v_lshlrev_b64 v[82:83], 10, v[82:83]
	v_lshl_add_u64 v[82:83], v[82:83], 1, s[50:51]
	v_lshl_add_u64 v[82:83], v[98:99], 1, v[82:83]
	s_waitcnt lgkmcnt(0)
	v_pk_mul_f32 v[88:89], v[64:65], v[88:89]
	v_pk_mul_f32 v[64:65], v[64:65], v[64:65]
	v_pk_mul_f32 v[84:85], v[66:67], v[90:91]
	v_pk_mul_f32 v[66:67], v[66:67], v[66:67]
	v_add_f32_e32 v64, v64, v65
	v_add_f32_e32 v64, v66, v64
	v_add_f32_e32 v64, v67, v64
	v_cvt_pk_bf16_f32 v88, v88, v89
	v_cvt_pk_bf16_f32 v89, v84, v85
	v_add_f32_dpp v64, v64, v64 quad_perm:[1,0,3,2] row_mask:0xf bank_mask:0xf bound_ctrl:1
	global_store_dwordx2 v[82:83], v[88:89], off
	s_nop 0
	v_add_f32_dpp v64, v64, v64 quad_perm:[2,3,0,1] row_mask:0xf bank_mask:0xf bound_ctrl:1
	s_nop 1
	v_add_f32_dpp v64, v64, v64 row_half_mirror row_mask:0xf bank_mask:0xf bound_ctrl:1
	s_nop 1
	v_mov_b32_dpp v65, v64 row_mirror row_mask:0xf bank_mask:0xf bound_ctrl:1
	s_and_saveexec_b64 s[4:5], s[36:37]
	s_cbranch_execz .LBB0_1462
	v_ashrrev_i32_e32 v97, 31, v96
	v_lshl_add_u64 v[66:67], s[54:55], 0, v[68:69]
	v_lshl_add_u64 v[82:83], v[96:97], 0, v[128:129]
	v_lshl_add_u64 v[66:67], v[82:83], 2, v[66:67]
	v_add_f32_e32 v64, v64, v65
	global_store_dword v[66:67], v64, off offset:96

.LBB0_1463:
	v_or_b32_e32 v82, 28, v128
	v_or_b32_e32 v84, v96, v82
	v_ashrrev_i32_e32 v85, 31, v84
	v_lshlrev_b64 v[64:65], 12, v[84:85]
	v_lshl_add_u64 v[64:65], s[40:41], 0, v[64:65]
	v_lshl_add_u64 v[100:101], v[98:99], 2, v[64:65]
	s_movk_i32 s4, 0x1000
	v_cmp_gt_i32_e32 vcc, s4, v84
	s_nop 1
	v_cndmask_b32_e32 v71, v71, v102, vcc
	v_and_b32_e32 v71, 1, v71
	v_cmp_eq_u32_e32 vcc, 1, v71
	s_nop 1
	v_cndmask_b32_e64 v71, v171, 0, vcc
	v_add_u32_e32 v71, v103, v71
	ds_read_b128 v[88:91], v86 offset:7616
	ds_read_b128 v[92:95], v71
	s_and_b64 vcc, exec, s[0:1]
	s_waitcnt lgkmcnt(0)
	v_pk_fma_f32 v[66:67], v[90:91], v[94:95], v[228:229]
	v_pk_fma_f32 v[64:65], v[88:89], v[92:93], v[226:227]
	global_store_dwordx4 v[100:101], v[64:67], off nt
	s_cbranch_vccnz .LBB0_1467
	ds_read_b128 v[88:91], v71 offset:2048
	v_lshlrev_b64 v[84:85], 10, v[84:85]
	v_lshl_add_u64 v[84:85], v[84:85], 1, s[50:51]
	v_lshl_add_u64 v[84:85], v[98:99], 1, v[84:85]
	s_waitcnt lgkmcnt(0)
	v_pk_mul_f32 v[88:89], v[64:65], v[88:89]
	v_pk_mul_f32 v[64:65], v[64:65], v[64:65]
	v_pk_mul_f32 v[90:91], v[66:67], v[90:91]
	v_pk_mul_f32 v[66:67], v[66:67], v[66:67]
	v_add_f32_e32 v64, v64, v65
	v_add_f32_e32 v64, v66, v64
	v_add_f32_e32 v64, v67, v64
	v_cvt_pk_bf16_f32 v88, v88, v89
	v_cvt_pk_bf16_f32 v89, v90, v91
	v_add_f32_dpp v64, v64, v64 quad_perm:[1,0,3,2] row_mask:0xf bank_mask:0xf bound_ctrl:1
	global_store_dwordx2 v[84:85], v[88:89], off
	s_nop 0
	v_add_f32_dpp v64, v64, v64 quad_perm:[2,3,0,1] row_mask:0xf bank_mask:0xf bound_ctrl:1
	s_nop 1
	v_add_f32_dpp v64, v64, v64 row_half_mirror row_mask:0xf bank_mask:0xf bound_ctrl:1
	s_nop 1
	v_mov_b32_dpp v65, v64 row_mirror row_mask:0xf bank_mask:0xf bound_ctrl:1
	s_and_saveexec_b64 s[4:5], s[36:37]
	s_cbranch_execz .LBB0_1466
	v_ashrrev_i32_e32 v97, 31, v96
	v_lshl_add_u64 v[66:67], s[54:55], 0, v[68:69]
	v_lshl_add_u64 v[84:85], v[96:97], 0, v[128:129]
	v_lshl_add_u64 v[66:67], v[84:85], 2, v[66:67]
	v_add_f32_e32 v64, v64, v65
	global_store_dword v[66:67], v64, off offset:112

.LBB0_1467:
	s_nop 0
	v_add_u32_e32 v66, 32, v96
	v_or_b32_e32 v64, v66, v128
	v_ashrrev_i32_e32 v65, 31, v64
	v_lshlrev_b64 v[84:85], 12, v[64:65]
	v_lshl_add_u64 v[84:85], s[40:41], 0, v[84:85]
	v_lshl_add_u64 v[84:85], v[98:99], 2, v[84:85]
	v_add_co_u32_e32 v182, vcc, 0x20000, v84
	s_nop 1
	v_addc_co_u32_e32 v183, vcc, 0, v85, vcc
	global_load_dwordx4 v[198:201], v[182:183], off
	v_add_co_u32_e32 v182, vcc, 0x4000, v182
	s_nop 1
	v_addc_co_u32_e32 v183, vcc, 0, v183, vcc
	global_load_dwordx4 v[202:205], v[182:183], off
	v_add_co_u32_e32 v182, vcc, 0x4000, v182
	s_nop 1
	v_addc_co_u32_e32 v183, vcc, 0, v183, vcc
	global_load_dwordx4 v[206:209], v[182:183], off
	v_add_co_u32_e32 v182, vcc, 0x4000, v182
	s_nop 1
	v_addc_co_u32_e32 v183, vcc, 0, v183, vcc
	global_load_dwordx4 v[210:213], v[182:183], off
	v_add_co_u32_e32 v182, vcc, 0x4000, v182
	s_nop 1
	v_addc_co_u32_e32 v183, vcc, 0, v183, vcc
	global_load_dwordx4 v[214:217], v[182:183], off
	v_add_co_u32_e32 v182, vcc, 0x4000, v182
	s_nop 1
	v_addc_co_u32_e32 v183, vcc, 0, v183, vcc
	global_load_dwordx4 v[218:221], v[182:183], off
	v_add_co_u32_e32 v182, vcc, 0x4000, v182
	s_nop 1
	v_addc_co_u32_e32 v183, vcc, 0, v183, vcc
	global_load_dwordx4 v[222:225], v[182:183], off
	v_add_co_u32_e32 v182, vcc, 0x4000, v182
	s_nop 1
	v_addc_co_u32_e32 v183, vcc, 0, v183, vcc
	global_load_dwordx4 v[226:229], v[182:183], off
	ds_write_b128 v104, v[32:35]
	ds_write_b128 v104, v[36:39] offset:32
	ds_write_b128 v104, v[40:43] offset:64
	ds_write_b128 v104, v[44:47] offset:96
	ds_write_b128 v104, v[48:51] offset:128
	ds_write_b128 v104, v[52:55] offset:160
	ds_write_b128 v104, v[56:59] offset:192
	ds_write_b128 v104, v[60:63] offset:224
	v_add_u32_e32 v32, 0xfffff020, v96
	v_xor_b32_e32 v32, s7, v32
	s_movk_i32 s4, 0x400
	v_cmp_gt_u32_e32 vcc, s4, v32
	s_and_b64 s[4:5], s[2:3], vcc
	v_cndmask_b32_e64 v38, 0, 1, s[4:5]
	s_movk_i32 s4, 0x1000
	v_cmp_gt_i32_e32 vcc, s4, v64
	s_nop 1
	v_cndmask_b32_e32 v32, v38, v102, vcc
	v_and_b32_e32 v32, 1, v32
	v_cmp_eq_u32_e32 vcc, 1, v32
	s_nop 1
	v_cndmask_b32_e64 v32, v171, 0, vcc
	v_add_u32_e32 v36, v103, v32
	ds_read_b128 v[32:35], v86
	ds_read_b128 v[40:43], v36
	s_and_b64 vcc, exec, s[0:1]
	s_waitcnt vmcnt(23) lgkmcnt(0)
	v_pk_fma_f32 v[34:35], v[34:35], v[42:43], v[186:187]
	v_pk_fma_f32 v[32:33], v[32:33], v[40:41], v[184:185]
	global_store_dwordx4 v[84:85], v[32:35], off nt
	s_cbranch_vccnz .LBB0_1471
	ds_read_b128 v[40:43], v36 offset:2048
	v_lshlrev_b64 v[36:37], 10, v[64:65]
	v_lshl_add_u64 v[36:37], v[36:37], 1, s[50:51]
	v_lshl_add_u64 v[36:37], v[98:99], 1, v[36:37]
	s_waitcnt lgkmcnt(0)
	v_pk_mul_f32 v[40:41], v[32:33], v[40:41]
	v_pk_mul_f32 v[32:33], v[32:33], v[32:33]
	v_pk_mul_f32 v[42:43], v[34:35], v[42:43]
	v_pk_mul_f32 v[34:35], v[34:35], v[34:35]
	v_add_f32_e32 v32, v32, v33
	v_add_f32_e32 v32, v34, v32
	v_add_f32_e32 v32, v35, v32
	v_cvt_pk_bf16_f32 v40, v40, v41
	v_cvt_pk_bf16_f32 v41, v42, v43
	v_add_f32_dpp v32, v32, v32 quad_perm:[1,0,3,2] row_mask:0xf bank_mask:0xf bound_ctrl:1
	global_store_dwordx2 v[36:37], v[40:41], off
	s_nop 0
	v_add_f32_dpp v32, v32, v32 quad_perm:[2,3,0,1] row_mask:0xf bank_mask:0xf bound_ctrl:1
	s_nop 1
	v_add_f32_dpp v32, v32, v32 row_half_mirror row_mask:0xf bank_mask:0xf bound_ctrl:1
	s_nop 1
	v_mov_b32_dpp v33, v32 row_mirror row_mask:0xf bank_mask:0xf bound_ctrl:1
	s_and_saveexec_b64 s[4:5], s[36:37]
	s_cbranch_execz .LBB0_1470
	v_ashrrev_i32_e32 v97, 31, v96
	v_lshl_add_u64 v[34:35], s[54:55], 0, v[68:69]
	v_lshl_add_u64 v[36:37], v[96:97], 0, v[128:129]
	v_lshl_add_u64 v[34:35], v[36:37], 2, v[34:35]
	v_add_f32_e32 v32, v32, v33
	global_store_dword v[34:35], v32, off offset:128

.LBB0_1471:
	v_or_b32_e32 v36, v66, v70
	v_ashrrev_i32_e32 v37, 31, v36
	v_lshlrev_b64 v[32:33], 12, v[36:37]
	v_lshl_add_u64 v[32:33], s[40:41], 0, v[32:33]
	v_lshl_add_u64 v[48:49], v[98:99], 2, v[32:33]
	s_movk_i32 s4, 0x1000
	v_cmp_gt_i32_e32 vcc, s4, v36
	s_nop 1
	v_cndmask_b32_e32 v39, v38, v102, vcc
	v_and_b32_e32 v39, 1, v39
	v_cmp_eq_u32_e32 vcc, 1, v39
	s_nop 1
	v_cndmask_b32_e64 v39, v171, 0, vcc
	v_add_u32_e32 v39, v103, v39
	ds_read_b128 v[40:43], v86 offset:1088
	ds_read_b128 v[44:47], v39
	s_and_b64 vcc, exec, s[0:1]
	s_waitcnt vmcnt(23) lgkmcnt(0)
	v_pk_fma_f32 v[34:35], v[42:43], v[46:47], v[190:191]
	v_pk_fma_f32 v[32:33], v[40:41], v[44:45], v[188:189]
	global_store_dwordx4 v[48:49], v[32:35], off nt
	s_cbranch_vccnz .LBB0_1475
	ds_read_b128 v[40:43], v39 offset:2048
	v_lshlrev_b64 v[36:37], 10, v[36:37]
	v_lshl_add_u64 v[36:37], v[36:37], 1, s[50:51]
	v_lshl_add_u64 v[36:37], v[98:99], 1, v[36:37]
	s_waitcnt lgkmcnt(0)
	v_pk_mul_f32 v[40:41], v[32:33], v[40:41]
	v_pk_mul_f32 v[32:33], v[32:33], v[32:33]
	v_pk_mul_f32 v[42:43], v[34:35], v[42:43]
	v_pk_mul_f32 v[34:35], v[34:35], v[34:35]
	v_add_f32_e32 v32, v32, v33
	v_add_f32_e32 v32, v34, v32
	v_add_f32_e32 v32, v35, v32
	v_cvt_pk_bf16_f32 v40, v40, v41
	v_cvt_pk_bf16_f32 v41, v42, v43
	v_add_f32_dpp v32, v32, v32 quad_perm:[1,0,3,2] row_mask:0xf bank_mask:0xf bound_ctrl:1
	global_store_dwordx2 v[36:37], v[40:41], off
	s_nop 0
	v_add_f32_dpp v32, v32, v32 quad_perm:[2,3,0,1] row_mask:0xf bank_mask:0xf bound_ctrl:1
	s_nop 1
	v_add_f32_dpp v32, v32, v32 row_half_mirror row_mask:0xf bank_mask:0xf bound_ctrl:1
	s_nop 1
	v_mov_b32_dpp v33, v32 row_mirror row_mask:0xf bank_mask:0xf bound_ctrl:1
	s_and_saveexec_b64 s[4:5], s[36:37]
	s_cbranch_execz .LBB0_1474
	v_mov_b32_e32 v71, v129
	v_ashrrev_i32_e32 v97, 31, v96
	v_lshl_add_u64 v[34:35], s[54:55], 0, v[68:69]
	v_lshl_add_u64 v[36:37], v[96:97], 0, v[70:71]
	v_lshl_add_u64 v[34:35], v[36:37], 2, v[34:35]
	v_add_f32_e32 v32, v32, v33
	global_store_dword v[34:35], v32, off offset:128

.LBB0_1475:
	v_or_b32_e32 v36, v66, v72
	v_ashrrev_i32_e32 v37, 31, v36
	v_lshlrev_b64 v[32:33], 12, v[36:37]
	v_lshl_add_u64 v[32:33], s[40:41], 0, v[32:33]
	v_lshl_add_u64 v[48:49], v[98:99], 2, v[32:33]
	s_movk_i32 s4, 0x1000
	v_cmp_gt_i32_e32 vcc, s4, v36
	s_nop 1
	v_cndmask_b32_e32 v39, v38, v102, vcc
	v_and_b32_e32 v39, 1, v39
	v_cmp_eq_u32_e32 vcc, 1, v39
	s_nop 1
	v_cndmask_b32_e64 v39, v171, 0, vcc
	v_add_u32_e32 v39, v103, v39
	ds_read_b128 v[40:43], v86 offset:2176
	ds_read_b128 v[44:47], v39
	s_and_b64 vcc, exec, s[0:1]
	s_waitcnt vmcnt(23) lgkmcnt(0)
	v_pk_fma_f32 v[34:35], v[42:43], v[46:47], v[194:195]
	v_pk_fma_f32 v[32:33], v[40:41], v[44:45], v[192:193]
	global_store_dwordx4 v[48:49], v[32:35], off nt
	s_cbranch_vccnz .LBB0_1479
	ds_read_b128 v[40:43], v39 offset:2048
	v_lshlrev_b64 v[36:37], 10, v[36:37]
	v_lshl_add_u64 v[36:37], v[36:37], 1, s[50:51]
	v_lshl_add_u64 v[36:37], v[98:99], 1, v[36:37]
	s_waitcnt lgkmcnt(0)
	v_pk_mul_f32 v[40:41], v[32:33], v[40:41]
	v_pk_mul_f32 v[32:33], v[32:33], v[32:33]
	v_pk_mul_f32 v[42:43], v[34:35], v[42:43]
	v_pk_mul_f32 v[34:35], v[34:35], v[34:35]
	v_add_f32_e32 v32, v32, v33
	v_add_f32_e32 v32, v34, v32
	v_add_f32_e32 v32, v35, v32
	v_cvt_pk_bf16_f32 v40, v40, v41
	v_cvt_pk_bf16_f32 v41, v42, v43
	v_add_f32_dpp v32, v32, v32 quad_perm:[1,0,3,2] row_mask:0xf bank_mask:0xf bound_ctrl:1
	global_store_dwordx2 v[36:37], v[40:41], off
	s_nop 0
	v_add_f32_dpp v32, v32, v32 quad_perm:[2,3,0,1] row_mask:0xf bank_mask:0xf bound_ctrl:1
	s_nop 1
	v_add_f32_dpp v32, v32, v32 row_half_mirror row_mask:0xf bank_mask:0xf bound_ctrl:1
	s_nop 1
	v_mov_b32_dpp v33, v32 row_mirror row_mask:0xf bank_mask:0xf bound_ctrl:1
	s_and_saveexec_b64 s[4:5], s[36:37]
	s_cbranch_execz .LBB0_1478
	v_mov_b32_e32 v73, v129
	v_ashrrev_i32_e32 v97, 31, v96
	v_lshl_add_u64 v[34:35], s[54:55], 0, v[68:69]
	v_lshl_add_u64 v[36:37], v[96:97], 0, v[72:73]
	v_lshl_add_u64 v[34:35], v[36:37], 2, v[34:35]
	v_add_f32_e32 v32, v32, v33
	global_store_dword v[34:35], v32, off offset:128

.LBB0_1479:
	v_or_b32_e32 v36, v66, v74
	v_ashrrev_i32_e32 v37, 31, v36
	v_lshlrev_b64 v[32:33], 12, v[36:37]
	v_lshl_add_u64 v[32:33], s[40:41], 0, v[32:33]
	v_lshl_add_u64 v[48:49], v[98:99], 2, v[32:33]
	s_movk_i32 s4, 0x1000
	v_cmp_gt_i32_e32 vcc, s4, v36
	s_nop 1
	v_cndmask_b32_e32 v39, v38, v102, vcc
	v_and_b32_e32 v39, 1, v39
	v_cmp_eq_u32_e32 vcc, 1, v39
	s_nop 1
	v_cndmask_b32_e64 v39, v171, 0, vcc
	v_add_u32_e32 v39, v103, v39
	ds_read_b128 v[40:43], v86 offset:3264
	ds_read_b128 v[44:47], v39
	s_and_b64 vcc, exec, s[0:1]
	s_waitcnt vmcnt(23) lgkmcnt(0)
	v_pk_fma_f32 v[34:35], v[42:43], v[46:47], v[118:119]
	v_pk_fma_f32 v[32:33], v[40:41], v[44:45], v[116:117]
	global_store_dwordx4 v[48:49], v[32:35], off nt
	s_cbranch_vccnz .LBB0_1483
	ds_read_b128 v[40:43], v39 offset:2048
	v_lshlrev_b64 v[36:37], 10, v[36:37]
	v_lshl_add_u64 v[36:37], v[36:37], 1, s[50:51]
	v_lshl_add_u64 v[36:37], v[98:99], 1, v[36:37]
	s_waitcnt lgkmcnt(0)
	v_pk_mul_f32 v[40:41], v[32:33], v[40:41]
	v_pk_mul_f32 v[32:33], v[32:33], v[32:33]
	v_pk_mul_f32 v[42:43], v[34:35], v[42:43]
	v_pk_mul_f32 v[34:35], v[34:35], v[34:35]
	v_add_f32_e32 v32, v32, v33
	v_add_f32_e32 v32, v34, v32
	v_add_f32_e32 v32, v35, v32
	v_cvt_pk_bf16_f32 v40, v40, v41
	v_cvt_pk_bf16_f32 v41, v42, v43
	v_add_f32_dpp v32, v32, v32 quad_perm:[1,0,3,2] row_mask:0xf bank_mask:0xf bound_ctrl:1
	global_store_dwordx2 v[36:37], v[40:41], off
	s_nop 0
	v_add_f32_dpp v32, v32, v32 quad_perm:[2,3,0,1] row_mask:0xf bank_mask:0xf bound_ctrl:1
	s_nop 1
	v_add_f32_dpp v32, v32, v32 row_half_mirror row_mask:0xf bank_mask:0xf bound_ctrl:1
	s_nop 1
	v_mov_b32_dpp v33, v32 row_mirror row_mask:0xf bank_mask:0xf bound_ctrl:1
	s_and_saveexec_b64 s[4:5], s[36:37]
	s_cbranch_execz .LBB0_1482
	v_mov_b32_e32 v75, v129
	v_ashrrev_i32_e32 v97, 31, v96
	v_lshl_add_u64 v[34:35], s[54:55], 0, v[68:69]
	v_lshl_add_u64 v[36:37], v[96:97], 0, v[74:75]
	v_lshl_add_u64 v[34:35], v[36:37], 2, v[34:35]
	v_add_f32_e32 v32, v32, v33
	global_store_dword v[34:35], v32, off offset:128

.LBB0_1483:
	v_or_b32_e32 v36, v66, v76
	v_ashrrev_i32_e32 v37, 31, v36
	v_lshlrev_b64 v[32:33], 12, v[36:37]
	v_lshl_add_u64 v[32:33], s[40:41], 0, v[32:33]
	v_lshl_add_u64 v[48:49], v[98:99], 2, v[32:33]
	s_movk_i32 s4, 0x1000
	v_cmp_gt_i32_e32 vcc, s4, v36
	s_nop 1
	v_cndmask_b32_e32 v39, v38, v102, vcc
	v_and_b32_e32 v39, 1, v39
	v_cmp_eq_u32_e32 vcc, 1, v39
	s_nop 1
	v_cndmask_b32_e64 v39, v171, 0, vcc
	v_add_u32_e32 v39, v103, v39
	ds_read_b128 v[40:43], v86 offset:4352
	ds_read_b128 v[44:47], v39
	s_and_b64 vcc, exec, s[0:1]
	s_waitcnt vmcnt(23) lgkmcnt(0)
	v_pk_fma_f32 v[34:35], v[42:43], v[46:47], v[122:123]
	v_pk_fma_f32 v[32:33], v[40:41], v[44:45], v[120:121]
	global_store_dwordx4 v[48:49], v[32:35], off nt
	s_cbranch_vccnz .LBB0_1487
	ds_read_b128 v[40:43], v39 offset:2048
	v_lshlrev_b64 v[36:37], 10, v[36:37]
	v_lshl_add_u64 v[36:37], v[36:37], 1, s[50:51]
	v_lshl_add_u64 v[36:37], v[98:99], 1, v[36:37]
	s_waitcnt lgkmcnt(0)
	v_pk_mul_f32 v[40:41], v[32:33], v[40:41]
	v_pk_mul_f32 v[32:33], v[32:33], v[32:33]
	v_pk_mul_f32 v[42:43], v[34:35], v[42:43]
	v_pk_mul_f32 v[34:35], v[34:35], v[34:35]
	v_add_f32_e32 v32, v32, v33
	v_add_f32_e32 v32, v34, v32
	v_add_f32_e32 v32, v35, v32
	v_cvt_pk_bf16_f32 v40, v40, v41
	v_cvt_pk_bf16_f32 v41, v42, v43
	v_add_f32_dpp v32, v32, v32 quad_perm:[1,0,3,2] row_mask:0xf bank_mask:0xf bound_ctrl:1
	global_store_dwordx2 v[36:37], v[40:41], off
	s_nop 0
	v_add_f32_dpp v32, v32, v32 quad_perm:[2,3,0,1] row_mask:0xf bank_mask:0xf bound_ctrl:1
	s_nop 1
	v_add_f32_dpp v32, v32, v32 row_half_mirror row_mask:0xf bank_mask:0xf bound_ctrl:1
	s_nop 1
	v_mov_b32_dpp v33, v32 row_mirror row_mask:0xf bank_mask:0xf bound_ctrl:1
	s_and_saveexec_b64 s[4:5], s[36:37]
	s_cbranch_execz .LBB0_1486
	v_mov_b32_e32 v77, v129
	v_ashrrev_i32_e32 v97, 31, v96
	v_lshl_add_u64 v[34:35], s[54:55], 0, v[68:69]
	v_lshl_add_u64 v[36:37], v[96:97], 0, v[76:77]
	v_lshl_add_u64 v[34:35], v[36:37], 2, v[34:35]
	v_add_f32_e32 v32, v32, v33
	global_store_dword v[34:35], v32, off offset:128

.LBB0_1487:
	v_or_b32_e32 v36, v66, v78
	v_ashrrev_i32_e32 v37, 31, v36
	v_lshlrev_b64 v[32:33], 12, v[36:37]
	v_lshl_add_u64 v[32:33], s[40:41], 0, v[32:33]
	v_lshl_add_u64 v[48:49], v[98:99], 2, v[32:33]
	s_movk_i32 s4, 0x1000
	v_cmp_gt_i32_e32 vcc, s4, v36
	s_nop 1
	v_cndmask_b32_e32 v39, v38, v102, vcc
	v_and_b32_e32 v39, 1, v39
	v_cmp_eq_u32_e32 vcc, 1, v39
	s_nop 1
	v_cndmask_b32_e64 v39, v171, 0, vcc
	v_add_u32_e32 v39, v103, v39
	ds_read_b128 v[40:43], v86 offset:5440
	ds_read_b128 v[44:47], v39
	s_and_b64 vcc, exec, s[0:1]
	s_waitcnt vmcnt(23) lgkmcnt(0)
	v_pk_fma_f32 v[34:35], v[42:43], v[46:47], v[126:127]
	v_pk_fma_f32 v[32:33], v[40:41], v[44:45], v[124:125]
	global_store_dwordx4 v[48:49], v[32:35], off nt
	s_cbranch_vccnz .LBB0_1491
	ds_read_b128 v[40:43], v39 offset:2048
	v_lshlrev_b64 v[36:37], 10, v[36:37]
	v_lshl_add_u64 v[36:37], v[36:37], 1, s[50:51]
	v_lshl_add_u64 v[36:37], v[98:99], 1, v[36:37]
	s_waitcnt lgkmcnt(0)
	v_pk_mul_f32 v[40:41], v[32:33], v[40:41]
	v_pk_mul_f32 v[32:33], v[32:33], v[32:33]
	v_pk_mul_f32 v[42:43], v[34:35], v[42:43]
	v_pk_mul_f32 v[34:35], v[34:35], v[34:35]
	v_add_f32_e32 v32, v32, v33
	v_add_f32_e32 v32, v34, v32
	v_add_f32_e32 v32, v35, v32
	v_cvt_pk_bf16_f32 v40, v40, v41
	v_cvt_pk_bf16_f32 v41, v42, v43
	v_add_f32_dpp v32, v32, v32 quad_perm:[1,0,3,2] row_mask:0xf bank_mask:0xf bound_ctrl:1
	global_store_dwordx2 v[36:37], v[40:41], off
	s_nop 0
	v_add_f32_dpp v32, v32, v32 quad_perm:[2,3,0,1] row_mask:0xf bank_mask:0xf bound_ctrl:1
	s_nop 1
	v_add_f32_dpp v32, v32, v32 row_half_mirror row_mask:0xf bank_mask:0xf bound_ctrl:1
	s_nop 1
	v_mov_b32_dpp v33, v32 row_mirror row_mask:0xf bank_mask:0xf bound_ctrl:1
	s_and_saveexec_b64 s[4:5], s[36:37]
	s_cbranch_execz .LBB0_1490
	v_mov_b32_e32 v79, v129
	v_ashrrev_i32_e32 v97, 31, v96
	v_lshl_add_u64 v[34:35], s[54:55], 0, v[68:69]
	v_lshl_add_u64 v[36:37], v[96:97], 0, v[78:79]
	v_lshl_add_u64 v[34:35], v[36:37], 2, v[34:35]
	v_add_f32_e32 v32, v32, v33
	global_store_dword v[34:35], v32, off offset:128

.LBB0_1491:
	v_or_b32_e32 v36, v66, v80
	v_ashrrev_i32_e32 v37, 31, v36
	v_lshlrev_b64 v[32:33], 12, v[36:37]
	v_lshl_add_u64 v[32:33], s[40:41], 0, v[32:33]
	v_lshl_add_u64 v[48:49], v[98:99], 2, v[32:33]
	s_movk_i32 s4, 0x1000
	v_cmp_gt_i32_e32 vcc, s4, v36
	s_nop 1
	v_cndmask_b32_e32 v39, v38, v102, vcc
	v_and_b32_e32 v39, 1, v39
	v_cmp_eq_u32_e32 vcc, 1, v39
	s_nop 1
	v_cndmask_b32_e64 v39, v171, 0, vcc
	v_add_u32_e32 v39, v103, v39
	ds_read_b128 v[40:43], v86 offset:6528
	ds_read_b128 v[44:47], v39
	s_and_b64 vcc, exec, s[0:1]
	s_waitcnt vmcnt(23) lgkmcnt(0)
	v_pk_fma_f32 v[34:35], v[42:43], v[46:47], v[132:133]
	v_pk_fma_f32 v[32:33], v[40:41], v[44:45], v[130:131]
	global_store_dwordx4 v[48:49], v[32:35], off nt
	s_cbranch_vccnz .LBB0_1495
	ds_read_b128 v[40:43], v39 offset:2048
	v_lshlrev_b64 v[36:37], 10, v[36:37]
	v_lshl_add_u64 v[36:37], v[36:37], 1, s[50:51]
	v_lshl_add_u64 v[36:37], v[98:99], 1, v[36:37]
	s_waitcnt lgkmcnt(0)
	v_pk_mul_f32 v[40:41], v[32:33], v[40:41]
	v_pk_mul_f32 v[32:33], v[32:33], v[32:33]
	v_pk_mul_f32 v[42:43], v[34:35], v[42:43]
	v_pk_mul_f32 v[34:35], v[34:35], v[34:35]
	v_add_f32_e32 v32, v32, v33
	v_add_f32_e32 v32, v34, v32
	v_add_f32_e32 v32, v35, v32
	v_cvt_pk_bf16_f32 v40, v40, v41
	v_cvt_pk_bf16_f32 v41, v42, v43
	v_add_f32_dpp v32, v32, v32 quad_perm:[1,0,3,2] row_mask:0xf bank_mask:0xf bound_ctrl:1
	global_store_dwordx2 v[36:37], v[40:41], off
	s_nop 0
	v_add_f32_dpp v32, v32, v32 quad_perm:[2,3,0,1] row_mask:0xf bank_mask:0xf bound_ctrl:1
	s_nop 1
	v_add_f32_dpp v32, v32, v32 row_half_mirror row_mask:0xf bank_mask:0xf bound_ctrl:1
	s_nop 1
	v_mov_b32_dpp v33, v32 row_mirror row_mask:0xf bank_mask:0xf bound_ctrl:1
	s_and_saveexec_b64 s[4:5], s[36:37]
	s_cbranch_execz .LBB0_1494
	v_mov_b32_e32 v81, v129
	v_ashrrev_i32_e32 v97, 31, v96
	v_lshl_add_u64 v[34:35], s[54:55], 0, v[68:69]
	v_lshl_add_u64 v[36:37], v[96:97], 0, v[80:81]
	v_lshl_add_u64 v[34:35], v[36:37], 2, v[34:35]
	v_add_f32_e32 v32, v32, v33
	global_store_dword v[34:35], v32, off offset:128

.LBB0_1495:
	v_or_b32_e32 v36, v66, v82
	v_ashrrev_i32_e32 v37, 31, v36
	v_lshlrev_b64 v[32:33], 12, v[36:37]
	v_lshl_add_u64 v[32:33], s[40:41], 0, v[32:33]
	v_lshl_add_u64 v[48:49], v[98:99], 2, v[32:33]
	s_movk_i32 s4, 0x1000
	v_cmp_gt_i32_e32 vcc, s4, v36
	s_nop 1
	v_cndmask_b32_e32 v38, v38, v102, vcc
	v_and_b32_e32 v38, 1, v38
	v_cmp_eq_u32_e32 vcc, 1, v38
	s_nop 1
	v_cndmask_b32_e64 v38, v171, 0, vcc
	v_add_u32_e32 v38, v103, v38
	ds_read_b128 v[40:43], v86 offset:7616
	ds_read_b128 v[44:47], v38
	s_and_b64 vcc, exec, s[0:1]
	s_waitcnt vmcnt(23) lgkmcnt(0)
	v_pk_fma_f32 v[34:35], v[42:43], v[46:47], v[136:137]
	v_pk_fma_f32 v[32:33], v[40:41], v[44:45], v[134:135]
	global_store_dwordx4 v[48:49], v[32:35], off nt
	s_cbranch_vccnz .LBB0_1499
	ds_read_b128 v[38:41], v38 offset:2048
	v_lshlrev_b64 v[36:37], 10, v[36:37]
	v_lshl_add_u64 v[36:37], v[36:37], 1, s[50:51]
	v_lshl_add_u64 v[36:37], v[98:99], 1, v[36:37]
	s_waitcnt lgkmcnt(0)
	v_pk_mul_f32 v[38:39], v[32:33], v[38:39]
	v_pk_mul_f32 v[32:33], v[32:33], v[32:33]
	v_pk_mul_f32 v[40:41], v[34:35], v[40:41]
	v_pk_mul_f32 v[34:35], v[34:35], v[34:35]
	v_add_f32_e32 v32, v32, v33
	v_add_f32_e32 v32, v34, v32
	v_add_f32_e32 v32, v35, v32
	v_cvt_pk_bf16_f32 v38, v38, v39
	v_cvt_pk_bf16_f32 v39, v40, v41
	v_add_f32_dpp v32, v32, v32 quad_perm:[1,0,3,2] row_mask:0xf bank_mask:0xf bound_ctrl:1
	global_store_dwordx2 v[36:37], v[38:39], off
	s_nop 0
	v_add_f32_dpp v32, v32, v32 quad_perm:[2,3,0,1] row_mask:0xf bank_mask:0xf bound_ctrl:1
	s_nop 1
	v_add_f32_dpp v32, v32, v32 row_half_mirror row_mask:0xf bank_mask:0xf bound_ctrl:1
	s_nop 1
	v_mov_b32_dpp v33, v32 row_mirror row_mask:0xf bank_mask:0xf bound_ctrl:1
	s_and_saveexec_b64 s[4:5], s[36:37]
	s_cbranch_execz .LBB0_1498
	v_mov_b32_e32 v83, v129
	v_ashrrev_i32_e32 v97, 31, v96
	v_lshl_add_u64 v[34:35], s[54:55], 0, v[68:69]
	v_lshl_add_u64 v[36:37], v[96:97], 0, v[82:83]
	v_lshl_add_u64 v[34:35], v[36:37], 2, v[34:35]
	v_add_f32_e32 v32, v32, v33
	global_store_dword v[34:35], v32, off offset:128

.LBB0_1499:
	s_nop 0
	v_add_u32_e32 v34, 64, v96
	v_or_b32_e32 v32, v34, v128
	v_ashrrev_i32_e32 v33, 31, v32
	v_lshlrev_b64 v[36:37], 12, v[32:33]
	v_lshl_add_u64 v[36:37], s[40:41], 0, v[36:37]
	v_lshl_add_u64 v[40:41], v[98:99], 2, v[36:37]
	ds_write_b128 v104, v[0:3]
	ds_write_b128 v104, v[4:7] offset:32
	ds_write_b128 v104, v[8:11] offset:64
	ds_write_b128 v104, v[12:15] offset:96
	ds_write_b128 v104, v[16:19] offset:128
	ds_write_b128 v104, v[20:23] offset:160
	ds_write_b128 v104, v[24:27] offset:192
	ds_write_b128 v104, v[28:31] offset:224
	v_add_u32_e32 v0, 0xfffff040, v96
	v_xor_b32_e32 v0, s7, v0
	s_movk_i32 s4, 0x400
	v_cmp_gt_u32_e32 vcc, s4, v0
	s_and_b64 s[2:3], s[2:3], vcc
	v_cndmask_b32_e64 v6, 0, 1, s[2:3]
	s_movk_i32 s2, 0x1000
	v_cmp_gt_i32_e32 vcc, s2, v32
	s_nop 1
	v_cndmask_b32_e32 v0, v6, v102, vcc
	v_and_b32_e32 v0, 1, v0
	v_cmp_eq_u32_e32 vcc, 1, v0
	s_nop 1
	v_cndmask_b32_e64 v0, v171, 0, vcc
	v_add_u32_e32 v4, v103, v0
	ds_read_b128 v[0:3], v86
	ds_read_b128 v[8:11], v4
	s_and_b64 vcc, exec, s[0:1]
	s_waitcnt vmcnt(15) lgkmcnt(0)
	v_pk_fma_f32 v[2:3], v[2:3], v[10:11], v[200:201]
	v_pk_fma_f32 v[0:1], v[0:1], v[8:9], v[198:199]
	global_store_dwordx4 v[40:41], v[0:3], off nt
	s_cbranch_vccnz .LBB0_1503
	ds_read_b128 v[8:11], v4 offset:2048
	v_lshlrev_b64 v[4:5], 10, v[32:33]
	v_lshl_add_u64 v[4:5], v[4:5], 1, s[50:51]
	v_lshl_add_u64 v[4:5], v[98:99], 1, v[4:5]
	s_waitcnt lgkmcnt(0)
	v_pk_mul_f32 v[8:9], v[0:1], v[8:9]
	v_pk_mul_f32 v[0:1], v[0:1], v[0:1]
	v_pk_mul_f32 v[10:11], v[2:3], v[10:11]
	v_pk_mul_f32 v[2:3], v[2:3], v[2:3]
	v_add_f32_e32 v0, v0, v1
	v_add_f32_e32 v0, v2, v0
	v_add_f32_e32 v0, v3, v0
	v_cvt_pk_bf16_f32 v8, v8, v9
	v_cvt_pk_bf16_f32 v9, v10, v11
	v_add_f32_dpp v0, v0, v0 quad_perm:[1,0,3,2] row_mask:0xf bank_mask:0xf bound_ctrl:1
	global_store_dwordx2 v[4:5], v[8:9], off
	s_nop 0
	v_add_f32_dpp v0, v0, v0 quad_perm:[2,3,0,1] row_mask:0xf bank_mask:0xf bound_ctrl:1
	s_nop 1
	v_add_f32_dpp v0, v0, v0 row_half_mirror row_mask:0xf bank_mask:0xf bound_ctrl:1
	s_nop 1
	v_mov_b32_dpp v1, v0 row_mirror row_mask:0xf bank_mask:0xf bound_ctrl:1
	s_and_saveexec_b64 s[2:3], s[36:37]
	s_cbranch_execz .LBB0_1502
	v_ashrrev_i32_e32 v97, 31, v96
	v_lshl_add_u64 v[2:3], s[54:55], 0, v[68:69]
	v_lshl_add_u64 v[4:5], v[96:97], 0, v[128:129]
	v_lshl_add_u64 v[2:3], v[4:5], 2, v[2:3]
	v_add_f32_e32 v0, v0, v1
	global_store_dword v[2:3], v0, off offset:256

.LBB0_1503:
	v_or_b32_e32 v4, v34, v70
	v_ashrrev_i32_e32 v5, 31, v4
	v_lshlrev_b64 v[0:1], 12, v[4:5]
	v_lshl_add_u64 v[0:1], s[40:41], 0, v[0:1]
	v_lshl_add_u64 v[16:17], v[98:99], 2, v[0:1]
	s_movk_i32 s2, 0x1000
	v_cmp_gt_i32_e32 vcc, s2, v4
	s_nop 1
	v_cndmask_b32_e32 v7, v6, v102, vcc
	v_and_b32_e32 v7, 1, v7
	v_cmp_eq_u32_e32 vcc, 1, v7
	s_nop 1
	v_cndmask_b32_e64 v7, v171, 0, vcc
	v_add_u32_e32 v7, v103, v7
	ds_read_b128 v[8:11], v86 offset:1088
	ds_read_b128 v[12:15], v7
	s_and_b64 vcc, exec, s[0:1]
	s_waitcnt vmcnt(15) lgkmcnt(0)
	v_pk_fma_f32 v[2:3], v[10:11], v[14:15], v[204:205]
	v_pk_fma_f32 v[0:1], v[8:9], v[12:13], v[202:203]
	global_store_dwordx4 v[16:17], v[0:3], off nt
	s_cbranch_vccnz .LBB0_1507
	ds_read_b128 v[8:11], v7 offset:2048
	v_lshlrev_b64 v[4:5], 10, v[4:5]
	v_lshl_add_u64 v[4:5], v[4:5], 1, s[50:51]
	v_lshl_add_u64 v[4:5], v[98:99], 1, v[4:5]
	s_waitcnt lgkmcnt(0)
	v_pk_mul_f32 v[8:9], v[0:1], v[8:9]
	v_pk_mul_f32 v[0:1], v[0:1], v[0:1]
	v_pk_mul_f32 v[10:11], v[2:3], v[10:11]
	v_pk_mul_f32 v[2:3], v[2:3], v[2:3]
	v_add_f32_e32 v0, v0, v1
	v_add_f32_e32 v0, v2, v0
	v_add_f32_e32 v0, v3, v0
	v_cvt_pk_bf16_f32 v8, v8, v9
	v_cvt_pk_bf16_f32 v9, v10, v11
	v_add_f32_dpp v0, v0, v0 quad_perm:[1,0,3,2] row_mask:0xf bank_mask:0xf bound_ctrl:1
	global_store_dwordx2 v[4:5], v[8:9], off
	s_nop 0
	v_add_f32_dpp v0, v0, v0 quad_perm:[2,3,0,1] row_mask:0xf bank_mask:0xf bound_ctrl:1
	s_nop 1
	v_add_f32_dpp v0, v0, v0 row_half_mirror row_mask:0xf bank_mask:0xf bound_ctrl:1
	s_nop 1
	v_mov_b32_dpp v1, v0 row_mirror row_mask:0xf bank_mask:0xf bound_ctrl:1
	s_and_saveexec_b64 s[2:3], s[36:37]
	s_cbranch_execz .LBB0_1506
	v_mov_b32_e32 v71, v129
	v_ashrrev_i32_e32 v97, 31, v96
	v_lshl_add_u64 v[2:3], s[54:55], 0, v[68:69]
	v_lshl_add_u64 v[4:5], v[96:97], 0, v[70:71]
	v_lshl_add_u64 v[2:3], v[4:5], 2, v[2:3]
	v_add_f32_e32 v0, v0, v1
	global_store_dword v[2:3], v0, off offset:256

.LBB0_1507:
	v_or_b32_e32 v4, v34, v72
	v_ashrrev_i32_e32 v5, 31, v4
	v_lshlrev_b64 v[0:1], 12, v[4:5]
	v_lshl_add_u64 v[0:1], s[40:41], 0, v[0:1]
	v_lshl_add_u64 v[16:17], v[98:99], 2, v[0:1]
	s_movk_i32 s2, 0x1000
	v_cmp_gt_i32_e32 vcc, s2, v4
	s_nop 1
	v_cndmask_b32_e32 v7, v6, v102, vcc
	v_and_b32_e32 v7, 1, v7
	v_cmp_eq_u32_e32 vcc, 1, v7
	s_nop 1
	v_cndmask_b32_e64 v7, v171, 0, vcc
	v_add_u32_e32 v7, v103, v7
	ds_read_b128 v[8:11], v86 offset:2176
	ds_read_b128 v[12:15], v7
	s_and_b64 vcc, exec, s[0:1]
	s_waitcnt vmcnt(15) lgkmcnt(0)
	v_pk_fma_f32 v[2:3], v[10:11], v[14:15], v[208:209]
	v_pk_fma_f32 v[0:1], v[8:9], v[12:13], v[206:207]
	global_store_dwordx4 v[16:17], v[0:3], off nt
	s_cbranch_vccnz .LBB0_1511
	ds_read_b128 v[8:11], v7 offset:2048
	v_lshlrev_b64 v[4:5], 10, v[4:5]
	v_lshl_add_u64 v[4:5], v[4:5], 1, s[50:51]
	v_lshl_add_u64 v[4:5], v[98:99], 1, v[4:5]
	s_waitcnt lgkmcnt(0)
	v_pk_mul_f32 v[8:9], v[0:1], v[8:9]
	v_pk_mul_f32 v[0:1], v[0:1], v[0:1]
	v_pk_mul_f32 v[10:11], v[2:3], v[10:11]
	v_pk_mul_f32 v[2:3], v[2:3], v[2:3]
	v_add_f32_e32 v0, v0, v1
	v_add_f32_e32 v0, v2, v0
	v_add_f32_e32 v0, v3, v0
	v_cvt_pk_bf16_f32 v8, v8, v9
	v_cvt_pk_bf16_f32 v9, v10, v11
	v_add_f32_dpp v0, v0, v0 quad_perm:[1,0,3,2] row_mask:0xf bank_mask:0xf bound_ctrl:1
	global_store_dwordx2 v[4:5], v[8:9], off
	s_nop 0
	v_add_f32_dpp v0, v0, v0 quad_perm:[2,3,0,1] row_mask:0xf bank_mask:0xf bound_ctrl:1
	s_nop 1
	v_add_f32_dpp v0, v0, v0 row_half_mirror row_mask:0xf bank_mask:0xf bound_ctrl:1
	s_nop 1
	v_mov_b32_dpp v1, v0 row_mirror row_mask:0xf bank_mask:0xf bound_ctrl:1
	s_and_saveexec_b64 s[2:3], s[36:37]
	s_cbranch_execz .LBB0_1510
	v_mov_b32_e32 v73, v129
	v_ashrrev_i32_e32 v97, 31, v96
	v_lshl_add_u64 v[2:3], s[54:55], 0, v[68:69]
	v_lshl_add_u64 v[4:5], v[96:97], 0, v[72:73]
	v_lshl_add_u64 v[2:3], v[4:5], 2, v[2:3]
	v_add_f32_e32 v0, v0, v1
	global_store_dword v[2:3], v0, off offset:256

.LBB0_1511:
	v_or_b32_e32 v4, v34, v74
	v_ashrrev_i32_e32 v5, 31, v4
	v_lshlrev_b64 v[0:1], 12, v[4:5]
	v_lshl_add_u64 v[0:1], s[40:41], 0, v[0:1]
	v_lshl_add_u64 v[16:17], v[98:99], 2, v[0:1]
	s_movk_i32 s2, 0x1000
	v_cmp_gt_i32_e32 vcc, s2, v4
	s_nop 1
	v_cndmask_b32_e32 v7, v6, v102, vcc
	v_and_b32_e32 v7, 1, v7
	v_cmp_eq_u32_e32 vcc, 1, v7
	s_nop 1
	v_cndmask_b32_e64 v7, v171, 0, vcc
	v_add_u32_e32 v7, v103, v7
	ds_read_b128 v[8:11], v86 offset:3264
	ds_read_b128 v[12:15], v7
	s_and_b64 vcc, exec, s[0:1]
	s_waitcnt vmcnt(15) lgkmcnt(0)
	v_pk_fma_f32 v[2:3], v[10:11], v[14:15], v[212:213]
	v_pk_fma_f32 v[0:1], v[8:9], v[12:13], v[210:211]
	global_store_dwordx4 v[16:17], v[0:3], off nt
	s_cbranch_vccnz .LBB0_1515
	ds_read_b128 v[8:11], v7 offset:2048
	v_lshlrev_b64 v[4:5], 10, v[4:5]
	v_lshl_add_u64 v[4:5], v[4:5], 1, s[50:51]
	v_lshl_add_u64 v[4:5], v[98:99], 1, v[4:5]
	s_waitcnt lgkmcnt(0)
	v_pk_mul_f32 v[8:9], v[0:1], v[8:9]
	v_pk_mul_f32 v[0:1], v[0:1], v[0:1]
	v_pk_mul_f32 v[10:11], v[2:3], v[10:11]
	v_pk_mul_f32 v[2:3], v[2:3], v[2:3]
	v_add_f32_e32 v0, v0, v1
	v_add_f32_e32 v0, v2, v0
	v_add_f32_e32 v0, v3, v0
	v_cvt_pk_bf16_f32 v8, v8, v9
	v_cvt_pk_bf16_f32 v9, v10, v11
	v_add_f32_dpp v0, v0, v0 quad_perm:[1,0,3,2] row_mask:0xf bank_mask:0xf bound_ctrl:1
	global_store_dwordx2 v[4:5], v[8:9], off
	s_nop 0
	v_add_f32_dpp v0, v0, v0 quad_perm:[2,3,0,1] row_mask:0xf bank_mask:0xf bound_ctrl:1
	s_nop 1
	v_add_f32_dpp v0, v0, v0 row_half_mirror row_mask:0xf bank_mask:0xf bound_ctrl:1
	s_nop 1
	v_mov_b32_dpp v1, v0 row_mirror row_mask:0xf bank_mask:0xf bound_ctrl:1
	s_and_saveexec_b64 s[2:3], s[36:37]
	s_cbranch_execz .LBB0_1514
	v_mov_b32_e32 v75, v129
	v_ashrrev_i32_e32 v97, 31, v96
	v_lshl_add_u64 v[2:3], s[54:55], 0, v[68:69]
	v_lshl_add_u64 v[4:5], v[96:97], 0, v[74:75]
	v_lshl_add_u64 v[2:3], v[4:5], 2, v[2:3]
	v_add_f32_e32 v0, v0, v1
	global_store_dword v[2:3], v0, off offset:256

.LBB0_1515:
	v_or_b32_e32 v4, v34, v76
	v_ashrrev_i32_e32 v5, 31, v4
	v_lshlrev_b64 v[0:1], 12, v[4:5]
	v_lshl_add_u64 v[0:1], s[40:41], 0, v[0:1]
	v_lshl_add_u64 v[16:17], v[98:99], 2, v[0:1]
	s_movk_i32 s2, 0x1000
	v_cmp_gt_i32_e32 vcc, s2, v4
	s_nop 1
	v_cndmask_b32_e32 v7, v6, v102, vcc
	v_and_b32_e32 v7, 1, v7
	v_cmp_eq_u32_e32 vcc, 1, v7
	s_nop 1
	v_cndmask_b32_e64 v7, v171, 0, vcc
	v_add_u32_e32 v7, v103, v7
	ds_read_b128 v[8:11], v86 offset:4352
	ds_read_b128 v[12:15], v7
	s_and_b64 vcc, exec, s[0:1]
	s_waitcnt vmcnt(15) lgkmcnt(0)
	v_pk_fma_f32 v[2:3], v[10:11], v[14:15], v[216:217]
	v_pk_fma_f32 v[0:1], v[8:9], v[12:13], v[214:215]
	global_store_dwordx4 v[16:17], v[0:3], off nt
	s_cbranch_vccnz .LBB0_1519
	ds_read_b128 v[8:11], v7 offset:2048
	v_lshlrev_b64 v[4:5], 10, v[4:5]
	v_lshl_add_u64 v[4:5], v[4:5], 1, s[50:51]
	v_lshl_add_u64 v[4:5], v[98:99], 1, v[4:5]
	s_waitcnt lgkmcnt(0)
	v_pk_mul_f32 v[8:9], v[0:1], v[8:9]
	v_pk_mul_f32 v[0:1], v[0:1], v[0:1]
	v_pk_mul_f32 v[10:11], v[2:3], v[10:11]
	v_pk_mul_f32 v[2:3], v[2:3], v[2:3]
	v_add_f32_e32 v0, v0, v1
	v_add_f32_e32 v0, v2, v0
	v_add_f32_e32 v0, v3, v0
	v_cvt_pk_bf16_f32 v8, v8, v9
	v_cvt_pk_bf16_f32 v9, v10, v11
	v_add_f32_dpp v0, v0, v0 quad_perm:[1,0,3,2] row_mask:0xf bank_mask:0xf bound_ctrl:1
	global_store_dwordx2 v[4:5], v[8:9], off
	s_nop 0
	v_add_f32_dpp v0, v0, v0 quad_perm:[2,3,0,1] row_mask:0xf bank_mask:0xf bound_ctrl:1
	s_nop 1
	v_add_f32_dpp v0, v0, v0 row_half_mirror row_mask:0xf bank_mask:0xf bound_ctrl:1
	s_nop 1
	v_mov_b32_dpp v1, v0 row_mirror row_mask:0xf bank_mask:0xf bound_ctrl:1
	s_and_saveexec_b64 s[2:3], s[36:37]
	s_cbranch_execz .LBB0_1518
	v_mov_b32_e32 v77, v129
	v_ashrrev_i32_e32 v97, 31, v96
	v_lshl_add_u64 v[2:3], s[54:55], 0, v[68:69]
	v_lshl_add_u64 v[4:5], v[96:97], 0, v[76:77]
	v_lshl_add_u64 v[2:3], v[4:5], 2, v[2:3]
	v_add_f32_e32 v0, v0, v1
	global_store_dword v[2:3], v0, off offset:256

.LBB0_1519:
	v_or_b32_e32 v4, v34, v78
	v_ashrrev_i32_e32 v5, 31, v4
	v_lshlrev_b64 v[0:1], 12, v[4:5]
	v_lshl_add_u64 v[0:1], s[40:41], 0, v[0:1]
	v_lshl_add_u64 v[16:17], v[98:99], 2, v[0:1]
	s_movk_i32 s2, 0x1000
	v_cmp_gt_i32_e32 vcc, s2, v4
	s_nop 1
	v_cndmask_b32_e32 v7, v6, v102, vcc
	v_and_b32_e32 v7, 1, v7
	v_cmp_eq_u32_e32 vcc, 1, v7
	s_nop 1
	v_cndmask_b32_e64 v7, v171, 0, vcc
	v_add_u32_e32 v7, v103, v7
	ds_read_b128 v[8:11], v86 offset:5440
	ds_read_b128 v[12:15], v7
	s_and_b64 vcc, exec, s[0:1]
	s_waitcnt vmcnt(15) lgkmcnt(0)
	v_pk_fma_f32 v[2:3], v[10:11], v[14:15], v[220:221]
	v_pk_fma_f32 v[0:1], v[8:9], v[12:13], v[218:219]
	global_store_dwordx4 v[16:17], v[0:3], off nt
	s_cbranch_vccnz .LBB0_1523
	ds_read_b128 v[8:11], v7 offset:2048
	v_lshlrev_b64 v[4:5], 10, v[4:5]
	v_lshl_add_u64 v[4:5], v[4:5], 1, s[50:51]
	v_lshl_add_u64 v[4:5], v[98:99], 1, v[4:5]
	s_waitcnt lgkmcnt(0)
	v_pk_mul_f32 v[8:9], v[0:1], v[8:9]
	v_pk_mul_f32 v[0:1], v[0:1], v[0:1]
	v_pk_mul_f32 v[10:11], v[2:3], v[10:11]
	v_pk_mul_f32 v[2:3], v[2:3], v[2:3]
	v_add_f32_e32 v0, v0, v1
	v_add_f32_e32 v0, v2, v0
	v_add_f32_e32 v0, v3, v0
	v_cvt_pk_bf16_f32 v8, v8, v9
	v_cvt_pk_bf16_f32 v9, v10, v11
	v_add_f32_dpp v0, v0, v0 quad_perm:[1,0,3,2] row_mask:0xf bank_mask:0xf bound_ctrl:1
	global_store_dwordx2 v[4:5], v[8:9], off
	s_nop 0
	v_add_f32_dpp v0, v0, v0 quad_perm:[2,3,0,1] row_mask:0xf bank_mask:0xf bound_ctrl:1
	s_nop 1
	v_add_f32_dpp v0, v0, v0 row_half_mirror row_mask:0xf bank_mask:0xf bound_ctrl:1
	s_nop 1
	v_mov_b32_dpp v1, v0 row_mirror row_mask:0xf bank_mask:0xf bound_ctrl:1
	s_and_saveexec_b64 s[2:3], s[36:37]
	s_cbranch_execz .LBB0_1522
	v_mov_b32_e32 v79, v129
	v_ashrrev_i32_e32 v97, 31, v96
	v_lshl_add_u64 v[2:3], s[54:55], 0, v[68:69]
	v_lshl_add_u64 v[4:5], v[96:97], 0, v[78:79]
	v_lshl_add_u64 v[2:3], v[4:5], 2, v[2:3]
	v_add_f32_e32 v0, v0, v1
	global_store_dword v[2:3], v0, off offset:256

.LBB0_1523:
	v_or_b32_e32 v4, v34, v80
	v_ashrrev_i32_e32 v5, 31, v4
	v_lshlrev_b64 v[0:1], 12, v[4:5]
	v_lshl_add_u64 v[0:1], s[40:41], 0, v[0:1]
	v_lshl_add_u64 v[16:17], v[98:99], 2, v[0:1]
	s_movk_i32 s2, 0x1000
	v_cmp_gt_i32_e32 vcc, s2, v4
	s_nop 1
	v_cndmask_b32_e32 v7, v6, v102, vcc
	v_and_b32_e32 v7, 1, v7
	v_cmp_eq_u32_e32 vcc, 1, v7
	s_nop 1
	v_cndmask_b32_e64 v7, v171, 0, vcc
	v_add_u32_e32 v7, v103, v7
	ds_read_b128 v[8:11], v86 offset:6528
	ds_read_b128 v[12:15], v7
	s_and_b64 vcc, exec, s[0:1]
	s_waitcnt vmcnt(15) lgkmcnt(0)
	v_pk_fma_f32 v[2:3], v[10:11], v[14:15], v[224:225]
	v_pk_fma_f32 v[0:1], v[8:9], v[12:13], v[222:223]
	global_store_dwordx4 v[16:17], v[0:3], off nt
	s_cbranch_vccnz .LBB0_1527
	ds_read_b128 v[8:11], v7 offset:2048
	v_lshlrev_b64 v[4:5], 10, v[4:5]
	v_lshl_add_u64 v[4:5], v[4:5], 1, s[50:51]
	v_lshl_add_u64 v[4:5], v[98:99], 1, v[4:5]
	s_waitcnt lgkmcnt(0)
	v_pk_mul_f32 v[8:9], v[0:1], v[8:9]
	v_pk_mul_f32 v[0:1], v[0:1], v[0:1]
	v_pk_mul_f32 v[10:11], v[2:3], v[10:11]
	v_pk_mul_f32 v[2:3], v[2:3], v[2:3]
	v_add_f32_e32 v0, v0, v1
	v_add_f32_e32 v0, v2, v0
	v_add_f32_e32 v0, v3, v0
	v_cvt_pk_bf16_f32 v8, v8, v9
	v_cvt_pk_bf16_f32 v9, v10, v11
	v_add_f32_dpp v0, v0, v0 quad_perm:[1,0,3,2] row_mask:0xf bank_mask:0xf bound_ctrl:1
	global_store_dwordx2 v[4:5], v[8:9], off
	s_nop 0
	v_add_f32_dpp v0, v0, v0 quad_perm:[2,3,0,1] row_mask:0xf bank_mask:0xf bound_ctrl:1
	s_nop 1
	v_add_f32_dpp v0, v0, v0 row_half_mirror row_mask:0xf bank_mask:0xf bound_ctrl:1
	s_nop 1
	v_mov_b32_dpp v1, v0 row_mirror row_mask:0xf bank_mask:0xf bound_ctrl:1
	s_and_saveexec_b64 s[2:3], s[36:37]
	s_cbranch_execz .LBB0_1526
	v_mov_b32_e32 v81, v129
	v_ashrrev_i32_e32 v97, 31, v96
	v_lshl_add_u64 v[2:3], s[54:55], 0, v[68:69]
	v_lshl_add_u64 v[4:5], v[96:97], 0, v[80:81]
	v_lshl_add_u64 v[2:3], v[4:5], 2, v[2:3]
	v_add_f32_e32 v0, v0, v1
	global_store_dword v[2:3], v0, off offset:256

.LBB0_1527:
	v_or_b32_e32 v4, v34, v82
	v_ashrrev_i32_e32 v5, 31, v4
	v_lshlrev_b64 v[0:1], 12, v[4:5]
	v_lshl_add_u64 v[0:1], s[40:41], 0, v[0:1]
	v_lshl_add_u64 v[16:17], v[98:99], 2, v[0:1]
	s_movk_i32 s2, 0x1000
	v_cmp_gt_i32_e32 vcc, s2, v4
	s_nop 1
	v_cndmask_b32_e32 v6, v6, v102, vcc
	v_and_b32_e32 v6, 1, v6
	v_cmp_eq_u32_e32 vcc, 1, v6
	s_nop 1
	v_cndmask_b32_e64 v6, v171, 0, vcc
	v_add_u32_e32 v6, v103, v6
	ds_read_b128 v[8:11], v86 offset:7616
	ds_read_b128 v[12:15], v6
	s_and_b64 vcc, exec, s[0:1]
	s_waitcnt vmcnt(15) lgkmcnt(0)
	v_pk_fma_f32 v[2:3], v[10:11], v[14:15], v[228:229]
	v_pk_fma_f32 v[0:1], v[8:9], v[12:13], v[226:227]
	global_store_dwordx4 v[16:17], v[0:3], off nt
	s_cbranch_vccnz .LBB0_1430
	ds_read_b128 v[6:9], v6 offset:2048
	v_lshlrev_b64 v[4:5], 10, v[4:5]
	v_lshl_add_u64 v[4:5], v[4:5], 1, s[50:51]
	v_lshl_add_u64 v[4:5], v[98:99], 1, v[4:5]
	s_waitcnt lgkmcnt(0)
	v_pk_mul_f32 v[6:7], v[0:1], v[6:7]
	v_pk_mul_f32 v[0:1], v[0:1], v[0:1]
	v_pk_mul_f32 v[8:9], v[2:3], v[8:9]
	v_pk_mul_f32 v[2:3], v[2:3], v[2:3]
	v_add_f32_e32 v0, v0, v1
	v_add_f32_e32 v0, v2, v0
	v_add_f32_e32 v0, v3, v0
	v_cvt_pk_bf16_f32 v6, v6, v7
	v_cvt_pk_bf16_f32 v7, v8, v9
	v_add_f32_dpp v0, v0, v0 quad_perm:[1,0,3,2] row_mask:0xf bank_mask:0xf bound_ctrl:1
	global_store_dwordx2 v[4:5], v[6:7], off
	s_nop 0
	v_add_f32_dpp v0, v0, v0 quad_perm:[2,3,0,1] row_mask:0xf bank_mask:0xf bound_ctrl:1
	s_nop 1
	v_add_f32_dpp v0, v0, v0 row_half_mirror row_mask:0xf bank_mask:0xf bound_ctrl:1
	s_nop 1
	v_mov_b32_dpp v1, v0 row_mirror row_mask:0xf bank_mask:0xf bound_ctrl:1
	s_and_saveexec_b64 s[0:1], s[36:37]
	s_cbranch_execz .LBB0_1429
	v_mov_b32_e32 v83, v129
	v_ashrrev_i32_e32 v97, 31, v96
	v_lshl_add_u64 v[2:3], s[54:55], 0, v[68:69]
	v_lshl_add_u64 v[4:5], v[96:97], 0, v[82:83]
	v_lshl_add_u64 v[2:3], v[4:5], 2, v[2:3]
	v_add_f32_e32 v0, v0, v1
	global_store_dword v[2:3], v0, off offset:256
	s_branch .LBB0_1429
